# attention: separate loop copies per wave half, staging loads at QK^T slots 4/12/20/28 (waves 0-3) and 0/8/16/24 (waves 4-7)
# baseline (speedup 1.0000x reference)
; #define QF(d, e) __uint_as_float(((unsigned)(unsigned short)qr[d][e]) << 16)
; template <typename TQ> ...
;     ...
;   const int tid = tid_, wid = __builtin_amdgcn_readfirstlane(tid >> 6), lane = tid & 63, r32 = lane & 31, hi = lane >> 5;
;   bf16* V_lds = (bf16*)lds; bf16* K_lds = (bf16*)(lds + 2 * SHM_V);
;   float* ws = (float*)(lds + 2 * SHM_V + 2 * SHM_K) + wid * 64; float* li_l = ws;
;   float l_reg = 0; f32x16 o[4] = {}; bf16x8 qr[8];
;   const TQ* Qw = Qb + (long)(wid * QBLK + r32) * LDQ + hi * 8;
; #pragma unroll
;   for (int d0 = 0; d0 < 8; ++d0) qr[d0] = SQ::tobf(SQ::ld8(Qw + d0 * 16));
;   const int sr = tid >> 4, sc = (tid & 15) * 8, vst0 = v_st(sr, sc), vst1 = v_st(32 + sr, sc);
;   const int vb0 = (int)(uintptr_t)V_lds + v_rd_base(lane);
;   struct { typename St::T vs0, vs1, ks0, ks1; } sr_[SDEPTH];
;     ...
;   constexpr int SE = 0, SO = SDEPTH - 1;
;   SLOAD(SE, 0);
;   {
;     float ss = 0.f;
;     ...
; #pragma unroll
;     for (int d0 = 0; d0 < 8; ++d0)
; #pragma unroll
;       for (int e = 0; e < 8; ++e) { const float x = QF(d0, e); ss += x * x; }
;     ss += __shfl_xor(ss, 32);
;     const float rn = (SCALE * 1.4426950408889634f) / sqrtf(ss * (1.0f / 128.0f) + 1e-6f);
;     const int t = trow0 + wid * QBLK + r32; const int prow = t >> 6, pcol = t & 63;
; #pragma unroll
;     for (int hf = 0; hf < 2; ++hf)
; #pragma unroll
;       for (int dd = 0; dd < 2; ++dd) {
;         const int dl = 4 * hf + dd, du = dl + 2;
;         const int f0 = 16 * dd + 8 * hi;
;         const float* cp = rc + (hf ? pcol : prow) * 32 + f0; const float* sp = rsn + (hf ? pcol : prow) * 32 + f0;
;         const float* gl = gq + 16 * dl + 8 * hi; const float* gu = gq + 16 * du + 8 * hi;
; __global__ void __launch_bounds__(NTHR, 2) fwd_megakernel(KArgs a) {
;     ...
;         for (int i = 0; i < upb; ++i) {
;             const int unit = vcu * upb + i; if (unit >= 512) break;
;             const int grp = unit >> 7, rem = unit & 127, gq = rem >> 5, qb = rem & 31, b = grp >> 1, kvh = grp & 1, h = kvh * 4 + gq;
;             const size_t qoff = ((size_t)(b * SEQ + qb * 256)) * DM + h * 128, koff = (size_t)b * SKV * 256 + kvh * 128;
;             att::attn_dense_body<att::bf16>(Q + qoff, Kb + koff, Vb + koff, O + qoff, SKV, (char*)lds_raw, mC, a.g_q, (const float*)(ws + WS_ROPE), (const float*)(ws + WS_ROPE) + 4096, qb * 256);
.LBB0_819:
	s_add_i32 s12, s74, s73
	s_cmpk_gt_i32 s12, 0x1ff
	s_mov_b64 s[0:1], -1
	s_cbranch_scc1 .LBB0_818
	s_lshl_b32 s0, s94, 1
	s_ashr_i32 s96, s12, 8
	s_lshl_b32 s1, s12, 8
	s_and_b32 s95, s0, 0x100
	s_lshl_b32 s0, s96, 13
	s_and_b32 s33, s1, 0x1f00
	s_bfe_u32 s15, s12, 0x10007
	s_or_b32 s0, s0, s33
	s_lshl_b32 s12, s12, 2
	s_ashr_i32 s1, s0, 31
	s_lshl_b32 s13, s15, 9
	s_and_b32 s12, s12, 0x180
	s_lshl_b64 s[0:1], s[0:1], 10
	s_or_b32 s12, s13, s12
	s_or_b32 s0, s0, s12
	s_mul_i32 s12, s96, 0x210000
	s_lshl_b32 s15, s15, 7
	s_or_b32 s12, s12, s15
	s_lshl_b64 s[48:49], s[0:1], 1
	s_mul_hi_i32 s13, s96, 0x210000
	s_add_u32 s0, s20, s48
	s_addc_u32 s1, s21, s49
	s_lshl_b64 s[12:13], s[12:13], 1
	s_add_u32 s54, s69, s12
	s_addc_u32 s55, s70, s13
	v_mov_b32_e32 v114, v0
	s_add_u32 s64, s67, s12
	s_addc_u32 s65, s68, s13
	v_readfirstlane_b32 s53, v114
	s_lshr_b32 s15, s53, 6
	s_lshl_b32 s80, s15, 11
	s_add_u32 s79, s80, 0x10000
	s_lshl_b32 s52, s15, 5
	s_lshl_b32 s12, s15, 3
	v_and_b32_e32 v1, 63, v0
	v_and_b32_e32 v16, 15, v1
	v_lshrrev_b32_e32 v17, 4, v1
	v_add_u32_e32 v12, s12, v17
	v_and_b32_e32 v6, 15, v12
	v_xor_b32_e32 v6, v6, v16
	v_lshlrev_b32_e32 v6, 4, v6
	v_lshl_or_b32 v246, v12, 9, v6
	v_and_b32_e32 v6, 7, v12
	v_lshrrev_b32_e32 v7, 1, v16
	v_xor_b32_e32 v6, v6, v7
	v_and_b32_e32 v7, 1, v16
	v_lshl_or_b32 v6, v6, 1, v7
	v_lshlrev_b32_e32 v6, 4, v6
	v_lshl_or_b32 v248, v12, 9, v6
	v_add_u32_e32 v12, s12, v17
	v_add_u32_e32 v12, 4, v12
	v_and_b32_e32 v6, 15, v12
	v_xor_b32_e32 v6, v6, v16
	v_lshlrev_b32_e32 v6, 4, v6
	v_lshl_or_b32 v247, v12, 9, v6
	v_and_b32_e32 v6, 7, v12
	v_lshrrev_b32_e32 v7, 1, v16
	v_xor_b32_e32 v6, v6, v7
	v_and_b32_e32 v7, 1, v16
	v_lshl_or_b32 v6, v6, 1, v7
	v_lshlrev_b32_e32 v6, 4, v6
	v_lshl_or_b32 v249, v12, 9, v6
	s_mov_b32 s98, s54
	s_mov_b32 s99, s55
	s_mov_b32 s100, s64
	s_mov_b32 s101, s65
	s_add_u32 m0, s79, 0
	s_nop 0
	global_load_lds_dwordx4 v246, s[98:99]
	s_add_u32 m0, s79, 1024
	s_nop 0
	global_load_lds_dwordx4 v247, s[98:99]
	s_add_u32 m0, s80, 0
	s_nop 0
	global_load_lds_dwordx4 v248, s[100:101]
	s_add_u32 m0, s80, 1024
	s_nop 0
	global_load_lds_dwordx4 v249, s[100:101]
	s_add_u32 s98, s98, 0x8000
	s_addc_u32 s99, s99, 0
	s_add_u32 s100, s100, 0x8000
	s_addc_u32 s101, s101, 0
	s_add_u32 m0, s79, 16384
	s_nop 0
	global_load_lds_dwordx4 v246, s[98:99]
	s_add_u32 m0, s79, 17408
	s_nop 0
	global_load_lds_dwordx4 v247, s[98:99]
	s_add_u32 m0, s80, 16384
	s_nop 0
	global_load_lds_dwordx4 v248, s[100:101]
	s_add_u32 m0, s80, 17408
	s_nop 0
	global_load_lds_dwordx4 v249, s[100:101]
	s_add_u32 s98, s98, 0x8000
	s_addc_u32 s99, s99, 0
	s_add_u32 s100, s100, 0x8000
	s_addc_u32 s101, s101, 0
	s_add_u32 m0, s79, 32768
	s_nop 0
	global_load_lds_dwordx4 v246, s[98:99]
	s_add_u32 m0, s79, 33792
	s_nop 0
	global_load_lds_dwordx4 v247, s[98:99]
	s_add_u32 m0, s80, 32768
	s_nop 0
	global_load_lds_dwordx4 v248, s[100:101]
	s_add_u32 m0, s80, 33792
	s_nop 0
	global_load_lds_dwordx4 v249, s[100:101]
	s_add_u32 s98, s98, 0x8000
	s_addc_u32 s99, s99, 0
	s_add_u32 m0, s79, 49152
	s_nop 0
	global_load_lds_dwordx4 v246, s[98:99]
	s_add_u32 m0, s79, 50176
	s_nop 0
	global_load_lds_dwordx4 v247, s[98:99]
	v_add_u32_e32 v6, s52, v16
	v_lshlrev_b32_e32 v6, 11, v6
	v_lshl_or_b32 v13, v17, 4, v6
	v_add_u32_e32 v14, 0x8000, v13
	global_load_dwordx4 v[146:149], v13, s[0:1] offset:0
	global_load_dwordx4 v[150:153], v13, s[0:1] offset:64
	global_load_dwordx4 v[154:157], v13, s[0:1] offset:128
	global_load_dwordx4 v[158:161], v13, s[0:1] offset:192
	global_load_dwordx4 v[162:165], v14, s[0:1] offset:0
	global_load_dwordx4 v[166:169], v14, s[0:1] offset:64
	global_load_dwordx4 v[170:173], v14, s[0:1] offset:128
	global_load_dwordx4 v[174:177], v14, s[0:1] offset:192
	v_lshlrev_b32_e32 v15, 5, v17
	global_load_dwordx4 v[18:21], v15, s[26:27] offset:0
	global_load_dwordx4 v[22:25], v15, s[26:27] offset:16
	global_load_dwordx4 v[26:29], v15, s[26:27] offset:128
	global_load_dwordx4 v[30:33], v15, s[26:27] offset:144
	global_load_dwordx4 v[34:37], v15, s[26:27] offset:256
	global_load_dwordx4 v[38:41], v15, s[26:27] offset:272
	global_load_dwordx4 v[42:45], v15, s[26:27] offset:384
	global_load_dwordx4 v[46:49], v15, s[26:27] offset:400
	s_add_u32 s13, s33, s52
	s_lshr_b32 s13, s13, 6
	s_lshl_b32 s13, s13, 7
	v_add_u32_e32 v200, s13, v15
	global_load_dwordx4 v[82:85], v200, s[4:5] offset:0
	global_load_dwordx4 v[90:93], v200, s[6:7] offset:0
	global_load_dwordx4 v[86:89], v200, s[4:5] offset:16
	global_load_dwordx4 v[94:97], v200, s[6:7] offset:16
	v_add_u32_e32 v6, s52, v16
	v_and_b32_e32 v6, 63, v6
	v_lshl_or_b32 v200, v6, 7, v15
	global_load_dwordx4 v[98:101], v200, s[4:5] offset:0
	global_load_dwordx4 v[106:109], v200, s[6:7] offset:0
	global_load_dwordx4 v[102:105], v200, s[4:5] offset:16
	global_load_dwordx4 v[110:113], v200, s[6:7] offset:16
	v_add_u32_e32 v6, s52, v16
	v_add_u32_e32 v6, 16, v6
	v_and_b32_e32 v6, 63, v6
	v_lshl_or_b32 v200, v6, 7, v15
	global_load_dwordx4 v[114:117], v200, s[4:5] offset:0
	global_load_dwordx4 v[122:125], v200, s[6:7] offset:0
	global_load_dwordx4 v[118:121], v200, s[4:5] offset:16
	global_load_dwordx4 v[126:129], v200, s[6:7] offset:16
	v_lshlrev_b32_e32 v7, 8, v16
	v_or_b32_e32 v6, 0, v17
	v_xor_b32_e32 v6, v6, v16
	v_lshl_or_b32 v6, v6, 4, v7
	v_add_u32_e32 v234, 0x10000, v6
	v_or_b32_e32 v6, 4, v17
	v_xor_b32_e32 v6, v6, v16
	v_lshl_or_b32 v6, v6, 4, v7
	v_add_u32_e32 v235, 0x10000, v6
	v_or_b32_e32 v6, 8, v17
	v_xor_b32_e32 v6, v6, v16
	v_lshl_or_b32 v6, v6, 4, v7
	v_add_u32_e32 v236, 0x10000, v6
	v_or_b32_e32 v6, 12, v17
	v_xor_b32_e32 v6, v6, v16
	v_lshl_or_b32 v6, v6, 4, v7
	v_add_u32_e32 v237, 0x10000, v6
	v_bfe_u32 v6, v1, 2, 2
	v_lshl_or_b32 v6, v17, 2, v6
	v_and_b32_e32 v201, 7, v6
	v_and_b32_e32 v7, 3, v1
	v_lshlrev_b32_e32 v7, 3, v7
	v_lshl_or_b32 v7, v6, 8, v7
	v_xor_b32_e32 v12, 0, v201
	v_lshl_or_b32 v238, v12, 5, v7
	v_xor_b32_e32 v12, 1, v201
	v_lshl_or_b32 v239, v12, 5, v7
	v_xor_b32_e32 v12, 2, v201
	v_lshl_or_b32 v240, v12, 5, v7
	v_xor_b32_e32 v12, 3, v201
	v_lshl_or_b32 v241, v12, 5, v7
	v_xor_b32_e32 v12, 4, v201
	v_lshl_or_b32 v242, v12, 5, v7
	v_xor_b32_e32 v12, 5, v201
	v_lshl_or_b32 v243, v12, 5, v7
	v_xor_b32_e32 v12, 6, v201
	v_lshl_or_b32 v244, v12, 5, v7
	v_xor_b32_e32 v12, 7, v201
	v_lshl_or_b32 v245, v12, 5, v7
	s_waitcnt vmcnt(0)
; #define QF(d, e) __uint_as_float(((unsigned)(unsigned short)qr[d][e]) << 16)
; template <typename TQ> ...
;     ...
;   {
;     float ss = 0.f;
;     ...
; #pragma unroll
;     for (int d0 = 0; d0 < 8; ++d0)
; #pragma unroll
;       for (int e = 0; e < 8; ++e) { const float x = QF(d0, e); ss += x * x; }
;     ss += __shfl_xor(ss, 32);
;     const float rn = (SCALE * 1.4426950408889634f) / sqrtf(ss * (1.0f / 128.0f) + 1e-6f);
;     const int t = trow0 + wid * QBLK + r32; const int prow = t >> 6, pcol = t & 63;
; #pragma unroll
;     for (int hf = 0; hf < 2; ++hf)
; #pragma unroll
;       for (int dd = 0; dd < 2; ++dd) {
;         const int dl = 4 * hf + dd, du = dl + 2;
;         const int f0 = 16 * dd + 8 * hi;
;         const float* cp = rc + (hf ? pcol : prow) * 32 + f0; const float* sp = rsn + (hf ? pcol : prow) * 32 + f0;
;         const float* gl = gq + 16 * dl + 8 * hi; const float* gu = gq + 16 * du + 8 * hi;
;         unsigned wl[4], wu[4];
; #pragma unroll
;         for (int e = 0; e < 8; e += 2) {
;           float o1[2], o2[2];
; #pragma unroll
;           for (int k = 0; k < 2; ++k) { const float x1 = QF(dl, e + k) * rn * gl[e + k], x2 = QF(du, e + k) * rn * gu[e + k]; const float c = cp[e + k], sn = sp[e + k];
;             o1[k] = x1 * c - x2 * sn; o2[k] = x2 * c + x1 * sn; }
;           wl[e >> 1] = cvtpk(o1[0], o1[1]); wu[e >> 1] = cvtpk(o2[0], o2[1]);
;         }
;         u32x4 vl = {wl[0], wl[1], wl[2], wl[3]}, vu = {wu[0], wu[1], wu[2], wu[3]};
;         qr[dl] = *reinterpret_cast<bf16x8*>(&vl); qr[du] = *reinterpret_cast<bf16x8*>(&vu);
;       }
;   }
	v_lshlrev_b32_e32 v50, 16, v146
	v_and_b32_e32 v51, 0xffff0000, v146
	v_lshlrev_b32_e32 v52, 16, v147
	v_and_b32_e32 v53, 0xffff0000, v147
	v_lshlrev_b32_e32 v54, 16, v148
	v_and_b32_e32 v55, 0xffff0000, v148
	v_lshlrev_b32_e32 v56, 16, v149
	v_and_b32_e32 v57, 0xffff0000, v149
	v_lshlrev_b32_e32 v58, 16, v150
	v_and_b32_e32 v59, 0xffff0000, v150
	v_lshlrev_b32_e32 v60, 16, v151
	v_and_b32_e32 v61, 0xffff0000, v151
	v_lshlrev_b32_e32 v62, 16, v152
	v_and_b32_e32 v63, 0xffff0000, v152
	v_lshlrev_b32_e32 v64, 16, v153
	v_and_b32_e32 v65, 0xffff0000, v153
	v_lshlrev_b32_e32 v66, 16, v154
	v_and_b32_e32 v67, 0xffff0000, v154
	v_lshlrev_b32_e32 v68, 16, v155
	v_and_b32_e32 v69, 0xffff0000, v155
	v_lshlrev_b32_e32 v70, 16, v156
	v_and_b32_e32 v71, 0xffff0000, v156
	v_lshlrev_b32_e32 v72, 16, v157
	v_and_b32_e32 v73, 0xffff0000, v157
	v_lshlrev_b32_e32 v74, 16, v158
	v_and_b32_e32 v75, 0xffff0000, v158
	v_lshlrev_b32_e32 v76, 16, v159
	v_and_b32_e32 v77, 0xffff0000, v159
	v_lshlrev_b32_e32 v78, 16, v160
	v_and_b32_e32 v79, 0xffff0000, v160
	v_lshlrev_b32_e32 v80, 16, v161
	v_and_b32_e32 v81, 0xffff0000, v161
	v_mul_f32_e32 v130, v50, v50
	v_fmac_f32_e32 v130, v51, v51
	v_fmac_f32_e32 v130, v52, v52
	v_fmac_f32_e32 v130, v53, v53
	v_fmac_f32_e32 v130, v54, v54
	v_fmac_f32_e32 v130, v55, v55
	v_fmac_f32_e32 v130, v56, v56
	v_fmac_f32_e32 v130, v57, v57
	v_fmac_f32_e32 v130, v58, v58
	v_fmac_f32_e32 v130, v59, v59
	v_fmac_f32_e32 v130, v60, v60
	v_fmac_f32_e32 v130, v61, v61
	v_fmac_f32_e32 v130, v62, v62
	v_fmac_f32_e32 v130, v63, v63
	v_fmac_f32_e32 v130, v64, v64
	v_fmac_f32_e32 v130, v65, v65
	v_fmac_f32_e32 v130, v66, v66
	v_fmac_f32_e32 v130, v67, v67
	v_fmac_f32_e32 v130, v68, v68
	v_fmac_f32_e32 v130, v69, v69
	v_fmac_f32_e32 v130, v70, v70
	v_fmac_f32_e32 v130, v71, v71
	v_fmac_f32_e32 v130, v72, v72
	v_fmac_f32_e32 v130, v73, v73
	v_fmac_f32_e32 v130, v74, v74
	v_fmac_f32_e32 v130, v75, v75
	v_fmac_f32_e32 v130, v76, v76
	v_fmac_f32_e32 v130, v77, v77
	v_fmac_f32_e32 v130, v78, v78
	v_fmac_f32_e32 v130, v79, v79
	v_fmac_f32_e32 v130, v80, v80
	v_fmac_f32_e32 v130, v81, v81
	ds_swizzle_b32 v132, v130 offset:swizzle(SWAP,16)
	s_waitcnt lgkmcnt(0)
	v_add_f32_e32 v130, v130, v132
	v_mov_b32_e32 v132, v130
	s_nop 1
	v_permlane32_swap_b32_e32 v130, v132
	v_add_f32_e32 v130, v130, v132
	v_fmamk_f32 v130, v130, 0x3c000000, v199
	v_rsq_f32_e32 v130, v130
	s_nop 0
	v_mul_f32_e32 v131, s77, v130
	v_mul_f32_e32 v50, v50, v131
	v_mul_f32_e32 v50, v50, v18
	v_mul_f32_e32 v51, v51, v131
	v_mul_f32_e32 v51, v51, v19
	v_mul_f32_e32 v52, v52, v131
	v_mul_f32_e32 v52, v52, v20
	v_mul_f32_e32 v53, v53, v131
	v_mul_f32_e32 v53, v53, v21
	v_mul_f32_e32 v54, v54, v131
	v_mul_f32_e32 v54, v54, v22
	v_mul_f32_e32 v55, v55, v131
	v_mul_f32_e32 v55, v55, v23
	v_mul_f32_e32 v56, v56, v131
	v_mul_f32_e32 v56, v56, v24
	v_mul_f32_e32 v57, v57, v131
	v_mul_f32_e32 v57, v57, v25
	v_mul_f32_e32 v58, v58, v131
	v_mul_f32_e32 v58, v58, v26
	v_mul_f32_e32 v59, v59, v131
	v_mul_f32_e32 v59, v59, v27
	v_mul_f32_e32 v60, v60, v131
	v_mul_f32_e32 v60, v60, v28
	v_mul_f32_e32 v61, v61, v131
	v_mul_f32_e32 v61, v61, v29
	v_mul_f32_e32 v62, v62, v131
	v_mul_f32_e32 v62, v62, v30
	v_mul_f32_e32 v63, v63, v131
	v_mul_f32_e32 v63, v63, v31
	v_mul_f32_e32 v64, v64, v131
	v_mul_f32_e32 v64, v64, v32
	v_mul_f32_e32 v65, v65, v131
	v_mul_f32_e32 v65, v65, v33
	v_mul_f32_e32 v66, v66, v131
	v_mul_f32_e32 v66, v66, v34
	v_mul_f32_e32 v67, v67, v131
	v_mul_f32_e32 v67, v67, v35
	v_mul_f32_e32 v68, v68, v131
	v_mul_f32_e32 v68, v68, v36
	v_mul_f32_e32 v69, v69, v131
	v_mul_f32_e32 v69, v69, v37
	v_mul_f32_e32 v70, v70, v131
	v_mul_f32_e32 v70, v70, v38
	v_mul_f32_e32 v71, v71, v131
	v_mul_f32_e32 v71, v71, v39
	v_mul_f32_e32 v72, v72, v131
	v_mul_f32_e32 v72, v72, v40
	v_mul_f32_e32 v73, v73, v131
	v_mul_f32_e32 v73, v73, v41
	v_mul_f32_e32 v74, v74, v131
	v_mul_f32_e32 v74, v74, v42
	v_mul_f32_e32 v75, v75, v131
	v_mul_f32_e32 v75, v75, v43
	v_mul_f32_e32 v76, v76, v131
	v_mul_f32_e32 v76, v76, v44
	v_mul_f32_e32 v77, v77, v131
	v_mul_f32_e32 v77, v77, v45
	v_mul_f32_e32 v78, v78, v131
	v_mul_f32_e32 v78, v78, v46
	v_mul_f32_e32 v79, v79, v131
	v_mul_f32_e32 v79, v79, v47
	v_mul_f32_e32 v80, v80, v131
	v_mul_f32_e32 v80, v80, v48
	v_mul_f32_e32 v81, v81, v131
	v_mul_f32_e32 v81, v81, v49
	v_mul_f32_e32 v133, v58, v90
	v_mul_f32_e32 v134, v50, v90
	v_fma_f32 v50, v50, v82, -v133
	v_fma_f32 v58, v58, v82, v134
	v_mul_f32_e32 v133, v59, v91
	v_mul_f32_e32 v134, v51, v91
	v_fma_f32 v51, v51, v83, -v133
	v_fma_f32 v59, v59, v83, v134
	v_mul_f32_e32 v133, v60, v92
	v_mul_f32_e32 v134, v52, v92
	v_fma_f32 v52, v52, v84, -v133
	v_fma_f32 v60, v60, v84, v134
	v_mul_f32_e32 v133, v61, v93
	v_mul_f32_e32 v134, v53, v93
	v_fma_f32 v53, v53, v85, -v133
	v_fma_f32 v61, v61, v85, v134
	v_mul_f32_e32 v133, v62, v94
	v_mul_f32_e32 v134, v54, v94
	v_fma_f32 v54, v54, v86, -v133
	v_fma_f32 v62, v62, v86, v134
	v_mul_f32_e32 v133, v63, v95
	v_mul_f32_e32 v134, v55, v95
	v_fma_f32 v55, v55, v87, -v133
	v_fma_f32 v63, v63, v87, v134
	v_mul_f32_e32 v133, v64, v96
	v_mul_f32_e32 v134, v56, v96
	v_fma_f32 v56, v56, v88, -v133
	v_fma_f32 v64, v64, v88, v134
	v_mul_f32_e32 v133, v65, v97
	v_mul_f32_e32 v134, v57, v97
	v_fma_f32 v57, v57, v89, -v133
	v_fma_f32 v65, v65, v89, v134
	v_mul_f32_e32 v133, v74, v106
	v_mul_f32_e32 v134, v66, v106
	v_fma_f32 v66, v66, v98, -v133
	v_fma_f32 v74, v74, v98, v134
	v_mul_f32_e32 v133, v75, v107
	v_mul_f32_e32 v134, v67, v107
	v_fma_f32 v67, v67, v99, -v133
	v_fma_f32 v75, v75, v99, v134
	v_mul_f32_e32 v133, v76, v108
	v_mul_f32_e32 v134, v68, v108
	v_fma_f32 v68, v68, v100, -v133
; #define QF(d, e) __uint_as_float(((unsigned)(unsigned short)qr[d][e]) << 16)
; template <typename TQ> ...
;     ...
;   {
;     float ss = 0.f;
;     ...
; #pragma unroll
;     for (int d0 = 0; d0 < 8; ++d0)
; #pragma unroll
;       for (int e = 0; e < 8; ++e) { const float x = QF(d0, e); ss += x * x; }
;     ss += __shfl_xor(ss, 32);
;     const float rn = (SCALE * 1.4426950408889634f) / sqrtf(ss * (1.0f / 128.0f) + 1e-6f);
;     const int t = trow0 + wid * QBLK + r32; const int prow = t >> 6, pcol = t & 63;
; #pragma unroll
;     for (int hf = 0; hf < 2; ++hf)
; #pragma unroll
;       for (int dd = 0; dd < 2; ++dd) {
;         const int dl = 4 * hf + dd, du = dl + 2;
;         const int f0 = 16 * dd + 8 * hi;
;         const float* cp = rc + (hf ? pcol : prow) * 32 + f0; const float* sp = rsn + (hf ? pcol : prow) * 32 + f0;
;         const float* gl = gq + 16 * dl + 8 * hi; const float* gu = gq + 16 * du + 8 * hi;
;         unsigned wl[4], wu[4];
; #pragma unroll
;         for (int e = 0; e < 8; e += 2) {
;           float o1[2], o2[2];
; #pragma unroll
;           for (int k = 0; k < 2; ++k) { const float x1 = QF(dl, e + k) * rn * gl[e + k], x2 = QF(du, e + k) * rn * gu[e + k]; const float c = cp[e + k], sn = sp[e + k];
;             o1[k] = x1 * c - x2 * sn; o2[k] = x2 * c + x1 * sn; }
;           wl[e >> 1] = cvtpk(o1[0], o1[1]); wu[e >> 1] = cvtpk(o2[0], o2[1]);
;         }
;         u32x4 vl = {wl[0], wl[1], wl[2], wl[3]}, vu = {wu[0], wu[1], wu[2], wu[3]};
;         qr[dl] = *reinterpret_cast<bf16x8*>(&vl); qr[du] = *reinterpret_cast<bf16x8*>(&vu);
;       }
;   }
	v_fma_f32 v76, v76, v100, v134
	v_mul_f32_e32 v133, v77, v109
	v_mul_f32_e32 v134, v69, v109
	v_fma_f32 v69, v69, v101, -v133
	v_fma_f32 v77, v77, v101, v134
	v_mul_f32_e32 v133, v78, v110
	v_mul_f32_e32 v134, v70, v110
	v_fma_f32 v70, v70, v102, -v133
	v_fma_f32 v78, v78, v102, v134
	v_mul_f32_e32 v133, v79, v111
	v_mul_f32_e32 v134, v71, v111
	v_fma_f32 v71, v71, v103, -v133
	v_fma_f32 v79, v79, v103, v134
	v_mul_f32_e32 v133, v80, v112
	v_mul_f32_e32 v134, v72, v112
	v_fma_f32 v72, v72, v104, -v133
	v_fma_f32 v80, v80, v104, v134
	v_mul_f32_e32 v133, v81, v113
	v_mul_f32_e32 v134, v73, v113
	v_fma_f32 v73, v73, v105, -v133
	v_fma_f32 v81, v81, v105, v134
	v_cvt_pk_bf16_f32 v146, v50, v51
	v_cvt_pk_bf16_f32 v147, v52, v53
	v_cvt_pk_bf16_f32 v148, v54, v55
	v_cvt_pk_bf16_f32 v149, v56, v57
	v_cvt_pk_bf16_f32 v150, v58, v59
	v_cvt_pk_bf16_f32 v151, v60, v61
	v_cvt_pk_bf16_f32 v152, v62, v63
	v_cvt_pk_bf16_f32 v153, v64, v65
	v_cvt_pk_bf16_f32 v154, v66, v67
	v_cvt_pk_bf16_f32 v155, v68, v69
	v_cvt_pk_bf16_f32 v156, v70, v71
	v_cvt_pk_bf16_f32 v157, v72, v73
	v_cvt_pk_bf16_f32 v158, v74, v75
	v_cvt_pk_bf16_f32 v159, v76, v77
	v_cvt_pk_bf16_f32 v160, v78, v79
	v_cvt_pk_bf16_f32 v161, v80, v81
	v_lshlrev_b32_e32 v50, 16, v162
	v_and_b32_e32 v51, 0xffff0000, v162
	v_lshlrev_b32_e32 v52, 16, v163
	v_and_b32_e32 v53, 0xffff0000, v163
	v_lshlrev_b32_e32 v54, 16, v164
	v_and_b32_e32 v55, 0xffff0000, v164
	v_lshlrev_b32_e32 v56, 16, v165
	v_and_b32_e32 v57, 0xffff0000, v165
	v_lshlrev_b32_e32 v58, 16, v166
	v_and_b32_e32 v59, 0xffff0000, v166
	v_lshlrev_b32_e32 v60, 16, v167
	v_and_b32_e32 v61, 0xffff0000, v167
	v_lshlrev_b32_e32 v62, 16, v168
	v_and_b32_e32 v63, 0xffff0000, v168
	v_lshlrev_b32_e32 v64, 16, v169
	v_and_b32_e32 v65, 0xffff0000, v169
	v_lshlrev_b32_e32 v66, 16, v170
	v_and_b32_e32 v67, 0xffff0000, v170
	v_lshlrev_b32_e32 v68, 16, v171
	v_and_b32_e32 v69, 0xffff0000, v171
	v_lshlrev_b32_e32 v70, 16, v172
	v_and_b32_e32 v71, 0xffff0000, v172
	v_lshlrev_b32_e32 v72, 16, v173
	v_and_b32_e32 v73, 0xffff0000, v173
	v_lshlrev_b32_e32 v74, 16, v174
	v_and_b32_e32 v75, 0xffff0000, v174
	v_lshlrev_b32_e32 v76, 16, v175
	v_and_b32_e32 v77, 0xffff0000, v175
	v_lshlrev_b32_e32 v78, 16, v176
	v_and_b32_e32 v79, 0xffff0000, v176
	v_lshlrev_b32_e32 v80, 16, v177
	v_and_b32_e32 v81, 0xffff0000, v177
	v_mul_f32_e32 v130, v50, v50
	v_fmac_f32_e32 v130, v51, v51
	v_fmac_f32_e32 v130, v52, v52
	v_fmac_f32_e32 v130, v53, v53
	v_fmac_f32_e32 v130, v54, v54
	v_fmac_f32_e32 v130, v55, v55
	v_fmac_f32_e32 v130, v56, v56
	v_fmac_f32_e32 v130, v57, v57
	v_fmac_f32_e32 v130, v58, v58
	v_fmac_f32_e32 v130, v59, v59
	v_fmac_f32_e32 v130, v60, v60
	v_fmac_f32_e32 v130, v61, v61
	v_fmac_f32_e32 v130, v62, v62
	v_fmac_f32_e32 v130, v63, v63
	v_fmac_f32_e32 v130, v64, v64
	v_fmac_f32_e32 v130, v65, v65
	v_fmac_f32_e32 v130, v66, v66
	v_fmac_f32_e32 v130, v67, v67
	v_fmac_f32_e32 v130, v68, v68
	v_fmac_f32_e32 v130, v69, v69
	v_fmac_f32_e32 v130, v70, v70
	v_fmac_f32_e32 v130, v71, v71
	v_fmac_f32_e32 v130, v72, v72
	v_fmac_f32_e32 v130, v73, v73
	v_fmac_f32_e32 v130, v74, v74
	v_fmac_f32_e32 v130, v75, v75
	v_fmac_f32_e32 v130, v76, v76
	v_fmac_f32_e32 v130, v77, v77
	v_fmac_f32_e32 v130, v78, v78
	v_fmac_f32_e32 v130, v79, v79
	v_fmac_f32_e32 v130, v80, v80
	v_fmac_f32_e32 v130, v81, v81
	ds_swizzle_b32 v132, v130 offset:swizzle(SWAP,16)
	s_waitcnt lgkmcnt(0)
	v_add_f32_e32 v130, v130, v132
	v_mov_b32_e32 v132, v130
	s_nop 1
	v_permlane32_swap_b32_e32 v130, v132
	v_add_f32_e32 v130, v130, v132
	v_fmamk_f32 v130, v130, 0x3c000000, v199
	v_rsq_f32_e32 v130, v130
	s_nop 0
	v_mul_f32_e32 v131, s77, v130
	v_mul_f32_e32 v50, v50, v131
	v_mul_f32_e32 v50, v50, v18
	v_mul_f32_e32 v51, v51, v131
	v_mul_f32_e32 v51, v51, v19
	v_mul_f32_e32 v52, v52, v131
	v_mul_f32_e32 v52, v52, v20
	v_mul_f32_e32 v53, v53, v131
	v_mul_f32_e32 v53, v53, v21
	v_mul_f32_e32 v54, v54, v131
	v_mul_f32_e32 v54, v54, v22
	v_mul_f32_e32 v55, v55, v131
	v_mul_f32_e32 v55, v55, v23
	v_mul_f32_e32 v56, v56, v131
	v_mul_f32_e32 v56, v56, v24
	v_mul_f32_e32 v57, v57, v131
	v_mul_f32_e32 v57, v57, v25
	v_mul_f32_e32 v58, v58, v131
	v_mul_f32_e32 v58, v58, v26
	v_mul_f32_e32 v59, v59, v131
	v_mul_f32_e32 v59, v59, v27
	v_mul_f32_e32 v60, v60, v131
	v_mul_f32_e32 v60, v60, v28
	v_mul_f32_e32 v61, v61, v131
	v_mul_f32_e32 v61, v61, v29
	v_mul_f32_e32 v62, v62, v131
	v_mul_f32_e32 v62, v62, v30
	v_mul_f32_e32 v63, v63, v131
	v_mul_f32_e32 v63, v63, v31
	v_mul_f32_e32 v64, v64, v131
	v_mul_f32_e32 v64, v64, v32
	v_mul_f32_e32 v65, v65, v131
	v_mul_f32_e32 v65, v65, v33
	v_mul_f32_e32 v66, v66, v131
	v_mul_f32_e32 v66, v66, v34
	v_mul_f32_e32 v67, v67, v131
	v_mul_f32_e32 v67, v67, v35
	v_mul_f32_e32 v68, v68, v131
	v_mul_f32_e32 v68, v68, v36
	v_mul_f32_e32 v69, v69, v131
	v_mul_f32_e32 v69, v69, v37
	v_mul_f32_e32 v70, v70, v131
	v_mul_f32_e32 v70, v70, v38
	v_mul_f32_e32 v71, v71, v131
	v_mul_f32_e32 v71, v71, v39
	v_mul_f32_e32 v72, v72, v131
	v_mul_f32_e32 v72, v72, v40
	v_mul_f32_e32 v73, v73, v131
	v_mul_f32_e32 v73, v73, v41
	v_mul_f32_e32 v74, v74, v131
	v_mul_f32_e32 v74, v74, v42
	v_mul_f32_e32 v75, v75, v131
	v_mul_f32_e32 v75, v75, v43
	v_mul_f32_e32 v76, v76, v131
	v_mul_f32_e32 v76, v76, v44
	v_mul_f32_e32 v77, v77, v131
	v_mul_f32_e32 v77, v77, v45
	v_mul_f32_e32 v78, v78, v131
	v_mul_f32_e32 v78, v78, v46
	v_mul_f32_e32 v79, v79, v131
	v_mul_f32_e32 v79, v79, v47
	v_mul_f32_e32 v80, v80, v131
	v_mul_f32_e32 v80, v80, v48
	v_mul_f32_e32 v81, v81, v131
	v_mul_f32_e32 v81, v81, v49
	v_mul_f32_e32 v133, v58, v90
	v_mul_f32_e32 v134, v50, v90
	v_fma_f32 v50, v50, v82, -v133
	v_fma_f32 v58, v58, v82, v134
; #define SBAR() __builtin_amdgcn_sched_barrier(0)
; #define QF(d, e) __uint_as_float(((unsigned)(unsigned short)qr[d][e]) << 16)
; template <typename TQ> ...
;     ...
;   {
;     float ss = 0.f;
;     ...
; #pragma unroll
;     for (int d0 = 0; d0 < 8; ++d0)
; #pragma unroll
;       for (int e = 0; e < 8; ++e) { const float x = QF(d0, e); ss += x * x; }
;     ss += __shfl_xor(ss, 32);
;     const float rn = (SCALE * 1.4426950408889634f) / sqrtf(ss * (1.0f / 128.0f) + 1e-6f);
;     const int t = trow0 + wid * QBLK + r32; const int prow = t >> 6, pcol = t & 63;
; #pragma unroll
;     for (int hf = 0; hf < 2; ++hf)
; #pragma unroll
;       for (int dd = 0; dd < 2; ++dd) {
;         const int dl = 4 * hf + dd, du = dl + 2;
;         const int f0 = 16 * dd + 8 * hi;
;         const float* cp = rc + (hf ? pcol : prow) * 32 + f0; const float* sp = rsn + (hf ? pcol : prow) * 32 + f0;
;         const float* gl = gq + 16 * dl + 8 * hi; const float* gu = gq + 16 * du + 8 * hi;
;         unsigned wl[4], wu[4];
; #pragma unroll
;         for (int e = 0; e < 8; e += 2) {
;           float o1[2], o2[2];
; #pragma unroll
;           for (int k = 0; k < 2; ++k) { const float x1 = QF(dl, e + k) * rn * gl[e + k], x2 = QF(du, e + k) * rn * gu[e + k]; const float c = cp[e + k], sn = sp[e + k];
;             o1[k] = x1 * c - x2 * sn; o2[k] = x2 * c + x1 * sn; }
;           wl[e >> 1] = cvtpk(o1[0], o1[1]); wu[e >> 1] = cvtpk(o2[0], o2[1]);
;         }
;         u32x4 vl = {wl[0], wl[1], wl[2], wl[3]}, vu = {wu[0], wu[1], wu[2], wu[3]};
;         qr[dl] = *reinterpret_cast<bf16x8*>(&vl); qr[du] = *reinterpret_cast<bf16x8*>(&vu);
;       }
;   }
;     ...
;   SBAR();
;   f32x16 pA0, pA1, pB0, pB1; bf16x8 pa0, pa1, pa2, pa3; const int NT = seq / KVBLK;
;   f32x16 negm;
; #pragma unroll
;   for (int r = 0; r < 16; ++r) negm[r] = -mC;
;   asm volatile("" : "+v"(negm));
;   asm volatile("s_waitcnt vmcnt(0)" ::: "memory"); SWRITE(0, SE); __syncthreads();
;   qkt(pA0, pA1, K_lds, qr, r32, hi, negm); partialSM(pA0, pA1, mC);
	v_mul_f32_e32 v133, v59, v91
	v_mul_f32_e32 v134, v51, v91
	v_fma_f32 v51, v51, v83, -v133
	v_fma_f32 v59, v59, v83, v134
	v_mul_f32_e32 v133, v60, v92
	v_mul_f32_e32 v134, v52, v92
	v_fma_f32 v52, v52, v84, -v133
	v_fma_f32 v60, v60, v84, v134
	v_mul_f32_e32 v133, v61, v93
	v_mul_f32_e32 v134, v53, v93
	v_fma_f32 v53, v53, v85, -v133
	v_fma_f32 v61, v61, v85, v134
	v_mul_f32_e32 v133, v62, v94
	v_mul_f32_e32 v134, v54, v94
	v_fma_f32 v54, v54, v86, -v133
	v_fma_f32 v62, v62, v86, v134
	v_mul_f32_e32 v133, v63, v95
	v_mul_f32_e32 v134, v55, v95
	v_fma_f32 v55, v55, v87, -v133
	v_fma_f32 v63, v63, v87, v134
	v_mul_f32_e32 v133, v64, v96
	v_mul_f32_e32 v134, v56, v96
	v_fma_f32 v56, v56, v88, -v133
	v_fma_f32 v64, v64, v88, v134
	v_mul_f32_e32 v133, v65, v97
	v_mul_f32_e32 v134, v57, v97
	v_fma_f32 v57, v57, v89, -v133
	v_fma_f32 v65, v65, v89, v134
	v_mul_f32_e32 v133, v74, v122
	v_mul_f32_e32 v134, v66, v122
	v_fma_f32 v66, v66, v114, -v133
	v_fma_f32 v74, v74, v114, v134
	v_mul_f32_e32 v133, v75, v123
	v_mul_f32_e32 v134, v67, v123
	v_fma_f32 v67, v67, v115, -v133
	v_fma_f32 v75, v75, v115, v134
	v_mul_f32_e32 v133, v76, v124
	v_mul_f32_e32 v134, v68, v124
	v_fma_f32 v68, v68, v116, -v133
	v_fma_f32 v76, v76, v116, v134
	v_mul_f32_e32 v133, v77, v125
	v_mul_f32_e32 v134, v69, v125
	v_fma_f32 v69, v69, v117, -v133
	v_fma_f32 v77, v77, v117, v134
	v_mul_f32_e32 v133, v78, v126
	v_mul_f32_e32 v134, v70, v126
	v_fma_f32 v70, v70, v118, -v133
	v_fma_f32 v78, v78, v118, v134
	v_mul_f32_e32 v133, v79, v127
	v_mul_f32_e32 v134, v71, v127
	v_fma_f32 v71, v71, v119, -v133
	v_fma_f32 v79, v79, v119, v134
	v_mul_f32_e32 v133, v80, v128
	v_mul_f32_e32 v134, v72, v128
	v_fma_f32 v72, v72, v120, -v133
	v_fma_f32 v80, v80, v120, v134
	v_mul_f32_e32 v133, v81, v129
	v_mul_f32_e32 v134, v73, v129
	v_fma_f32 v73, v73, v121, -v133
	v_fma_f32 v81, v81, v121, v134
	v_cvt_pk_bf16_f32 v162, v50, v51
	v_cvt_pk_bf16_f32 v163, v52, v53
	v_cvt_pk_bf16_f32 v164, v54, v55
	v_cvt_pk_bf16_f32 v165, v56, v57
	v_cvt_pk_bf16_f32 v166, v58, v59
	v_cvt_pk_bf16_f32 v167, v60, v61
	v_cvt_pk_bf16_f32 v168, v62, v63
	v_cvt_pk_bf16_f32 v169, v64, v65
	v_cvt_pk_bf16_f32 v170, v66, v67
	v_cvt_pk_bf16_f32 v171, v68, v69
	v_cvt_pk_bf16_f32 v172, v70, v71
	v_cvt_pk_bf16_f32 v173, v72, v73
	v_cvt_pk_bf16_f32 v174, v74, v75
	v_cvt_pk_bf16_f32 v175, v76, v77
	v_cvt_pk_bf16_f32 v176, v78, v79
	v_cvt_pk_bf16_f32 v177, v80, v81
	v_mov_b32_e32 v18, 0
	v_mov_b32_e32 v19, 0
	v_mov_b32_e32 v20, 0
	v_mov_b32_e32 v21, 0
	v_mov_b32_e32 v22, 0
	v_mov_b32_e32 v23, 0
	v_mov_b32_e32 v24, 0
	v_mov_b32_e32 v25, 0
	v_mov_b32_e32 v26, 0
	v_mov_b32_e32 v27, 0
	v_mov_b32_e32 v28, 0
	v_mov_b32_e32 v29, 0
	v_mov_b32_e32 v30, 0
	v_mov_b32_e32 v31, 0
	v_mov_b32_e32 v32, 0
	v_mov_b32_e32 v33, 0
	v_mov_b32_e32 v34, 0
	v_mov_b32_e32 v35, 0
	v_mov_b32_e32 v36, 0
	v_mov_b32_e32 v37, 0
	v_mov_b32_e32 v38, 0
	v_mov_b32_e32 v39, 0
	v_mov_b32_e32 v40, 0
	v_mov_b32_e32 v41, 0
	v_mov_b32_e32 v42, 0
	v_mov_b32_e32 v43, 0
	v_mov_b32_e32 v44, 0
	v_mov_b32_e32 v45, 0
	v_mov_b32_e32 v46, 0
	v_mov_b32_e32 v47, 0
	v_mov_b32_e32 v48, 0
	v_mov_b32_e32 v49, 0
	v_mov_b32_e32 v50, 0
	v_mov_b32_e32 v51, 0
	v_mov_b32_e32 v52, 0
	v_mov_b32_e32 v53, 0
	v_mov_b32_e32 v54, 0
	v_mov_b32_e32 v55, 0
	v_mov_b32_e32 v56, 0
	v_mov_b32_e32 v57, 0
	v_mov_b32_e32 v58, 0
	v_mov_b32_e32 v59, 0
	v_mov_b32_e32 v60, 0
	v_mov_b32_e32 v61, 0
	v_mov_b32_e32 v62, 0
	v_mov_b32_e32 v63, 0
	v_mov_b32_e32 v64, 0
	v_mov_b32_e32 v65, 0
	v_mov_b32_e32 v66, 0
	v_mov_b32_e32 v67, 0
	v_mov_b32_e32 v68, 0
	v_mov_b32_e32 v69, 0
	v_mov_b32_e32 v70, 0
	v_mov_b32_e32 v71, 0
	v_mov_b32_e32 v72, 0
	v_mov_b32_e32 v73, 0
	v_mov_b32_e32 v74, 0
	v_mov_b32_e32 v75, 0
	v_mov_b32_e32 v76, 0
	v_mov_b32_e32 v77, 0
	v_mov_b32_e32 v78, 0
	v_mov_b32_e32 v79, 0
	v_mov_b32_e32 v80, 0
	v_mov_b32_e32 v81, 0
	v_mov_b32_e32 v250, 0
	v_mov_b32_e32 v251, 0
	s_barrier
	ds_read_b128 v[178:181], v234 offset:0
	ds_read_b128 v[182:185], v234 offset:4096
	ds_read_b128 v[186:189], v234 offset:8192
	ds_read_b128 v[190:193], v234 offset:12288
	s_waitcnt lgkmcnt(3)
	v_mfma_f32_16x16x32_bf16 v[82:85], v[178:181], v[146:149], v[2:5]
	v_mfma_f32_16x16x32_bf16 v[86:89], v[178:181], v[162:165], v[2:5]
	ds_read_b128 v[178:181], v235 offset:0
	s_waitcnt lgkmcnt(3)
	v_mfma_f32_16x16x32_bf16 v[90:93], v[182:185], v[146:149], v[2:5]
	v_mfma_f32_16x16x32_bf16 v[94:97], v[182:185], v[162:165], v[2:5]
	ds_read_b128 v[182:185], v235 offset:4096
	s_waitcnt lgkmcnt(3)
	v_mfma_f32_16x16x32_bf16 v[98:101], v[186:189], v[146:149], v[2:5]
	v_mfma_f32_16x16x32_bf16 v[102:105], v[186:189], v[162:165], v[2:5]
	ds_read_b128 v[186:189], v235 offset:8192
	s_waitcnt lgkmcnt(3)
	v_mfma_f32_16x16x32_bf16 v[106:109], v[190:193], v[146:149], v[2:5]
	v_mfma_f32_16x16x32_bf16 v[110:113], v[190:193], v[162:165], v[2:5]
	ds_read_b128 v[190:193], v235 offset:12288
	s_waitcnt lgkmcnt(3)
	v_mfma_f32_16x16x32_bf16 v[82:85], v[178:181], v[150:153], v[82:85]
	v_mfma_f32_16x16x32_bf16 v[86:89], v[178:181], v[166:169], v[86:89]
	ds_read_b128 v[178:181], v236 offset:0
	s_waitcnt lgkmcnt(3)
	v_mfma_f32_16x16x32_bf16 v[90:93], v[182:185], v[150:153], v[90:93]
	v_mfma_f32_16x16x32_bf16 v[94:97], v[182:185], v[166:169], v[94:97]
	ds_read_b128 v[182:185], v236 offset:4096
	s_waitcnt lgkmcnt(3)
	v_mfma_f32_16x16x32_bf16 v[98:101], v[186:189], v[150:153], v[98:101]
	v_mfma_f32_16x16x32_bf16 v[102:105], v[186:189], v[166:169], v[102:105]
	ds_read_b128 v[186:189], v236 offset:8192
	s_waitcnt lgkmcnt(3)
	v_mfma_f32_16x16x32_bf16 v[106:109], v[190:193], v[150:153], v[106:109]
	v_mfma_f32_16x16x32_bf16 v[110:113], v[190:193], v[166:169], v[110:113]
	ds_read_b128 v[190:193], v236 offset:12288
	s_waitcnt lgkmcnt(3)
; #define SBAR() __builtin_amdgcn_sched_barrier(0)
; #define SLOAD(i, k0) do { sr_[i].vs0 = St::ld8(&Vh[(long)((k0) + sr) * LDK + sc]); sr_[i].vs1 = St::ld8(&Vh[(long)((k0) + 32 + sr) * LDK + sc]); \
;     sr_[i].ks0 = St::ld8(&Kh[(long)((k0) + sr) * LDK + sc]); sr_[i].ks1 = St::ld8(&Kh[(long)((k0) + 32 + sr) * LDK + sc]); } while (0)
; #define SWAIT() do { if constexpr (SDEPTH == 2) asm volatile("s_waitcnt vmcnt(4)" ::: "memory"); else asm volatile("s_waitcnt vmcnt(0)" ::: "memory"); } while (0)
; __device__ __forceinline__ void qkt(f32x16& p0, f32x16& p1, const bf16* Ks, const bf16x8* qr, int r32, int hi, const f32x16& negm) {
; #pragma unroll
;   for (int d0 = 0; d0 < 8; ++d0) { int cb = (d0 * 16 + hi * 8) * 2;
;     bf16x8 b0 = *reinterpret_cast<const bf16x8*>((const char*)Ks + KSWZ(r32, cb));
;     bf16x8 b1 = *reinterpret_cast<const bf16x8*>((const char*)Ks + KSWZ(32 + r32, cb));
;     if (d0 == 0) { p0 = __builtin_amdgcn_mfma_f32_32x32x16_bf16(b0, qr[0], negm, 0, 0, 0); p1 = __builtin_amdgcn_mfma_f32_32x32x16_bf16(b1, qr[0], negm, 0, 0, 0); }
;     else { p0 = __builtin_amdgcn_mfma_f32_32x32x16_bf16(b0, qr[d0], p0, 0, 0, 0); p1 = __builtin_amdgcn_mfma_f32_32x32x16_bf16(b1, qr[d0], p1, 0, 0, 0); } }
; }
; template <typename TQ> ...
;     ...
;   for (int j = 1; j + 1 < NT; j += 2) {
;     SBAR(); SLOAD(SO, (j + SDEPTH) * KVBLK); SBAR();
;     qkt(pB0, pB1, (bf16*)((char*)K_lds + SHM_K), qr, r32, hi, negm);
;     finishSM(pA0, pA1, l_reg, pa0, pa1, pa2, pa3); SBAR();
;     pv_d0(o, vb0, pa0, pa1, pa2, pa3); partialSM(pB0, pB1, mC);
;     __syncthreads(); SWAIT(); SWRITE(0, SE);
;     __syncthreads();
;     SBAR(); if (SDEPTH == 1 || j + 3 < NT) SLOAD(SE, (j + 1 + SDEPTH) * KVBLK); SBAR();
;     qkt(pA0, pA1, K_lds, qr, r32, hi, negm);
	v_mfma_f32_16x16x32_bf16 v[82:85], v[178:181], v[154:157], v[82:85]
	v_mfma_f32_16x16x32_bf16 v[86:89], v[178:181], v[170:173], v[86:89]
	ds_read_b128 v[178:181], v237 offset:0
	s_waitcnt lgkmcnt(3)
	v_mfma_f32_16x16x32_bf16 v[90:93], v[182:185], v[154:157], v[90:93]
	v_mfma_f32_16x16x32_bf16 v[94:97], v[182:185], v[170:173], v[94:97]
	ds_read_b128 v[182:185], v237 offset:4096
	s_waitcnt lgkmcnt(3)
	v_mfma_f32_16x16x32_bf16 v[98:101], v[186:189], v[154:157], v[98:101]
	v_mfma_f32_16x16x32_bf16 v[102:105], v[186:189], v[170:173], v[102:105]
	ds_read_b128 v[186:189], v237 offset:8192
	s_waitcnt lgkmcnt(3)
	v_mfma_f32_16x16x32_bf16 v[106:109], v[190:193], v[154:157], v[106:109]
	v_mfma_f32_16x16x32_bf16 v[110:113], v[190:193], v[170:173], v[110:113]
	ds_read_b128 v[190:193], v237 offset:12288
	s_waitcnt lgkmcnt(3)
	v_mfma_f32_16x16x32_bf16 v[82:85], v[178:181], v[158:161], v[82:85]
	v_mfma_f32_16x16x32_bf16 v[86:89], v[178:181], v[174:177], v[86:89]
	s_waitcnt lgkmcnt(2)
	v_mfma_f32_16x16x32_bf16 v[90:93], v[182:185], v[158:161], v[90:93]
	v_mfma_f32_16x16x32_bf16 v[94:97], v[182:185], v[174:177], v[94:97]
	s_waitcnt lgkmcnt(1)
	v_mfma_f32_16x16x32_bf16 v[98:101], v[186:189], v[158:161], v[98:101]
	v_mfma_f32_16x16x32_bf16 v[102:105], v[186:189], v[174:177], v[102:105]
	s_waitcnt lgkmcnt(0)
	v_mfma_f32_16x16x32_bf16 v[106:109], v[190:193], v[158:161], v[106:109]
	v_mfma_f32_16x16x32_bf16 v[110:113], v[190:193], v[174:177], v[110:113]
	s_nop 7
	v_exp_f32_e32 v82, v82
	v_exp_f32_e32 v83, v83
	v_exp_f32_e32 v84, v84
	v_exp_f32_e32 v85, v85
	v_exp_f32_e32 v86, v86
	v_exp_f32_e32 v87, v87
	v_exp_f32_e32 v88, v88
	v_exp_f32_e32 v89, v89
	v_exp_f32_e32 v90, v90
	v_exp_f32_e32 v91, v91
	v_exp_f32_e32 v92, v92
	v_exp_f32_e32 v93, v93
	v_exp_f32_e32 v94, v94
	v_exp_f32_e32 v95, v95
	v_exp_f32_e32 v96, v96
	v_exp_f32_e32 v97, v97
	v_exp_f32_e32 v98, v98
	v_exp_f32_e32 v99, v99
	v_exp_f32_e32 v100, v100
	v_exp_f32_e32 v101, v101
	v_exp_f32_e32 v102, v102
	v_exp_f32_e32 v103, v103
	v_exp_f32_e32 v104, v104
	v_exp_f32_e32 v105, v105
	v_exp_f32_e32 v106, v106
	v_exp_f32_e32 v107, v107
	v_exp_f32_e32 v108, v108
	v_exp_f32_e32 v109, v109
	v_exp_f32_e32 v110, v110
	v_exp_f32_e32 v111, v111
	v_exp_f32_e32 v112, v112
	v_exp_f32_e32 v113, v113
	ds_read_b128 v[178:181], v234 offset:16384
	ds_read_b128 v[182:185], v234 offset:20480
	ds_read_b128 v[186:189], v234 offset:24576
	ds_read_b128 v[190:193], v234 offset:28672
	s_cmp_lt_u32 s53, 256
	s_cbranch_scc1 .Lattn_older
	s_setprio 1
	s_mov_b32 s15, 0
.Lattn_loop_y:
	s_barrier
	s_waitcnt lgkmcnt(3)
	v_mfma_f32_16x16x32_bf16 v[114:117], v[178:181], v[146:149], v[2:5]
	v_add_f32_e32 v250, v82, v250
	s_add_u32 s98, s98, 0x8000
	s_addc_u32 s99, s99, 0
	s_add_u32 s100, s100, 0x8000
	s_addc_u32 s101, s101, 0
	s_add_u32 m0, s79, 0
	s_nop 0
	global_load_lds_dwordx4 v246, s[98:99]
	v_mfma_f32_16x16x32_bf16 v[118:121], v[178:181], v[162:165], v[2:5]
	ds_read_b128 v[178:181], v235 offset:16384
	v_add_f32_e32 v250, v83, v250
	v_add_f32_e32 v250, v84, v250
	s_waitcnt lgkmcnt(3)
	v_mfma_f32_16x16x32_bf16 v[122:125], v[182:185], v[146:149], v[2:5]
	v_add_f32_e32 v250, v85, v250
	v_mfma_f32_16x16x32_bf16 v[126:129], v[182:185], v[162:165], v[2:5]
	ds_read_b128 v[182:185], v235 offset:20480
	v_add_f32_e32 v250, v90, v250
	v_add_f32_e32 v250, v91, v250
	s_waitcnt lgkmcnt(3)
	v_mfma_f32_16x16x32_bf16 v[130:133], v[186:189], v[146:149], v[2:5]
	v_add_f32_e32 v250, v92, v250
	v_mfma_f32_16x16x32_bf16 v[134:137], v[186:189], v[162:165], v[2:5]
	ds_read_b128 v[186:189], v235 offset:24576
	v_add_f32_e32 v250, v93, v250
	v_cvt_pk_bf16_f32 v82, v82, v83
	s_waitcnt lgkmcnt(3)
	v_mfma_f32_16x16x32_bf16 v[138:141], v[190:193], v[146:149], v[2:5]
	v_cvt_pk_bf16_f32 v83, v84, v85
	v_mfma_f32_16x16x32_bf16 v[142:145], v[190:193], v[162:165], v[2:5]
	ds_read_b128 v[190:193], v235 offset:28672
	v_cvt_pk_bf16_f32 v84, v90, v91
	v_cvt_pk_bf16_f32 v85, v92, v93
	s_waitcnt lgkmcnt(3)
	v_mfma_f32_16x16x32_bf16 v[114:117], v[178:181], v[150:153], v[114:117]
	v_add_f32_e32 v251, v86, v251
	s_add_u32 m0, s79, 1024
	s_nop 0
	global_load_lds_dwordx4 v247, s[98:99]
	v_mfma_f32_16x16x32_bf16 v[118:121], v[178:181], v[166:169], v[118:121]
	ds_read_b128 v[178:181], v236 offset:16384
	v_add_f32_e32 v251, v87, v251
	v_add_f32_e32 v251, v88, v251
	s_waitcnt lgkmcnt(3)
	v_mfma_f32_16x16x32_bf16 v[122:125], v[182:185], v[150:153], v[122:125]
	v_add_f32_e32 v251, v89, v251
	v_mfma_f32_16x16x32_bf16 v[126:129], v[182:185], v[166:169], v[126:129]
	ds_read_b128 v[182:185], v236 offset:20480
	v_add_f32_e32 v251, v94, v251
	v_add_f32_e32 v251, v95, v251
	s_waitcnt lgkmcnt(3)
	v_mfma_f32_16x16x32_bf16 v[130:133], v[186:189], v[150:153], v[130:133]
	v_add_f32_e32 v251, v96, v251
	v_mfma_f32_16x16x32_bf16 v[134:137], v[186:189], v[166:169], v[134:137]
	ds_read_b128 v[186:189], v236 offset:24576
	v_add_f32_e32 v251, v97, v251
	v_cvt_pk_bf16_f32 v86, v86, v87
	s_waitcnt lgkmcnt(3)
	v_mfma_f32_16x16x32_bf16 v[138:141], v[190:193], v[150:153], v[138:141]
	v_cvt_pk_bf16_f32 v87, v88, v89
	v_mfma_f32_16x16x32_bf16 v[142:145], v[190:193], v[166:169], v[142:145]
	ds_read_b128 v[190:193], v236 offset:28672
	v_cvt_pk_bf16_f32 v88, v94, v95
	v_cvt_pk_bf16_f32 v89, v96, v97
	s_waitcnt lgkmcnt(3)
	v_mfma_f32_16x16x32_bf16 v[114:117], v[178:181], v[154:157], v[114:117]
	v_add_f32_e32 v250, v98, v250
	s_add_u32 m0, s80, 49152
	s_nop 0
	global_load_lds_dwordx4 v248, s[100:101]
	v_mfma_f32_16x16x32_bf16 v[118:121], v[178:181], v[170:173], v[118:121]
	ds_read_b128 v[178:181], v237 offset:16384
	v_add_f32_e32 v250, v99, v250
	v_add_f32_e32 v250, v100, v250
	s_waitcnt lgkmcnt(3)
; __device__ __forceinline__ void partialSM(f32x16& p0, f32x16& p1, float mC) {
;     ...
;   for (int r = 0; r < 16; ++r) p0[r] = __builtin_amdgcn_exp2f(p0[r]);
; }
; __device__ __forceinline__ void finishSM(f32x16& p0, f32x16& p1, float& l_reg, bf16x8& pa0, bf16x8& pa1, bf16x8& pa2, bf16x8& pa3) {
;   for (int r = 0; r < 16; ++r) p1[r] = __builtin_amdgcn_exp2f(p1[r]);
;   float ps = 0; for (int r = 0; r < 16; ++r) ps += p0[r]; for (int r = 0; r < 16; ++r) ps += p1[r];
;   { auto rr = __builtin_amdgcn_permlane32_swap(__float_as_uint(ps), __float_as_uint(ps), false, false);
;     ps = __uint_as_float(rr[0]) + __uint_as_float(rr[1]); }
;   l_reg += ps;
;     ...
;   PK4(p0, 0, pa0); PK4(p0, 8, pa1); PK4(p1, 0, pa2); PK4(p1, 8, pa3);
;     ...
; }
; __device__ __forceinline__ void qkt(f32x16& p0, f32x16& p1, const bf16* Ks, const bf16x8* qr, int r32, int hi, const f32x16& negm) {
; #pragma unroll
;   for (int d0 = 0; d0 < 8; ++d0) { int cb = (d0 * 16 + hi * 8) * 2;
;     bf16x8 b0 = *reinterpret_cast<const bf16x8*>((const char*)Ks + KSWZ(r32, cb));
;     bf16x8 b1 = *reinterpret_cast<const bf16x8*>((const char*)Ks + KSWZ(32 + r32, cb));
;     if (d0 == 0) { p0 = __builtin_amdgcn_mfma_f32_32x32x16_bf16(b0, qr[0], negm, 0, 0, 0); p1 = __builtin_amdgcn_mfma_f32_32x32x16_bf16(b1, qr[0], negm, 0, 0, 0); }
;     else { p0 = __builtin_amdgcn_mfma_f32_32x32x16_bf16(b0, qr[d0], p0, 0, 0, 0); p1 = __builtin_amdgcn_mfma_f32_32x32x16_bf16(b1, qr[d0], p1, 0, 0, 0); } }
; }
; __device__ __forceinline__ int v_st(int k, int c) { const int kk = (k & ~0xC) | ((k & 4) << 1) | ((k & 8) >> 1); return ((kk >> 3) * 4 + (c >> 5)) * 512 + ((kk & 7) * 32 + (c & 31)) * 2; }
; __device__ __forceinline__ int v_rd_base(int lane) { return ((lane & 3) << 3) | (((lane >> 2) & 3) << 6) | (((lane >> 4) & 1) << 5) | (((lane >> 5) & 1) << 8); }
; template <int OFF> __device__ __forceinline__ s16x4 tr_read(int vb) {
;   s16x4 r; asm volatile("ds_read_b64_tr_b16 %0, %1 offset:%2" : "=&v"(r) : "v"(vb), "i"(OFF) : "memory"); return r;
; }
; template <int D0> __device__ __forceinline__ void pv_one(f32x16& od, int vb, bf16x8 pa0, bf16x8 pa1, bf16x8 pa2, bf16x8 pa3) {
;   const s16x4 l0 = tr_read<v_rd_off(D0, 0, 0)>(vb), h0 = tr_read<v_rd_off(D0, 0, 1)>(vb), l1 = tr_read<v_rd_off(D0, 1, 0)>(vb), h1 = tr_read<v_rd_off(D0, 1, 1)>(vb);
	v_mfma_f32_16x16x32_bf16 v[122:125], v[182:185], v[154:157], v[122:125]
	v_add_f32_e32 v250, v101, v250
	v_mfma_f32_16x16x32_bf16 v[126:129], v[182:185], v[170:173], v[126:129]
	ds_read_b128 v[182:185], v237 offset:20480
	v_add_f32_e32 v250, v106, v250
	v_add_f32_e32 v250, v107, v250
	s_waitcnt lgkmcnt(3)
	v_mfma_f32_16x16x32_bf16 v[130:133], v[186:189], v[154:157], v[130:133]
	v_add_f32_e32 v250, v108, v250
	ds_read_b64_tr_b16 v[202:203], v238 offset:0
	ds_read_b64_tr_b16 v[204:205], v238 offset:4096
	v_mfma_f32_16x16x32_bf16 v[134:137], v[186:189], v[170:173], v[134:137]
	ds_read_b128 v[186:189], v237 offset:24576
	v_add_f32_e32 v250, v109, v250
	v_cvt_pk_bf16_f32 v98, v98, v99
	s_waitcnt lgkmcnt(5)
	v_mfma_f32_16x16x32_bf16 v[138:141], v[190:193], v[154:157], v[138:141]
	v_cvt_pk_bf16_f32 v99, v100, v101
	ds_read_b64_tr_b16 v[206:207], v239 offset:0
	ds_read_b64_tr_b16 v[208:209], v239 offset:4096
	v_mfma_f32_16x16x32_bf16 v[142:145], v[190:193], v[170:173], v[142:145]
	ds_read_b128 v[190:193], v237 offset:28672
	v_cvt_pk_bf16_f32 v100, v106, v107
	v_cvt_pk_bf16_f32 v101, v108, v109
	s_waitcnt lgkmcnt(7)
	v_mfma_f32_16x16x32_bf16 v[114:117], v[178:181], v[158:161], v[114:117]
	v_add_f32_e32 v251, v102, v251
	s_add_u32 m0, s80, 50176
	s_nop 0
	global_load_lds_dwordx4 v249, s[100:101]
	ds_read_b64_tr_b16 v[210:211], v240 offset:0
	ds_read_b64_tr_b16 v[212:213], v240 offset:4096
	v_mfma_f32_16x16x32_bf16 v[118:121], v[178:181], v[174:177], v[118:121]
	v_add_f32_e32 v251, v103, v251
	v_add_f32_e32 v251, v104, v251
	s_waitcnt lgkmcnt(8)
	v_mfma_f32_16x16x32_bf16 v[122:125], v[182:185], v[158:161], v[122:125]
	v_add_f32_e32 v251, v105, v251
	ds_read_b64_tr_b16 v[214:215], v241 offset:0
	ds_read_b64_tr_b16 v[216:217], v241 offset:4096
	v_mfma_f32_16x16x32_bf16 v[126:129], v[182:185], v[174:177], v[126:129]
	v_add_f32_e32 v251, v110, v251
	v_add_f32_e32 v251, v111, v251
	s_waitcnt lgkmcnt(7)
	v_mfma_f32_16x16x32_bf16 v[130:133], v[186:189], v[158:161], v[130:133]
	v_add_f32_e32 v251, v112, v251
	ds_read_b64_tr_b16 v[218:219], v242 offset:0
	ds_read_b64_tr_b16 v[220:221], v242 offset:4096
	v_mfma_f32_16x16x32_bf16 v[134:137], v[186:189], v[174:177], v[134:137]
	v_add_f32_e32 v251, v113, v251
	v_cvt_pk_bf16_f32 v102, v102, v103
	s_waitcnt lgkmcnt(6)
	v_mfma_f32_16x16x32_bf16 v[138:141], v[190:193], v[158:161], v[138:141]
	v_cvt_pk_bf16_f32 v103, v104, v105
	ds_read_b64_tr_b16 v[222:223], v243 offset:0
	ds_read_b64_tr_b16 v[224:225], v243 offset:4096
	v_mfma_f32_16x16x32_bf16 v[142:145], v[190:193], v[174:177], v[142:145]
	v_cvt_pk_bf16_f32 v104, v110, v111
	v_cvt_pk_bf16_f32 v105, v112, v113
	v_mfma_f32_16x16x32_bf16 v[18:21], v[202:205], v[82:85], v[18:21]
	v_exp_f32_e32 v114, v114
	v_mfma_f32_16x16x32_bf16 v[22:25], v[202:205], v[86:89], v[22:25]
	ds_read_b64_tr_b16 v[202:203], v244 offset:0
	ds_read_b64_tr_b16 v[204:205], v244 offset:4096
	v_exp_f32_e32 v115, v115
	v_mfma_f32_16x16x32_bf16 v[26:29], v[206:209], v[82:85], v[26:29]
	v_exp_f32_e32 v116, v116
	v_mfma_f32_16x16x32_bf16 v[30:33], v[206:209], v[86:89], v[30:33]
	ds_read_b64_tr_b16 v[206:207], v245 offset:0
	ds_read_b64_tr_b16 v[208:209], v245 offset:4096
	v_exp_f32_e32 v117, v117
	s_waitcnt lgkmcnt(10)
	v_mfma_f32_16x16x32_bf16 v[34:37], v[210:213], v[82:85], v[34:37]
	v_exp_f32_e32 v118, v118
	v_mfma_f32_16x16x32_bf16 v[38:41], v[210:213], v[86:89], v[38:41]
	ds_read_b64_tr_b16 v[210:211], v238 offset:8192
	ds_read_b64_tr_b16 v[212:213], v238 offset:12288
	v_exp_f32_e32 v119, v119
	s_waitcnt lgkmcnt(10)
	v_mfma_f32_16x16x32_bf16 v[42:45], v[214:217], v[82:85], v[42:45]
	v_exp_f32_e32 v120, v120
	v_mfma_f32_16x16x32_bf16 v[46:49], v[214:217], v[86:89], v[46:49]
	ds_read_b64_tr_b16 v[214:215], v239 offset:8192
	ds_read_b64_tr_b16 v[216:217], v239 offset:12288
	v_exp_f32_e32 v121, v121
	s_waitcnt lgkmcnt(10)
	v_mfma_f32_16x16x32_bf16 v[50:53], v[218:221], v[82:85], v[50:53]
	v_exp_f32_e32 v122, v122
	v_mfma_f32_16x16x32_bf16 v[54:57], v[218:221], v[86:89], v[54:57]
	ds_read_b64_tr_b16 v[218:219], v240 offset:8192
	ds_read_b64_tr_b16 v[220:221], v240 offset:12288
	v_exp_f32_e32 v123, v123
	s_waitcnt lgkmcnt(10)
	v_mfma_f32_16x16x32_bf16 v[58:61], v[222:225], v[82:85], v[58:61]
	v_exp_f32_e32 v124, v124
	v_mfma_f32_16x16x32_bf16 v[62:65], v[222:225], v[86:89], v[62:65]
	ds_read_b64_tr_b16 v[222:223], v241 offset:8192
	ds_read_b64_tr_b16 v[224:225], v241 offset:12288
	v_exp_f32_e32 v125, v125
	s_waitcnt lgkmcnt(10)
	v_mfma_f32_16x16x32_bf16 v[66:69], v[202:205], v[82:85], v[66:69]
	v_exp_f32_e32 v126, v126
	v_mfma_f32_16x16x32_bf16 v[70:73], v[202:205], v[86:89], v[70:73]
	ds_read_b64_tr_b16 v[202:203], v242 offset:8192
	ds_read_b64_tr_b16 v[204:205], v242 offset:12288
	v_exp_f32_e32 v127, v127
	s_waitcnt lgkmcnt(10)
	v_mfma_f32_16x16x32_bf16 v[74:77], v[206:209], v[82:85], v[74:77]
	v_exp_f32_e32 v128, v128
	v_mfma_f32_16x16x32_bf16 v[78:81], v[206:209], v[86:89], v[78:81]
	ds_read_b64_tr_b16 v[206:207], v243 offset:8192
	ds_read_b64_tr_b16 v[208:209], v243 offset:12288
	v_exp_f32_e32 v129, v129
	s_waitcnt lgkmcnt(10)
	v_mfma_f32_16x16x32_bf16 v[18:21], v[210:213], v[98:101], v[18:21]
	v_exp_f32_e32 v130, v130
	v_mfma_f32_16x16x32_bf16 v[22:25], v[210:213], v[102:105], v[22:25]
	ds_read_b64_tr_b16 v[210:211], v244 offset:8192
	ds_read_b64_tr_b16 v[212:213], v244 offset:12288
	v_exp_f32_e32 v131, v131
	s_waitcnt lgkmcnt(10)
	v_mfma_f32_16x16x32_bf16 v[26:29], v[214:217], v[98:101], v[26:29]
	v_exp_f32_e32 v132, v132
	v_mfma_f32_16x16x32_bf16 v[30:33], v[214:217], v[102:105], v[30:33]
	ds_read_b64_tr_b16 v[214:215], v245 offset:8192
	ds_read_b64_tr_b16 v[216:217], v245 offset:12288
	v_exp_f32_e32 v133, v133
	s_waitcnt lgkmcnt(10)
; #define SBAR() __builtin_amdgcn_sched_barrier(0)
; __device__ __forceinline__ void qkt(f32x16& p0, f32x16& p1, const bf16* Ks, const bf16x8* qr, int r32, int hi, const f32x16& negm) {
; #pragma unroll
;   for (int d0 = 0; d0 < 8; ++d0) { int cb = (d0 * 16 + hi * 8) * 2;
;     bf16x8 b0 = *reinterpret_cast<const bf16x8*>((const char*)Ks + KSWZ(r32, cb));
;     bf16x8 b1 = *reinterpret_cast<const bf16x8*>((const char*)Ks + KSWZ(32 + r32, cb));
;     if (d0 == 0) { p0 = __builtin_amdgcn_mfma_f32_32x32x16_bf16(b0, qr[0], negm, 0, 0, 0); p1 = __builtin_amdgcn_mfma_f32_32x32x16_bf16(b1, qr[0], negm, 0, 0, 0); }
;     else { p0 = __builtin_amdgcn_mfma_f32_32x32x16_bf16(b0, qr[d0], p0, 0, 0, 0); p1 = __builtin_amdgcn_mfma_f32_32x32x16_bf16(b1, qr[d0], p1, 0, 0, 0); } }
; }
; __device__ __forceinline__ int v_st(int k, int c) { const int kk = (k & ~0xC) | ((k & 4) << 1) | ((k & 8) >> 1); return ((kk >> 3) * 4 + (c >> 5)) * 512 + ((kk & 7) * 32 + (c & 31)) * 2; }
; __device__ __forceinline__ int v_rd_base(int lane) { return ((lane & 3) << 3) | (((lane >> 2) & 3) << 6) | (((lane >> 4) & 1) << 5) | (((lane >> 5) & 1) << 8); }
; template <int OFF> __device__ __forceinline__ s16x4 tr_read(int vb) {
;   s16x4 r; asm volatile("ds_read_b64_tr_b16 %0, %1 offset:%2" : "=&v"(r) : "v"(vb), "i"(OFF) : "memory"); return r;
; }
; template <int D0> __device__ __forceinline__ void pv_one(f32x16& od, int vb, bf16x8 pa0, bf16x8 pa1, bf16x8 pa2, bf16x8 pa3) {
;   const s16x4 l0 = tr_read<v_rd_off(D0, 0, 0)>(vb), h0 = tr_read<v_rd_off(D0, 0, 1)>(vb), l1 = tr_read<v_rd_off(D0, 1, 0)>(vb), h1 = tr_read<v_rd_off(D0, 1, 1)>(vb);
;   const s16x4 l2 = tr_read<v_rd_off(D0, 2, 0)>(vb), h2 = tr_read<v_rd_off(D0, 2, 1)>(vb), l3 = tr_read<v_rd_off(D0, 3, 0)>(vb), h3 = tr_read<v_rd_off(D0, 3, 1)>(vb);
;   asm volatile("s_waitcnt lgkmcnt(0)" ::: "memory"); SBAR();
;     ...
;   od = __builtin_amdgcn_mfma_f32_32x32x16_bf16(pa0, PK(l0, h0), od, 0, 0, 0);
;   od = __builtin_amdgcn_mfma_f32_32x32x16_bf16(pa1, PK(l1, h1), od, 0, 0, 0);
;   od = __builtin_amdgcn_mfma_f32_32x32x16_bf16(pa2, PK(l2, h2), od, 0, 0, 0);
;   od = __builtin_amdgcn_mfma_f32_32x32x16_bf16(pa3, PK(l3, h3), od, 0, 0, 0);
;     ...
; }
; __device__ __forceinline__ void pv_d0(f32x16* o, int vb, bf16x8 pa0, bf16x8 pa1, bf16x8 pa2, bf16x8 pa3) {
	v_mfma_f32_16x16x32_bf16 v[34:37], v[218:221], v[98:101], v[34:37]
	v_exp_f32_e32 v134, v134
	v_mfma_f32_16x16x32_bf16 v[38:41], v[218:221], v[102:105], v[38:41]
	v_exp_f32_e32 v135, v135
	s_waitcnt lgkmcnt(8)
	v_mfma_f32_16x16x32_bf16 v[42:45], v[222:225], v[98:101], v[42:45]
	v_exp_f32_e32 v136, v136
	v_mfma_f32_16x16x32_bf16 v[46:49], v[222:225], v[102:105], v[46:49]
	v_exp_f32_e32 v137, v137
	s_waitcnt lgkmcnt(6)
	v_mfma_f32_16x16x32_bf16 v[50:53], v[202:205], v[98:101], v[50:53]
	v_exp_f32_e32 v138, v138
	ds_read_b128 v[178:181], v234 offset:32768
	v_mfma_f32_16x16x32_bf16 v[54:57], v[202:205], v[102:105], v[54:57]
	v_exp_f32_e32 v139, v139
	s_waitcnt lgkmcnt(5)
	v_mfma_f32_16x16x32_bf16 v[58:61], v[206:209], v[98:101], v[58:61]
	v_exp_f32_e32 v140, v140
	ds_read_b128 v[182:185], v234 offset:36864
	v_mfma_f32_16x16x32_bf16 v[62:65], v[206:209], v[102:105], v[62:65]
	v_exp_f32_e32 v141, v141
	s_waitcnt lgkmcnt(4)
	v_mfma_f32_16x16x32_bf16 v[66:69], v[210:213], v[98:101], v[66:69]
	v_exp_f32_e32 v142, v142
	ds_read_b128 v[186:189], v234 offset:40960
	v_mfma_f32_16x16x32_bf16 v[70:73], v[210:213], v[102:105], v[70:73]
	v_exp_f32_e32 v143, v143
	s_waitcnt lgkmcnt(3)
	v_mfma_f32_16x16x32_bf16 v[74:77], v[214:217], v[98:101], v[74:77]
	v_exp_f32_e32 v144, v144
	ds_read_b128 v[190:193], v234 offset:45056
	v_mfma_f32_16x16x32_bf16 v[78:81], v[214:217], v[102:105], v[78:81]
	v_exp_f32_e32 v145, v145
	s_waitcnt vmcnt(4)
	s_barrier
	s_waitcnt lgkmcnt(3)
	v_mfma_f32_16x16x32_bf16 v[82:85], v[178:181], v[146:149], v[2:5]
	v_add_f32_e32 v250, v114, v250
	s_add_u32 s98, s98, 0x8000
	s_addc_u32 s99, s99, 0
	s_add_u32 s100, s100, 0x8000
	s_addc_u32 s101, s101, 0
	s_add_u32 m0, s79, 16384
	s_nop 0
	global_load_lds_dwordx4 v246, s[98:99]
	v_mfma_f32_16x16x32_bf16 v[86:89], v[178:181], v[162:165], v[2:5]
	ds_read_b128 v[178:181], v235 offset:32768
	v_add_f32_e32 v250, v115, v250
	v_add_f32_e32 v250, v116, v250
	s_waitcnt lgkmcnt(3)
	v_mfma_f32_16x16x32_bf16 v[90:93], v[182:185], v[146:149], v[2:5]
	v_add_f32_e32 v250, v117, v250
	v_mfma_f32_16x16x32_bf16 v[94:97], v[182:185], v[162:165], v[2:5]
	ds_read_b128 v[182:185], v235 offset:36864
	v_add_f32_e32 v250, v122, v250
	v_add_f32_e32 v250, v123, v250
	s_waitcnt lgkmcnt(3)
	v_mfma_f32_16x16x32_bf16 v[98:101], v[186:189], v[146:149], v[2:5]
	v_add_f32_e32 v250, v124, v250
	v_mfma_f32_16x16x32_bf16 v[102:105], v[186:189], v[162:165], v[2:5]
	ds_read_b128 v[186:189], v235 offset:40960
	v_add_f32_e32 v250, v125, v250
	v_cvt_pk_bf16_f32 v114, v114, v115
	s_waitcnt lgkmcnt(3)
	v_mfma_f32_16x16x32_bf16 v[106:109], v[190:193], v[146:149], v[2:5]
	v_cvt_pk_bf16_f32 v115, v116, v117
	v_mfma_f32_16x16x32_bf16 v[110:113], v[190:193], v[162:165], v[2:5]
	ds_read_b128 v[190:193], v235 offset:45056
	v_cvt_pk_bf16_f32 v116, v122, v123
	v_cvt_pk_bf16_f32 v117, v124, v125
	s_waitcnt lgkmcnt(3)
	v_mfma_f32_16x16x32_bf16 v[82:85], v[178:181], v[150:153], v[82:85]
	v_add_f32_e32 v251, v118, v251
	s_add_u32 m0, s79, 17408
	s_nop 0
	global_load_lds_dwordx4 v247, s[98:99]
	v_mfma_f32_16x16x32_bf16 v[86:89], v[178:181], v[166:169], v[86:89]
	ds_read_b128 v[178:181], v236 offset:32768
	v_add_f32_e32 v251, v119, v251
	v_add_f32_e32 v251, v120, v251
	s_waitcnt lgkmcnt(3)
	v_mfma_f32_16x16x32_bf16 v[90:93], v[182:185], v[150:153], v[90:93]
	v_add_f32_e32 v251, v121, v251
	v_mfma_f32_16x16x32_bf16 v[94:97], v[182:185], v[166:169], v[94:97]
	ds_read_b128 v[182:185], v236 offset:36864
	v_add_f32_e32 v251, v126, v251
	v_add_f32_e32 v251, v127, v251
	s_waitcnt lgkmcnt(3)
	v_mfma_f32_16x16x32_bf16 v[98:101], v[186:189], v[150:153], v[98:101]
	v_add_f32_e32 v251, v128, v251
	v_mfma_f32_16x16x32_bf16 v[102:105], v[186:189], v[166:169], v[102:105]
	ds_read_b128 v[186:189], v236 offset:40960
	v_add_f32_e32 v251, v129, v251
	v_cvt_pk_bf16_f32 v118, v118, v119
	s_waitcnt lgkmcnt(3)
	v_mfma_f32_16x16x32_bf16 v[106:109], v[190:193], v[150:153], v[106:109]
	v_cvt_pk_bf16_f32 v119, v120, v121
	v_mfma_f32_16x16x32_bf16 v[110:113], v[190:193], v[166:169], v[110:113]
	ds_read_b128 v[190:193], v236 offset:45056
	v_cvt_pk_bf16_f32 v120, v126, v127
	v_cvt_pk_bf16_f32 v121, v128, v129
	s_waitcnt lgkmcnt(3)
	v_mfma_f32_16x16x32_bf16 v[82:85], v[178:181], v[154:157], v[82:85]
	v_add_f32_e32 v250, v130, v250
	s_add_u32 m0, s80, 0
	s_nop 0
	global_load_lds_dwordx4 v248, s[100:101]
	v_mfma_f32_16x16x32_bf16 v[86:89], v[178:181], v[170:173], v[86:89]
	ds_read_b128 v[178:181], v237 offset:32768
	v_add_f32_e32 v250, v131, v250
	v_add_f32_e32 v250, v132, v250
	s_waitcnt lgkmcnt(3)
	v_mfma_f32_16x16x32_bf16 v[90:93], v[182:185], v[154:157], v[90:93]
	v_add_f32_e32 v250, v133, v250
	v_mfma_f32_16x16x32_bf16 v[94:97], v[182:185], v[170:173], v[94:97]
	ds_read_b128 v[182:185], v237 offset:36864
	v_add_f32_e32 v250, v138, v250
	v_add_f32_e32 v250, v139, v250
	s_waitcnt lgkmcnt(3)
	v_mfma_f32_16x16x32_bf16 v[98:101], v[186:189], v[154:157], v[98:101]
	v_add_f32_e32 v250, v140, v250
	ds_read_b64_tr_b16 v[202:203], v238 offset:16384
	ds_read_b64_tr_b16 v[204:205], v238 offset:20480
	v_mfma_f32_16x16x32_bf16 v[102:105], v[186:189], v[170:173], v[102:105]
	ds_read_b128 v[186:189], v237 offset:40960
	v_add_f32_e32 v250, v141, v250
	v_cvt_pk_bf16_f32 v130, v130, v131
	s_waitcnt lgkmcnt(5)
	v_mfma_f32_16x16x32_bf16 v[106:109], v[190:193], v[154:157], v[106:109]
	v_cvt_pk_bf16_f32 v131, v132, v133
	ds_read_b64_tr_b16 v[206:207], v239 offset:16384
	ds_read_b64_tr_b16 v[208:209], v239 offset:20480
	v_mfma_f32_16x16x32_bf16 v[110:113], v[190:193], v[170:173], v[110:113]
	ds_read_b128 v[190:193], v237 offset:45056
	v_cvt_pk_bf16_f32 v132, v138, v139
	v_cvt_pk_bf16_f32 v133, v140, v141
	s_waitcnt lgkmcnt(7)
; __device__ __forceinline__ void partialSM(f32x16& p0, f32x16& p1, float mC) {
;     ...
;   for (int r = 0; r < 16; ++r) p0[r] = __builtin_amdgcn_exp2f(p0[r]);
; }
; __device__ __forceinline__ void finishSM(f32x16& p0, f32x16& p1, float& l_reg, bf16x8& pa0, bf16x8& pa1, bf16x8& pa2, bf16x8& pa3) {
;   for (int r = 0; r < 16; ++r) p1[r] = __builtin_amdgcn_exp2f(p1[r]);
;   float ps = 0; for (int r = 0; r < 16; ++r) ps += p0[r]; for (int r = 0; r < 16; ++r) ps += p1[r];
;   { auto rr = __builtin_amdgcn_permlane32_swap(__float_as_uint(ps), __float_as_uint(ps), false, false);
;     ps = __uint_as_float(rr[0]) + __uint_as_float(rr[1]); }
;   l_reg += ps;
;     ...
;   PK4(p0, 0, pa0); PK4(p0, 8, pa1); PK4(p1, 0, pa2); PK4(p1, 8, pa3);
;     ...
; }
; __device__ __forceinline__ void qkt(f32x16& p0, f32x16& p1, const bf16* Ks, const bf16x8* qr, int r32, int hi, const f32x16& negm) {
; #pragma unroll
;   for (int d0 = 0; d0 < 8; ++d0) { int cb = (d0 * 16 + hi * 8) * 2;
;     bf16x8 b0 = *reinterpret_cast<const bf16x8*>((const char*)Ks + KSWZ(r32, cb));
;     bf16x8 b1 = *reinterpret_cast<const bf16x8*>((const char*)Ks + KSWZ(32 + r32, cb));
;     if (d0 == 0) { p0 = __builtin_amdgcn_mfma_f32_32x32x16_bf16(b0, qr[0], negm, 0, 0, 0); p1 = __builtin_amdgcn_mfma_f32_32x32x16_bf16(b1, qr[0], negm, 0, 0, 0); }
;     else { p0 = __builtin_amdgcn_mfma_f32_32x32x16_bf16(b0, qr[d0], p0, 0, 0, 0); p1 = __builtin_amdgcn_mfma_f32_32x32x16_bf16(b1, qr[d0], p1, 0, 0, 0); } }
; }
; __device__ __forceinline__ int v_st(int k, int c) { const int kk = (k & ~0xC) | ((k & 4) << 1) | ((k & 8) >> 1); return ((kk >> 3) * 4 + (c >> 5)) * 512 + ((kk & 7) * 32 + (c & 31)) * 2; }
; __device__ __forceinline__ int v_rd_base(int lane) { return ((lane & 3) << 3) | (((lane >> 2) & 3) << 6) | (((lane >> 4) & 1) << 5) | (((lane >> 5) & 1) << 8); }
; template <int OFF> __device__ __forceinline__ s16x4 tr_read(int vb) {
;   s16x4 r; asm volatile("ds_read_b64_tr_b16 %0, %1 offset:%2" : "=&v"(r) : "v"(vb), "i"(OFF) : "memory"); return r;
; }
; template <int D0> __device__ __forceinline__ void pv_one(f32x16& od, int vb, bf16x8 pa0, bf16x8 pa1, bf16x8 pa2, bf16x8 pa3) {
;   const s16x4 l0 = tr_read<v_rd_off(D0, 0, 0)>(vb), h0 = tr_read<v_rd_off(D0, 0, 1)>(vb), l1 = tr_read<v_rd_off(D0, 1, 0)>(vb), h1 = tr_read<v_rd_off(D0, 1, 1)>(vb);
	v_mfma_f32_16x16x32_bf16 v[82:85], v[178:181], v[158:161], v[82:85]
	v_add_f32_e32 v251, v134, v251
	s_add_u32 m0, s80, 1024
	s_nop 0
	global_load_lds_dwordx4 v249, s[100:101]
	ds_read_b64_tr_b16 v[210:211], v240 offset:16384
	ds_read_b64_tr_b16 v[212:213], v240 offset:20480
	v_mfma_f32_16x16x32_bf16 v[86:89], v[178:181], v[174:177], v[86:89]
	v_add_f32_e32 v251, v135, v251
	v_add_f32_e32 v251, v136, v251
	s_waitcnt lgkmcnt(8)
	v_mfma_f32_16x16x32_bf16 v[90:93], v[182:185], v[158:161], v[90:93]
	v_add_f32_e32 v251, v137, v251
	ds_read_b64_tr_b16 v[214:215], v241 offset:16384
	ds_read_b64_tr_b16 v[216:217], v241 offset:20480
	v_mfma_f32_16x16x32_bf16 v[94:97], v[182:185], v[174:177], v[94:97]
	v_add_f32_e32 v251, v142, v251
	v_add_f32_e32 v251, v143, v251
	s_waitcnt lgkmcnt(7)
	v_mfma_f32_16x16x32_bf16 v[98:101], v[186:189], v[158:161], v[98:101]
	v_add_f32_e32 v251, v144, v251
	ds_read_b64_tr_b16 v[218:219], v242 offset:16384
	ds_read_b64_tr_b16 v[220:221], v242 offset:20480
	v_mfma_f32_16x16x32_bf16 v[102:105], v[186:189], v[174:177], v[102:105]
	v_add_f32_e32 v251, v145, v251
	v_cvt_pk_bf16_f32 v134, v134, v135
	s_waitcnt lgkmcnt(6)
	v_mfma_f32_16x16x32_bf16 v[106:109], v[190:193], v[158:161], v[106:109]
	v_cvt_pk_bf16_f32 v135, v136, v137
	ds_read_b64_tr_b16 v[222:223], v243 offset:16384
	ds_read_b64_tr_b16 v[224:225], v243 offset:20480
	v_mfma_f32_16x16x32_bf16 v[110:113], v[190:193], v[174:177], v[110:113]
	v_cvt_pk_bf16_f32 v136, v142, v143
	v_cvt_pk_bf16_f32 v137, v144, v145
	v_mfma_f32_16x16x32_bf16 v[18:21], v[202:205], v[114:117], v[18:21]
	v_exp_f32_e32 v82, v82
	v_mfma_f32_16x16x32_bf16 v[22:25], v[202:205], v[118:121], v[22:25]
	ds_read_b64_tr_b16 v[202:203], v244 offset:16384
	ds_read_b64_tr_b16 v[204:205], v244 offset:20480
	v_exp_f32_e32 v83, v83
	v_mfma_f32_16x16x32_bf16 v[26:29], v[206:209], v[114:117], v[26:29]
	v_exp_f32_e32 v84, v84
	v_mfma_f32_16x16x32_bf16 v[30:33], v[206:209], v[118:121], v[30:33]
	ds_read_b64_tr_b16 v[206:207], v245 offset:16384
	ds_read_b64_tr_b16 v[208:209], v245 offset:20480
	v_exp_f32_e32 v85, v85
	s_waitcnt lgkmcnt(10)
	v_mfma_f32_16x16x32_bf16 v[34:37], v[210:213], v[114:117], v[34:37]
	v_exp_f32_e32 v86, v86
	v_mfma_f32_16x16x32_bf16 v[38:41], v[210:213], v[118:121], v[38:41]
	ds_read_b64_tr_b16 v[210:211], v238 offset:24576
	ds_read_b64_tr_b16 v[212:213], v238 offset:28672
	v_exp_f32_e32 v87, v87
	s_waitcnt lgkmcnt(10)
	v_mfma_f32_16x16x32_bf16 v[42:45], v[214:217], v[114:117], v[42:45]
	v_exp_f32_e32 v88, v88
	v_mfma_f32_16x16x32_bf16 v[46:49], v[214:217], v[118:121], v[46:49]
	ds_read_b64_tr_b16 v[214:215], v239 offset:24576
	ds_read_b64_tr_b16 v[216:217], v239 offset:28672
	v_exp_f32_e32 v89, v89
	s_waitcnt lgkmcnt(10)
	v_mfma_f32_16x16x32_bf16 v[50:53], v[218:221], v[114:117], v[50:53]
	v_exp_f32_e32 v90, v90
	v_mfma_f32_16x16x32_bf16 v[54:57], v[218:221], v[118:121], v[54:57]
	ds_read_b64_tr_b16 v[218:219], v240 offset:24576
	ds_read_b64_tr_b16 v[220:221], v240 offset:28672
	v_exp_f32_e32 v91, v91
	s_waitcnt lgkmcnt(10)
	v_mfma_f32_16x16x32_bf16 v[58:61], v[222:225], v[114:117], v[58:61]
	v_exp_f32_e32 v92, v92
	v_mfma_f32_16x16x32_bf16 v[62:65], v[222:225], v[118:121], v[62:65]
	ds_read_b64_tr_b16 v[222:223], v241 offset:24576
	ds_read_b64_tr_b16 v[224:225], v241 offset:28672
	v_exp_f32_e32 v93, v93
	s_waitcnt lgkmcnt(10)
	v_mfma_f32_16x16x32_bf16 v[66:69], v[202:205], v[114:117], v[66:69]
	v_exp_f32_e32 v94, v94
	v_mfma_f32_16x16x32_bf16 v[70:73], v[202:205], v[118:121], v[70:73]
	ds_read_b64_tr_b16 v[202:203], v242 offset:24576
	ds_read_b64_tr_b16 v[204:205], v242 offset:28672
	v_exp_f32_e32 v95, v95
	s_waitcnt lgkmcnt(10)
	v_mfma_f32_16x16x32_bf16 v[74:77], v[206:209], v[114:117], v[74:77]
	v_exp_f32_e32 v96, v96
	v_mfma_f32_16x16x32_bf16 v[78:81], v[206:209], v[118:121], v[78:81]
	ds_read_b64_tr_b16 v[206:207], v243 offset:24576
	ds_read_b64_tr_b16 v[208:209], v243 offset:28672
	v_exp_f32_e32 v97, v97
	s_waitcnt lgkmcnt(10)
	v_mfma_f32_16x16x32_bf16 v[18:21], v[210:213], v[130:133], v[18:21]
	v_exp_f32_e32 v98, v98
	v_mfma_f32_16x16x32_bf16 v[22:25], v[210:213], v[134:137], v[22:25]
	ds_read_b64_tr_b16 v[210:211], v244 offset:24576
	ds_read_b64_tr_b16 v[212:213], v244 offset:28672
	v_exp_f32_e32 v99, v99
	s_waitcnt lgkmcnt(10)
	v_mfma_f32_16x16x32_bf16 v[26:29], v[214:217], v[130:133], v[26:29]
	v_exp_f32_e32 v100, v100
	v_mfma_f32_16x16x32_bf16 v[30:33], v[214:217], v[134:137], v[30:33]
	ds_read_b64_tr_b16 v[214:215], v245 offset:24576
	ds_read_b64_tr_b16 v[216:217], v245 offset:28672
	v_exp_f32_e32 v101, v101
	s_waitcnt lgkmcnt(10)
	v_mfma_f32_16x16x32_bf16 v[34:37], v[218:221], v[130:133], v[34:37]
	v_exp_f32_e32 v102, v102
	v_mfma_f32_16x16x32_bf16 v[38:41], v[218:221], v[134:137], v[38:41]
	v_exp_f32_e32 v103, v103
	s_waitcnt lgkmcnt(8)
	v_mfma_f32_16x16x32_bf16 v[42:45], v[222:225], v[130:133], v[42:45]
	v_exp_f32_e32 v104, v104
	v_mfma_f32_16x16x32_bf16 v[46:49], v[222:225], v[134:137], v[46:49]
	v_exp_f32_e32 v105, v105
	s_waitcnt lgkmcnt(6)
	v_mfma_f32_16x16x32_bf16 v[50:53], v[202:205], v[130:133], v[50:53]
	v_exp_f32_e32 v106, v106
	ds_read_b128 v[178:181], v234 offset:49152
	v_mfma_f32_16x16x32_bf16 v[54:57], v[202:205], v[134:137], v[54:57]
	v_exp_f32_e32 v107, v107
	s_waitcnt lgkmcnt(5)
	v_mfma_f32_16x16x32_bf16 v[58:61], v[206:209], v[130:133], v[58:61]
	v_exp_f32_e32 v108, v108
	ds_read_b128 v[182:185], v234 offset:53248
	v_mfma_f32_16x16x32_bf16 v[62:65], v[206:209], v[134:137], v[62:65]
	v_exp_f32_e32 v109, v109
	s_waitcnt lgkmcnt(4)
	v_mfma_f32_16x16x32_bf16 v[66:69], v[210:213], v[130:133], v[66:69]
	v_exp_f32_e32 v110, v110
	ds_read_b128 v[186:189], v234 offset:57344
	v_mfma_f32_16x16x32_bf16 v[70:73], v[210:213], v[134:137], v[70:73]
	v_exp_f32_e32 v111, v111
	s_waitcnt lgkmcnt(3)
	v_mfma_f32_16x16x32_bf16 v[74:77], v[214:217], v[130:133], v[74:77]
	v_exp_f32_e32 v112, v112
	ds_read_b128 v[190:193], v234 offset:61440
	v_mfma_f32_16x16x32_bf16 v[78:81], v[214:217], v[134:137], v[78:81]
	v_exp_f32_e32 v113, v113
	s_waitcnt vmcnt(4)
	s_barrier
; #define SBAR() __builtin_amdgcn_sched_barrier(0)
; #define SLOAD(i, k0) do { sr_[i].vs0 = St::ld8(&Vh[(long)((k0) + sr) * LDK + sc]); sr_[i].vs1 = St::ld8(&Vh[(long)((k0) + 32 + sr) * LDK + sc]); \
;     sr_[i].ks0 = St::ld8(&Kh[(long)((k0) + sr) * LDK + sc]); sr_[i].ks1 = St::ld8(&Kh[(long)((k0) + 32 + sr) * LDK + sc]); } while (0)
; #define SWAIT() do { if constexpr (SDEPTH == 2) asm volatile("s_waitcnt vmcnt(4)" ::: "memory"); else asm volatile("s_waitcnt vmcnt(0)" ::: "memory"); } while (0)
; __device__ __forceinline__ void finishSM(f32x16& p0, f32x16& p1, float& l_reg, bf16x8& pa0, bf16x8& pa1, bf16x8& pa2, bf16x8& pa3) {
;   for (int r = 0; r < 16; ++r) p1[r] = __builtin_amdgcn_exp2f(p1[r]);
;   float ps = 0; for (int r = 0; r < 16; ++r) ps += p0[r]; for (int r = 0; r < 16; ++r) ps += p1[r];
;   { auto rr = __builtin_amdgcn_permlane32_swap(__float_as_uint(ps), __float_as_uint(ps), false, false);
;     ps = __uint_as_float(rr[0]) + __uint_as_float(rr[1]); }
;   l_reg += ps;
;     ...
;   PK4(p0, 0, pa0); PK4(p0, 8, pa1); PK4(p1, 0, pa2); PK4(p1, 8, pa3);
;     ...
; }
; __device__ __forceinline__ void qkt(f32x16& p0, f32x16& p1, const bf16* Ks, const bf16x8* qr, int r32, int hi, const f32x16& negm) {
; #pragma unroll
;   for (int d0 = 0; d0 < 8; ++d0) { int cb = (d0 * 16 + hi * 8) * 2;
;     bf16x8 b0 = *reinterpret_cast<const bf16x8*>((const char*)Ks + KSWZ(r32, cb));
;     bf16x8 b1 = *reinterpret_cast<const bf16x8*>((const char*)Ks + KSWZ(32 + r32, cb));
;     if (d0 == 0) { p0 = __builtin_amdgcn_mfma_f32_32x32x16_bf16(b0, qr[0], negm, 0, 0, 0); p1 = __builtin_amdgcn_mfma_f32_32x32x16_bf16(b1, qr[0], negm, 0, 0, 0); }
;     else { p0 = __builtin_amdgcn_mfma_f32_32x32x16_bf16(b0, qr[d0], p0, 0, 0, 0); p1 = __builtin_amdgcn_mfma_f32_32x32x16_bf16(b1, qr[d0], p1, 0, 0, 0); } }
; }
; template <typename TQ> ...
;     ...
;   for (int j = 1; j + 1 < NT; j += 2) {
;     SBAR(); SLOAD(SO, (j + SDEPTH) * KVBLK); SBAR();
;     qkt(pB0, pB1, (bf16*)((char*)K_lds + SHM_K), qr, r32, hi, negm);
;     finishSM(pA0, pA1, l_reg, pa0, pa1, pa2, pa3); SBAR();
;     pv_d0(o, vb0, pa0, pa1, pa2, pa3); partialSM(pB0, pB1, mC);
;     __syncthreads(); SWAIT(); SWRITE(0, SE);
;     __syncthreads();
;     SBAR(); if (SDEPTH == 1 || j + 3 < NT) SLOAD(SE, (j + 1 + SDEPTH) * KVBLK); SBAR();
	s_waitcnt lgkmcnt(3)
	v_mfma_f32_16x16x32_bf16 v[114:117], v[178:181], v[146:149], v[2:5]
	v_add_f32_e32 v250, v82, v250
	s_add_u32 s98, s98, 0x8000
	s_addc_u32 s99, s99, 0
	s_add_u32 s100, s100, 0x8000
	s_addc_u32 s101, s101, 0
	s_add_u32 m0, s79, 32768
	s_nop 0
	global_load_lds_dwordx4 v246, s[98:99]
	v_mfma_f32_16x16x32_bf16 v[118:121], v[178:181], v[162:165], v[2:5]
	ds_read_b128 v[178:181], v235 offset:49152
	v_add_f32_e32 v250, v83, v250
	v_add_f32_e32 v250, v84, v250
	s_waitcnt lgkmcnt(3)
	v_mfma_f32_16x16x32_bf16 v[122:125], v[182:185], v[146:149], v[2:5]
	v_add_f32_e32 v250, v85, v250
	v_mfma_f32_16x16x32_bf16 v[126:129], v[182:185], v[162:165], v[2:5]
	ds_read_b128 v[182:185], v235 offset:53248
	v_add_f32_e32 v250, v90, v250
	v_add_f32_e32 v250, v91, v250
	s_waitcnt lgkmcnt(3)
	v_mfma_f32_16x16x32_bf16 v[130:133], v[186:189], v[146:149], v[2:5]
	v_add_f32_e32 v250, v92, v250
	v_mfma_f32_16x16x32_bf16 v[134:137], v[186:189], v[162:165], v[2:5]
	ds_read_b128 v[186:189], v235 offset:57344
	v_add_f32_e32 v250, v93, v250
	v_cvt_pk_bf16_f32 v82, v82, v83
	s_waitcnt lgkmcnt(3)
	v_mfma_f32_16x16x32_bf16 v[138:141], v[190:193], v[146:149], v[2:5]
	v_cvt_pk_bf16_f32 v83, v84, v85
	v_mfma_f32_16x16x32_bf16 v[142:145], v[190:193], v[162:165], v[2:5]
	ds_read_b128 v[190:193], v235 offset:61440
	v_cvt_pk_bf16_f32 v84, v90, v91
	v_cvt_pk_bf16_f32 v85, v92, v93
	s_waitcnt lgkmcnt(3)
	v_mfma_f32_16x16x32_bf16 v[114:117], v[178:181], v[150:153], v[114:117]
	v_add_f32_e32 v251, v86, v251
	s_add_u32 m0, s79, 33792
	s_nop 0
	global_load_lds_dwordx4 v247, s[98:99]
	v_mfma_f32_16x16x32_bf16 v[118:121], v[178:181], v[166:169], v[118:121]
	ds_read_b128 v[178:181], v236 offset:49152
	v_add_f32_e32 v251, v87, v251
	v_add_f32_e32 v251, v88, v251
	s_waitcnt lgkmcnt(3)
	v_mfma_f32_16x16x32_bf16 v[122:125], v[182:185], v[150:153], v[122:125]
	v_add_f32_e32 v251, v89, v251
	v_mfma_f32_16x16x32_bf16 v[126:129], v[182:185], v[166:169], v[126:129]
	ds_read_b128 v[182:185], v236 offset:53248
	v_add_f32_e32 v251, v94, v251
	v_add_f32_e32 v251, v95, v251
	s_waitcnt lgkmcnt(3)
	v_mfma_f32_16x16x32_bf16 v[130:133], v[186:189], v[150:153], v[130:133]
	v_add_f32_e32 v251, v96, v251
	v_mfma_f32_16x16x32_bf16 v[134:137], v[186:189], v[166:169], v[134:137]
	ds_read_b128 v[186:189], v236 offset:57344
	v_add_f32_e32 v251, v97, v251
	v_cvt_pk_bf16_f32 v86, v86, v87
	s_waitcnt lgkmcnt(3)
	v_mfma_f32_16x16x32_bf16 v[138:141], v[190:193], v[150:153], v[138:141]
	v_cvt_pk_bf16_f32 v87, v88, v89
	v_mfma_f32_16x16x32_bf16 v[142:145], v[190:193], v[166:169], v[142:145]
	ds_read_b128 v[190:193], v236 offset:61440
	v_cvt_pk_bf16_f32 v88, v94, v95
	v_cvt_pk_bf16_f32 v89, v96, v97
	s_waitcnt lgkmcnt(3)
	v_mfma_f32_16x16x32_bf16 v[114:117], v[178:181], v[154:157], v[114:117]
	v_add_f32_e32 v250, v98, v250
	s_add_u32 m0, s80, 16384
	s_nop 0
	global_load_lds_dwordx4 v248, s[100:101]
	v_mfma_f32_16x16x32_bf16 v[118:121], v[178:181], v[170:173], v[118:121]
	ds_read_b128 v[178:181], v237 offset:49152
	v_add_f32_e32 v250, v99, v250
	v_add_f32_e32 v250, v100, v250
	s_waitcnt lgkmcnt(3)
	v_mfma_f32_16x16x32_bf16 v[122:125], v[182:185], v[154:157], v[122:125]
	v_add_f32_e32 v250, v101, v250
	v_mfma_f32_16x16x32_bf16 v[126:129], v[182:185], v[170:173], v[126:129]
	ds_read_b128 v[182:185], v237 offset:53248
	v_add_f32_e32 v250, v106, v250
	v_add_f32_e32 v250, v107, v250
	s_waitcnt lgkmcnt(3)
	v_mfma_f32_16x16x32_bf16 v[130:133], v[186:189], v[154:157], v[130:133]
	v_add_f32_e32 v250, v108, v250
	ds_read_b64_tr_b16 v[202:203], v238 offset:32768
	ds_read_b64_tr_b16 v[204:205], v238 offset:36864
	v_mfma_f32_16x16x32_bf16 v[134:137], v[186:189], v[170:173], v[134:137]
	ds_read_b128 v[186:189], v237 offset:57344
	v_add_f32_e32 v250, v109, v250
	v_cvt_pk_bf16_f32 v98, v98, v99
	s_waitcnt lgkmcnt(5)
	v_mfma_f32_16x16x32_bf16 v[138:141], v[190:193], v[154:157], v[138:141]
	v_cvt_pk_bf16_f32 v99, v100, v101
	ds_read_b64_tr_b16 v[206:207], v239 offset:32768
	ds_read_b64_tr_b16 v[208:209], v239 offset:36864
	v_mfma_f32_16x16x32_bf16 v[142:145], v[190:193], v[170:173], v[142:145]
	ds_read_b128 v[190:193], v237 offset:61440
	v_cvt_pk_bf16_f32 v100, v106, v107
	v_cvt_pk_bf16_f32 v101, v108, v109
	s_waitcnt lgkmcnt(7)
	v_mfma_f32_16x16x32_bf16 v[114:117], v[178:181], v[158:161], v[114:117]
	v_add_f32_e32 v251, v102, v251
	s_add_u32 m0, s80, 17408
	s_nop 0
	global_load_lds_dwordx4 v249, s[100:101]
	ds_read_b64_tr_b16 v[210:211], v240 offset:32768
	ds_read_b64_tr_b16 v[212:213], v240 offset:36864
	v_mfma_f32_16x16x32_bf16 v[118:121], v[178:181], v[174:177], v[118:121]
	v_add_f32_e32 v251, v103, v251
	v_add_f32_e32 v251, v104, v251
	s_waitcnt lgkmcnt(8)
	v_mfma_f32_16x16x32_bf16 v[122:125], v[182:185], v[158:161], v[122:125]
	v_add_f32_e32 v251, v105, v251
	ds_read_b64_tr_b16 v[214:215], v241 offset:32768
	ds_read_b64_tr_b16 v[216:217], v241 offset:36864
	v_mfma_f32_16x16x32_bf16 v[126:129], v[182:185], v[174:177], v[126:129]
	v_add_f32_e32 v251, v110, v251
	v_add_f32_e32 v251, v111, v251
	s_waitcnt lgkmcnt(7)
	v_mfma_f32_16x16x32_bf16 v[130:133], v[186:189], v[158:161], v[130:133]
	v_add_f32_e32 v251, v112, v251
	ds_read_b64_tr_b16 v[218:219], v242 offset:32768
	ds_read_b64_tr_b16 v[220:221], v242 offset:36864
	v_mfma_f32_16x16x32_bf16 v[134:137], v[186:189], v[174:177], v[134:137]
	v_add_f32_e32 v251, v113, v251
	v_cvt_pk_bf16_f32 v102, v102, v103
	s_waitcnt lgkmcnt(6)
; __device__ __forceinline__ void partialSM(f32x16& p0, f32x16& p1, float mC) {
;   (void)mC; (void)p1;
;   for (int r = 0; r < 16; ++r) p0[r] = __builtin_amdgcn_exp2f(p0[r]);
; }
; __device__ __forceinline__ void finishSM(f32x16& p0, f32x16& p1, float& l_reg, bf16x8& pa0, bf16x8& pa1, bf16x8& pa2, bf16x8& pa3) {
;   for (int r = 0; r < 16; ++r) p1[r] = __builtin_amdgcn_exp2f(p1[r]);
;   float ps = 0; for (int r = 0; r < 16; ++r) ps += p0[r]; for (int r = 0; r < 16; ++r) ps += p1[r];
;   { auto rr = __builtin_amdgcn_permlane32_swap(__float_as_uint(ps), __float_as_uint(ps), false, false);
;     ps = __uint_as_float(rr[0]) + __uint_as_float(rr[1]); }
;   l_reg += ps;
;     ...
;   PK4(p0, 0, pa0); PK4(p0, 8, pa1); PK4(p1, 0, pa2); PK4(p1, 8, pa3);
;     ...
; }
; __device__ __forceinline__ void qkt(f32x16& p0, f32x16& p1, const bf16* Ks, const bf16x8* qr, int r32, int hi, const f32x16& negm) {
; #pragma unroll
;   for (int d0 = 0; d0 < 8; ++d0) { int cb = (d0 * 16 + hi * 8) * 2;
;     bf16x8 b0 = *reinterpret_cast<const bf16x8*>((const char*)Ks + KSWZ(r32, cb));
;     bf16x8 b1 = *reinterpret_cast<const bf16x8*>((const char*)Ks + KSWZ(32 + r32, cb));
;     if (d0 == 0) { p0 = __builtin_amdgcn_mfma_f32_32x32x16_bf16(b0, qr[0], negm, 0, 0, 0); p1 = __builtin_amdgcn_mfma_f32_32x32x16_bf16(b1, qr[0], negm, 0, 0, 0); }
;     else { p0 = __builtin_amdgcn_mfma_f32_32x32x16_bf16(b0, qr[d0], p0, 0, 0, 0); p1 = __builtin_amdgcn_mfma_f32_32x32x16_bf16(b1, qr[d0], p1, 0, 0, 0); } }
; }
; __device__ __forceinline__ int v_st(int k, int c) { const int kk = (k & ~0xC) | ((k & 4) << 1) | ((k & 8) >> 1); return ((kk >> 3) * 4 + (c >> 5)) * 512 + ((kk & 7) * 32 + (c & 31)) * 2; }
; __device__ __forceinline__ int v_rd_base(int lane) { return ((lane & 3) << 3) | (((lane >> 2) & 3) << 6) | (((lane >> 4) & 1) << 5) | (((lane >> 5) & 1) << 8); }
; template <int OFF> __device__ __forceinline__ s16x4 tr_read(int vb) {
;   s16x4 r; asm volatile("ds_read_b64_tr_b16 %0, %1 offset:%2" : "=&v"(r) : "v"(vb), "i"(OFF) : "memory"); return r;
; }
; template <int D0> __device__ __forceinline__ void pv_one(f32x16& od, int vb, bf16x8 pa0, bf16x8 pa1, bf16x8 pa2, bf16x8 pa3) {
;   const s16x4 l0 = tr_read<v_rd_off(D0, 0, 0)>(vb), h0 = tr_read<v_rd_off(D0, 0, 1)>(vb), l1 = tr_read<v_rd_off(D0, 1, 0)>(vb), h1 = tr_read<v_rd_off(D0, 1, 1)>(vb);
	v_mfma_f32_16x16x32_bf16 v[138:141], v[190:193], v[158:161], v[138:141]
	v_cvt_pk_bf16_f32 v103, v104, v105
	ds_read_b64_tr_b16 v[222:223], v243 offset:32768
	ds_read_b64_tr_b16 v[224:225], v243 offset:36864
	v_mfma_f32_16x16x32_bf16 v[142:145], v[190:193], v[174:177], v[142:145]
	v_cvt_pk_bf16_f32 v104, v110, v111
	v_cvt_pk_bf16_f32 v105, v112, v113
	v_mfma_f32_16x16x32_bf16 v[18:21], v[202:205], v[82:85], v[18:21]
	v_exp_f32_e32 v114, v114
	v_mfma_f32_16x16x32_bf16 v[22:25], v[202:205], v[86:89], v[22:25]
	ds_read_b64_tr_b16 v[202:203], v244 offset:32768
	ds_read_b64_tr_b16 v[204:205], v244 offset:36864
	v_exp_f32_e32 v115, v115
	v_mfma_f32_16x16x32_bf16 v[26:29], v[206:209], v[82:85], v[26:29]
	v_exp_f32_e32 v116, v116
	v_mfma_f32_16x16x32_bf16 v[30:33], v[206:209], v[86:89], v[30:33]
	ds_read_b64_tr_b16 v[206:207], v245 offset:32768
	ds_read_b64_tr_b16 v[208:209], v245 offset:36864
	v_exp_f32_e32 v117, v117
	s_waitcnt lgkmcnt(10)
	v_mfma_f32_16x16x32_bf16 v[34:37], v[210:213], v[82:85], v[34:37]
	v_exp_f32_e32 v118, v118
	v_mfma_f32_16x16x32_bf16 v[38:41], v[210:213], v[86:89], v[38:41]
	ds_read_b64_tr_b16 v[210:211], v238 offset:40960
	ds_read_b64_tr_b16 v[212:213], v238 offset:45056
	v_exp_f32_e32 v119, v119
	s_waitcnt lgkmcnt(10)
	v_mfma_f32_16x16x32_bf16 v[42:45], v[214:217], v[82:85], v[42:45]
	v_exp_f32_e32 v120, v120
	v_mfma_f32_16x16x32_bf16 v[46:49], v[214:217], v[86:89], v[46:49]
	ds_read_b64_tr_b16 v[214:215], v239 offset:40960
	ds_read_b64_tr_b16 v[216:217], v239 offset:45056
	v_exp_f32_e32 v121, v121
	s_waitcnt lgkmcnt(10)
	v_mfma_f32_16x16x32_bf16 v[50:53], v[218:221], v[82:85], v[50:53]
	v_exp_f32_e32 v122, v122
	v_mfma_f32_16x16x32_bf16 v[54:57], v[218:221], v[86:89], v[54:57]
	ds_read_b64_tr_b16 v[218:219], v240 offset:40960
	ds_read_b64_tr_b16 v[220:221], v240 offset:45056
	v_exp_f32_e32 v123, v123
	s_waitcnt lgkmcnt(10)
	v_mfma_f32_16x16x32_bf16 v[58:61], v[222:225], v[82:85], v[58:61]
	v_exp_f32_e32 v124, v124
	v_mfma_f32_16x16x32_bf16 v[62:65], v[222:225], v[86:89], v[62:65]
	ds_read_b64_tr_b16 v[222:223], v241 offset:40960
	ds_read_b64_tr_b16 v[224:225], v241 offset:45056
	v_exp_f32_e32 v125, v125
	s_waitcnt lgkmcnt(10)
	v_mfma_f32_16x16x32_bf16 v[66:69], v[202:205], v[82:85], v[66:69]
	v_exp_f32_e32 v126, v126
	v_mfma_f32_16x16x32_bf16 v[70:73], v[202:205], v[86:89], v[70:73]
	ds_read_b64_tr_b16 v[202:203], v242 offset:40960
	ds_read_b64_tr_b16 v[204:205], v242 offset:45056
	v_exp_f32_e32 v127, v127
	s_waitcnt lgkmcnt(10)
	v_mfma_f32_16x16x32_bf16 v[74:77], v[206:209], v[82:85], v[74:77]
	v_exp_f32_e32 v128, v128
	v_mfma_f32_16x16x32_bf16 v[78:81], v[206:209], v[86:89], v[78:81]
	ds_read_b64_tr_b16 v[206:207], v243 offset:40960
	ds_read_b64_tr_b16 v[208:209], v243 offset:45056
	v_exp_f32_e32 v129, v129
	s_waitcnt lgkmcnt(10)
	v_mfma_f32_16x16x32_bf16 v[18:21], v[210:213], v[98:101], v[18:21]
	v_exp_f32_e32 v130, v130
	v_mfma_f32_16x16x32_bf16 v[22:25], v[210:213], v[102:105], v[22:25]
	ds_read_b64_tr_b16 v[210:211], v244 offset:40960
	ds_read_b64_tr_b16 v[212:213], v244 offset:45056
	v_exp_f32_e32 v131, v131
	s_waitcnt lgkmcnt(10)
	v_mfma_f32_16x16x32_bf16 v[26:29], v[214:217], v[98:101], v[26:29]
	v_exp_f32_e32 v132, v132
	v_mfma_f32_16x16x32_bf16 v[30:33], v[214:217], v[102:105], v[30:33]
	ds_read_b64_tr_b16 v[214:215], v245 offset:40960
	ds_read_b64_tr_b16 v[216:217], v245 offset:45056
	v_exp_f32_e32 v133, v133
	s_waitcnt lgkmcnt(10)
	v_mfma_f32_16x16x32_bf16 v[34:37], v[218:221], v[98:101], v[34:37]
	v_exp_f32_e32 v134, v134
	v_mfma_f32_16x16x32_bf16 v[38:41], v[218:221], v[102:105], v[38:41]
	v_exp_f32_e32 v135, v135
	s_waitcnt lgkmcnt(8)
	v_mfma_f32_16x16x32_bf16 v[42:45], v[222:225], v[98:101], v[42:45]
	v_exp_f32_e32 v136, v136
	v_mfma_f32_16x16x32_bf16 v[46:49], v[222:225], v[102:105], v[46:49]
	v_exp_f32_e32 v137, v137
	s_waitcnt lgkmcnt(6)
	v_mfma_f32_16x16x32_bf16 v[50:53], v[202:205], v[98:101], v[50:53]
	v_exp_f32_e32 v138, v138
	ds_read_b128 v[178:181], v234 offset:0
	v_mfma_f32_16x16x32_bf16 v[54:57], v[202:205], v[102:105], v[54:57]
	v_exp_f32_e32 v139, v139
	s_waitcnt lgkmcnt(5)
	v_mfma_f32_16x16x32_bf16 v[58:61], v[206:209], v[98:101], v[58:61]
	v_exp_f32_e32 v140, v140
	ds_read_b128 v[182:185], v234 offset:4096
	v_mfma_f32_16x16x32_bf16 v[62:65], v[206:209], v[102:105], v[62:65]
	v_exp_f32_e32 v141, v141
	s_waitcnt lgkmcnt(4)
	v_mfma_f32_16x16x32_bf16 v[66:69], v[210:213], v[98:101], v[66:69]
	v_exp_f32_e32 v142, v142
	ds_read_b128 v[186:189], v234 offset:8192
	v_mfma_f32_16x16x32_bf16 v[70:73], v[210:213], v[102:105], v[70:73]
	v_exp_f32_e32 v143, v143
	s_waitcnt lgkmcnt(3)
	v_mfma_f32_16x16x32_bf16 v[74:77], v[214:217], v[98:101], v[74:77]
	v_exp_f32_e32 v144, v144
	ds_read_b128 v[190:193], v234 offset:12288
	v_mfma_f32_16x16x32_bf16 v[78:81], v[214:217], v[102:105], v[78:81]
	v_exp_f32_e32 v145, v145
	s_waitcnt vmcnt(4)
	s_barrier
; __device__ __forceinline__ void partialSM(f32x16& p0, f32x16& p1, float mC) {
;   (void)mC; (void)p1;
;   for (int r = 0; r < 16; ++r) p0[r] = __builtin_amdgcn_exp2f(p0[r]);
; }
; __device__ __forceinline__ void finishSM(f32x16& p0, f32x16& p1, float& l_reg, bf16x8& pa0, bf16x8& pa1, bf16x8& pa2, bf16x8& pa3) {
;   for (int r = 0; r < 16; ++r) p1[r] = __builtin_amdgcn_exp2f(p1[r]);
;   float ps = 0; for (int r = 0; r < 16; ++r) ps += p0[r]; for (int r = 0; r < 16; ++r) ps += p1[r];
;   { auto rr = __builtin_amdgcn_permlane32_swap(__float_as_uint(ps), __float_as_uint(ps), false, false);
;     ps = __uint_as_float(rr[0]) + __uint_as_float(rr[1]); }
;   l_reg += ps;
;     ...
;   PK4(p0, 0, pa0); PK4(p0, 8, pa1); PK4(p1, 0, pa2); PK4(p1, 8, pa3);
;     ...
; }
; __device__ __forceinline__ void qkt(f32x16& p0, f32x16& p1, const bf16* Ks, const bf16x8* qr, int r32, int hi, const f32x16& negm) {
; #pragma unroll
;   for (int d0 = 0; d0 < 8; ++d0) { int cb = (d0 * 16 + hi * 8) * 2;
;     bf16x8 b0 = *reinterpret_cast<const bf16x8*>((const char*)Ks + KSWZ(r32, cb));
;     bf16x8 b1 = *reinterpret_cast<const bf16x8*>((const char*)Ks + KSWZ(32 + r32, cb));
;     if (d0 == 0) { p0 = __builtin_amdgcn_mfma_f32_32x32x16_bf16(b0, qr[0], negm, 0, 0, 0); p1 = __builtin_amdgcn_mfma_f32_32x32x16_bf16(b1, qr[0], negm, 0, 0, 0); }
;     else { p0 = __builtin_amdgcn_mfma_f32_32x32x16_bf16(b0, qr[d0], p0, 0, 0, 0); p1 = __builtin_amdgcn_mfma_f32_32x32x16_bf16(b1, qr[d0], p1, 0, 0, 0); } }
; }
; __device__ __forceinline__ int v_st(int k, int c) { const int kk = (k & ~0xC) | ((k & 4) << 1) | ((k & 8) >> 1); return ((kk >> 3) * 4 + (c >> 5)) * 512 + ((kk & 7) * 32 + (c & 31)) * 2; }
; __device__ __forceinline__ int v_rd_base(int lane) { return ((lane & 3) << 3) | (((lane >> 2) & 3) << 6) | (((lane >> 4) & 1) << 5) | (((lane >> 5) & 1) << 8); }
; template <int OFF> __device__ __forceinline__ s16x4 tr_read(int vb) {
;   s16x4 r; asm volatile("ds_read_b64_tr_b16 %0, %1 offset:%2" : "=&v"(r) : "v"(vb), "i"(OFF) : "memory"); return r;
; }
; template <int D0> __device__ __forceinline__ void pv_one(f32x16& od, int vb, bf16x8 pa0, bf16x8 pa1, bf16x8 pa2, bf16x8 pa3) {
;   const s16x4 l0 = tr_read<v_rd_off(D0, 0, 0)>(vb), h0 = tr_read<v_rd_off(D0, 0, 1)>(vb), l1 = tr_read<v_rd_off(D0, 1, 0)>(vb), h1 = tr_read<v_rd_off(D0, 1, 1)>(vb);
	s_waitcnt lgkmcnt(3)
	v_mfma_f32_16x16x32_bf16 v[82:85], v[178:181], v[146:149], v[2:5]
	v_add_f32_e32 v250, v114, v250
	s_add_u32 s98, s98, 0x8000
	s_addc_u32 s99, s99, 0
	s_add_u32 s100, s100, 0x8000
	s_addc_u32 s101, s101, 0
	s_add_u32 m0, s79, 49152
	s_nop 0
	global_load_lds_dwordx4 v246, s[98:99]
	v_mfma_f32_16x16x32_bf16 v[86:89], v[178:181], v[162:165], v[2:5]
	ds_read_b128 v[178:181], v235 offset:0
	v_add_f32_e32 v250, v115, v250
	v_add_f32_e32 v250, v116, v250
	s_waitcnt lgkmcnt(3)
	v_mfma_f32_16x16x32_bf16 v[90:93], v[182:185], v[146:149], v[2:5]
	v_add_f32_e32 v250, v117, v250
	v_mfma_f32_16x16x32_bf16 v[94:97], v[182:185], v[162:165], v[2:5]
	ds_read_b128 v[182:185], v235 offset:4096
	v_add_f32_e32 v250, v122, v250
	v_add_f32_e32 v250, v123, v250
	s_waitcnt lgkmcnt(3)
	v_mfma_f32_16x16x32_bf16 v[98:101], v[186:189], v[146:149], v[2:5]
	v_add_f32_e32 v250, v124, v250
	v_mfma_f32_16x16x32_bf16 v[102:105], v[186:189], v[162:165], v[2:5]
	ds_read_b128 v[186:189], v235 offset:8192
	v_add_f32_e32 v250, v125, v250
	v_cvt_pk_bf16_f32 v114, v114, v115
	s_waitcnt lgkmcnt(3)
	v_mfma_f32_16x16x32_bf16 v[106:109], v[190:193], v[146:149], v[2:5]
	v_cvt_pk_bf16_f32 v115, v116, v117
	v_mfma_f32_16x16x32_bf16 v[110:113], v[190:193], v[162:165], v[2:5]
	ds_read_b128 v[190:193], v235 offset:12288
	v_cvt_pk_bf16_f32 v116, v122, v123
	v_cvt_pk_bf16_f32 v117, v124, v125
	s_waitcnt lgkmcnt(3)
	v_mfma_f32_16x16x32_bf16 v[82:85], v[178:181], v[150:153], v[82:85]
	v_add_f32_e32 v251, v118, v251
	s_add_u32 m0, s79, 50176
	s_nop 0
	global_load_lds_dwordx4 v247, s[98:99]
	v_mfma_f32_16x16x32_bf16 v[86:89], v[178:181], v[166:169], v[86:89]
	ds_read_b128 v[178:181], v236 offset:0
	v_add_f32_e32 v251, v119, v251
	v_add_f32_e32 v251, v120, v251
	s_waitcnt lgkmcnt(3)
	v_mfma_f32_16x16x32_bf16 v[90:93], v[182:185], v[150:153], v[90:93]
	v_add_f32_e32 v251, v121, v251
	v_mfma_f32_16x16x32_bf16 v[94:97], v[182:185], v[166:169], v[94:97]
	ds_read_b128 v[182:185], v236 offset:4096
	v_add_f32_e32 v251, v126, v251
	v_add_f32_e32 v251, v127, v251
	s_waitcnt lgkmcnt(3)
	v_mfma_f32_16x16x32_bf16 v[98:101], v[186:189], v[150:153], v[98:101]
	v_add_f32_e32 v251, v128, v251
	v_mfma_f32_16x16x32_bf16 v[102:105], v[186:189], v[166:169], v[102:105]
	ds_read_b128 v[186:189], v236 offset:8192
	v_add_f32_e32 v251, v129, v251
	v_cvt_pk_bf16_f32 v118, v118, v119
	s_waitcnt lgkmcnt(3)
	v_mfma_f32_16x16x32_bf16 v[106:109], v[190:193], v[150:153], v[106:109]
	v_cvt_pk_bf16_f32 v119, v120, v121
	v_mfma_f32_16x16x32_bf16 v[110:113], v[190:193], v[166:169], v[110:113]
	ds_read_b128 v[190:193], v236 offset:12288
	v_cvt_pk_bf16_f32 v120, v126, v127
	v_cvt_pk_bf16_f32 v121, v128, v129
	s_waitcnt lgkmcnt(3)
	v_mfma_f32_16x16x32_bf16 v[82:85], v[178:181], v[154:157], v[82:85]
	v_add_f32_e32 v250, v130, v250
	s_add_u32 m0, s80, 32768
	s_nop 0
	global_load_lds_dwordx4 v248, s[100:101]
	v_mfma_f32_16x16x32_bf16 v[86:89], v[178:181], v[170:173], v[86:89]
	ds_read_b128 v[178:181], v237 offset:0
	v_add_f32_e32 v250, v131, v250
	v_add_f32_e32 v250, v132, v250
	s_waitcnt lgkmcnt(3)
	v_mfma_f32_16x16x32_bf16 v[90:93], v[182:185], v[154:157], v[90:93]
	v_add_f32_e32 v250, v133, v250
	v_mfma_f32_16x16x32_bf16 v[94:97], v[182:185], v[170:173], v[94:97]
	ds_read_b128 v[182:185], v237 offset:4096
	v_add_f32_e32 v250, v138, v250
	v_add_f32_e32 v250, v139, v250
	s_waitcnt lgkmcnt(3)
	v_mfma_f32_16x16x32_bf16 v[98:101], v[186:189], v[154:157], v[98:101]
	v_add_f32_e32 v250, v140, v250
	ds_read_b64_tr_b16 v[202:203], v238 offset:49152
	ds_read_b64_tr_b16 v[204:205], v238 offset:53248
	v_mfma_f32_16x16x32_bf16 v[102:105], v[186:189], v[170:173], v[102:105]
	ds_read_b128 v[186:189], v237 offset:8192
	v_add_f32_e32 v250, v141, v250
	v_cvt_pk_bf16_f32 v130, v130, v131
	s_waitcnt lgkmcnt(5)
	v_mfma_f32_16x16x32_bf16 v[106:109], v[190:193], v[154:157], v[106:109]
	v_cvt_pk_bf16_f32 v131, v132, v133
	ds_read_b64_tr_b16 v[206:207], v239 offset:49152
	ds_read_b64_tr_b16 v[208:209], v239 offset:53248
	v_mfma_f32_16x16x32_bf16 v[110:113], v[190:193], v[170:173], v[110:113]
	ds_read_b128 v[190:193], v237 offset:12288
	v_cvt_pk_bf16_f32 v132, v138, v139
	v_cvt_pk_bf16_f32 v133, v140, v141
	s_waitcnt lgkmcnt(7)
	v_mfma_f32_16x16x32_bf16 v[82:85], v[178:181], v[158:161], v[82:85]
	v_add_f32_e32 v251, v134, v251
	s_add_u32 m0, s80, 33792
	s_nop 0
	global_load_lds_dwordx4 v249, s[100:101]
	ds_read_b64_tr_b16 v[210:211], v240 offset:49152
	ds_read_b64_tr_b16 v[212:213], v240 offset:53248
	v_mfma_f32_16x16x32_bf16 v[86:89], v[178:181], v[174:177], v[86:89]
	v_add_f32_e32 v251, v135, v251
	v_add_f32_e32 v251, v136, v251
	s_waitcnt lgkmcnt(8)
	v_mfma_f32_16x16x32_bf16 v[90:93], v[182:185], v[158:161], v[90:93]
	v_add_f32_e32 v251, v137, v251
	ds_read_b64_tr_b16 v[214:215], v241 offset:49152
	ds_read_b64_tr_b16 v[216:217], v241 offset:53248
	v_mfma_f32_16x16x32_bf16 v[94:97], v[182:185], v[174:177], v[94:97]
	v_add_f32_e32 v251, v142, v251
	v_add_f32_e32 v251, v143, v251
	s_waitcnt lgkmcnt(7)
	v_mfma_f32_16x16x32_bf16 v[98:101], v[186:189], v[158:161], v[98:101]
	v_add_f32_e32 v251, v144, v251
	ds_read_b64_tr_b16 v[218:219], v242 offset:49152
	ds_read_b64_tr_b16 v[220:221], v242 offset:53248
	v_mfma_f32_16x16x32_bf16 v[102:105], v[186:189], v[174:177], v[102:105]
	v_add_f32_e32 v251, v145, v251
	v_cvt_pk_bf16_f32 v134, v134, v135
	s_waitcnt lgkmcnt(6)
; __device__ __forceinline__ void partialSM(f32x16& p0, f32x16& p1, float mC) {
;   (void)mC; (void)p1;
;   for (int r = 0; r < 16; ++r) p0[r] = __builtin_amdgcn_exp2f(p0[r]);
; }
; __device__ __forceinline__ void finishSM(f32x16& p0, f32x16& p1, float& l_reg, bf16x8& pa0, bf16x8& pa1, bf16x8& pa2, bf16x8& pa3) {
;   for (int r = 0; r < 16; ++r) p1[r] = __builtin_amdgcn_exp2f(p1[r]);
;   float ps = 0; for (int r = 0; r < 16; ++r) ps += p0[r]; for (int r = 0; r < 16; ++r) ps += p1[r];
;   { auto rr = __builtin_amdgcn_permlane32_swap(__float_as_uint(ps), __float_as_uint(ps), false, false);
;     ps = __uint_as_float(rr[0]) + __uint_as_float(rr[1]); }
;   l_reg += ps;
;     ...
;   PK4(p0, 0, pa0); PK4(p0, 8, pa1); PK4(p1, 0, pa2); PK4(p1, 8, pa3);
;     ...
; }
; __device__ __forceinline__ void qkt(f32x16& p0, f32x16& p1, const bf16* Ks, const bf16x8* qr, int r32, int hi, const f32x16& negm) {
; #pragma unroll
;   for (int d0 = 0; d0 < 8; ++d0) { int cb = (d0 * 16 + hi * 8) * 2;
;     bf16x8 b0 = *reinterpret_cast<const bf16x8*>((const char*)Ks + KSWZ(r32, cb));
;     bf16x8 b1 = *reinterpret_cast<const bf16x8*>((const char*)Ks + KSWZ(32 + r32, cb));
;     if (d0 == 0) { p0 = __builtin_amdgcn_mfma_f32_32x32x16_bf16(b0, qr[0], negm, 0, 0, 0); p1 = __builtin_amdgcn_mfma_f32_32x32x16_bf16(b1, qr[0], negm, 0, 0, 0); }
;     else { p0 = __builtin_amdgcn_mfma_f32_32x32x16_bf16(b0, qr[d0], p0, 0, 0, 0); p1 = __builtin_amdgcn_mfma_f32_32x32x16_bf16(b1, qr[d0], p1, 0, 0, 0); } }
; }
; __device__ __forceinline__ int v_st(int k, int c) { const int kk = (k & ~0xC) | ((k & 4) << 1) | ((k & 8) >> 1); return ((kk >> 3) * 4 + (c >> 5)) * 512 + ((kk & 7) * 32 + (c & 31)) * 2; }
; __device__ __forceinline__ int v_rd_base(int lane) { return ((lane & 3) << 3) | (((lane >> 2) & 3) << 6) | (((lane >> 4) & 1) << 5) | (((lane >> 5) & 1) << 8); }
; template <int OFF> __device__ __forceinline__ s16x4 tr_read(int vb) {
;   s16x4 r; asm volatile("ds_read_b64_tr_b16 %0, %1 offset:%2" : "=&v"(r) : "v"(vb), "i"(OFF) : "memory"); return r;
; }
; template <int D0> __device__ __forceinline__ void pv_one(f32x16& od, int vb, bf16x8 pa0, bf16x8 pa1, bf16x8 pa2, bf16x8 pa3) {
;   const s16x4 l0 = tr_read<v_rd_off(D0, 0, 0)>(vb), h0 = tr_read<v_rd_off(D0, 0, 1)>(vb), l1 = tr_read<v_rd_off(D0, 1, 0)>(vb), h1 = tr_read<v_rd_off(D0, 1, 1)>(vb);
	v_mfma_f32_16x16x32_bf16 v[106:109], v[190:193], v[158:161], v[106:109]
	v_cvt_pk_bf16_f32 v135, v136, v137
	ds_read_b64_tr_b16 v[222:223], v243 offset:49152
	ds_read_b64_tr_b16 v[224:225], v243 offset:53248
	v_mfma_f32_16x16x32_bf16 v[110:113], v[190:193], v[174:177], v[110:113]
	v_cvt_pk_bf16_f32 v136, v142, v143
	v_cvt_pk_bf16_f32 v137, v144, v145
	v_mfma_f32_16x16x32_bf16 v[18:21], v[202:205], v[114:117], v[18:21]
	v_exp_f32_e32 v82, v82
	v_mfma_f32_16x16x32_bf16 v[22:25], v[202:205], v[118:121], v[22:25]
	ds_read_b64_tr_b16 v[202:203], v244 offset:49152
	ds_read_b64_tr_b16 v[204:205], v244 offset:53248
	v_exp_f32_e32 v83, v83
	v_mfma_f32_16x16x32_bf16 v[26:29], v[206:209], v[114:117], v[26:29]
	v_exp_f32_e32 v84, v84
	v_mfma_f32_16x16x32_bf16 v[30:33], v[206:209], v[118:121], v[30:33]
	ds_read_b64_tr_b16 v[206:207], v245 offset:49152
	ds_read_b64_tr_b16 v[208:209], v245 offset:53248
	v_exp_f32_e32 v85, v85
	s_waitcnt lgkmcnt(10)
	v_mfma_f32_16x16x32_bf16 v[34:37], v[210:213], v[114:117], v[34:37]
	v_exp_f32_e32 v86, v86
	v_mfma_f32_16x16x32_bf16 v[38:41], v[210:213], v[118:121], v[38:41]
	ds_read_b64_tr_b16 v[210:211], v238 offset:57344
	ds_read_b64_tr_b16 v[212:213], v238 offset:61440
	v_exp_f32_e32 v87, v87
	s_waitcnt lgkmcnt(10)
	v_mfma_f32_16x16x32_bf16 v[42:45], v[214:217], v[114:117], v[42:45]
	v_exp_f32_e32 v88, v88
	v_mfma_f32_16x16x32_bf16 v[46:49], v[214:217], v[118:121], v[46:49]
	ds_read_b64_tr_b16 v[214:215], v239 offset:57344
	ds_read_b64_tr_b16 v[216:217], v239 offset:61440
	v_exp_f32_e32 v89, v89
	s_waitcnt lgkmcnt(10)
	v_mfma_f32_16x16x32_bf16 v[50:53], v[218:221], v[114:117], v[50:53]
	v_exp_f32_e32 v90, v90
	v_mfma_f32_16x16x32_bf16 v[54:57], v[218:221], v[118:121], v[54:57]
	ds_read_b64_tr_b16 v[218:219], v240 offset:57344
	ds_read_b64_tr_b16 v[220:221], v240 offset:61440
	v_exp_f32_e32 v91, v91
	s_waitcnt lgkmcnt(10)
	v_mfma_f32_16x16x32_bf16 v[58:61], v[222:225], v[114:117], v[58:61]
	v_exp_f32_e32 v92, v92
	v_mfma_f32_16x16x32_bf16 v[62:65], v[222:225], v[118:121], v[62:65]
	ds_read_b64_tr_b16 v[222:223], v241 offset:57344
	ds_read_b64_tr_b16 v[224:225], v241 offset:61440
	v_exp_f32_e32 v93, v93
	s_waitcnt lgkmcnt(10)
	v_mfma_f32_16x16x32_bf16 v[66:69], v[202:205], v[114:117], v[66:69]
	v_exp_f32_e32 v94, v94
	v_mfma_f32_16x16x32_bf16 v[70:73], v[202:205], v[118:121], v[70:73]
	ds_read_b64_tr_b16 v[202:203], v242 offset:57344
	ds_read_b64_tr_b16 v[204:205], v242 offset:61440
	v_exp_f32_e32 v95, v95
	s_waitcnt lgkmcnt(10)
	v_mfma_f32_16x16x32_bf16 v[74:77], v[206:209], v[114:117], v[74:77]
	v_exp_f32_e32 v96, v96
	v_mfma_f32_16x16x32_bf16 v[78:81], v[206:209], v[118:121], v[78:81]
	ds_read_b64_tr_b16 v[206:207], v243 offset:57344
	ds_read_b64_tr_b16 v[208:209], v243 offset:61440
	v_exp_f32_e32 v97, v97
	s_waitcnt lgkmcnt(10)
	v_mfma_f32_16x16x32_bf16 v[18:21], v[210:213], v[130:133], v[18:21]
	v_exp_f32_e32 v98, v98
	v_mfma_f32_16x16x32_bf16 v[22:25], v[210:213], v[134:137], v[22:25]
	ds_read_b64_tr_b16 v[210:211], v244 offset:57344
	ds_read_b64_tr_b16 v[212:213], v244 offset:61440
	v_exp_f32_e32 v99, v99
	s_waitcnt lgkmcnt(10)
	v_mfma_f32_16x16x32_bf16 v[26:29], v[214:217], v[130:133], v[26:29]
	v_exp_f32_e32 v100, v100
	v_mfma_f32_16x16x32_bf16 v[30:33], v[214:217], v[134:137], v[30:33]
	ds_read_b64_tr_b16 v[214:215], v245 offset:57344
	ds_read_b64_tr_b16 v[216:217], v245 offset:61440
	v_exp_f32_e32 v101, v101
	s_waitcnt lgkmcnt(10)
	v_mfma_f32_16x16x32_bf16 v[34:37], v[218:221], v[130:133], v[34:37]
	v_exp_f32_e32 v102, v102
	v_mfma_f32_16x16x32_bf16 v[38:41], v[218:221], v[134:137], v[38:41]
	v_exp_f32_e32 v103, v103
	s_waitcnt lgkmcnt(8)
	v_mfma_f32_16x16x32_bf16 v[42:45], v[222:225], v[130:133], v[42:45]
	v_exp_f32_e32 v104, v104
	v_mfma_f32_16x16x32_bf16 v[46:49], v[222:225], v[134:137], v[46:49]
	v_exp_f32_e32 v105, v105
	s_waitcnt lgkmcnt(6)
	v_mfma_f32_16x16x32_bf16 v[50:53], v[202:205], v[130:133], v[50:53]
	v_exp_f32_e32 v106, v106
	ds_read_b128 v[178:181], v234 offset:16384
	v_mfma_f32_16x16x32_bf16 v[54:57], v[202:205], v[134:137], v[54:57]
	v_exp_f32_e32 v107, v107
	s_waitcnt lgkmcnt(5)
	v_mfma_f32_16x16x32_bf16 v[58:61], v[206:209], v[130:133], v[58:61]
	v_exp_f32_e32 v108, v108
	ds_read_b128 v[182:185], v234 offset:20480
	v_mfma_f32_16x16x32_bf16 v[62:65], v[206:209], v[134:137], v[62:65]
	v_exp_f32_e32 v109, v109
	s_waitcnt lgkmcnt(4)
	v_mfma_f32_16x16x32_bf16 v[66:69], v[210:213], v[130:133], v[66:69]
	v_exp_f32_e32 v110, v110
	ds_read_b128 v[186:189], v234 offset:24576
	v_mfma_f32_16x16x32_bf16 v[70:73], v[210:213], v[134:137], v[70:73]
	v_exp_f32_e32 v111, v111
	s_waitcnt lgkmcnt(3)
	v_mfma_f32_16x16x32_bf16 v[74:77], v[214:217], v[130:133], v[74:77]
	v_exp_f32_e32 v112, v112
	ds_read_b128 v[190:193], v234 offset:28672
	v_mfma_f32_16x16x32_bf16 v[78:81], v[214:217], v[134:137], v[78:81]
	v_exp_f32_e32 v113, v113
	s_waitcnt vmcnt(4)
	s_add_i32 s15, s15, 1
	s_cmp_lt_u32 s15, 32
	s_cbranch_scc1 .Lattn_loop_y
	s_barrier
; __device__ __forceinline__ void partialSM(f32x16& p0, f32x16& p1, float mC) {
;   (void)mC; (void)p1;
;   for (int r = 0; r < 16; ++r) p0[r] = __builtin_amdgcn_exp2f(p0[r]);
; }
; __device__ __forceinline__ void finishSM(f32x16& p0, f32x16& p1, float& l_reg, bf16x8& pa0, bf16x8& pa1, bf16x8& pa2, bf16x8& pa3) {
;   for (int r = 0; r < 16; ++r) p1[r] = __builtin_amdgcn_exp2f(p1[r]);
;   float ps = 0; for (int r = 0; r < 16; ++r) ps += p0[r]; for (int r = 0; r < 16; ++r) ps += p1[r];
;   { auto rr = __builtin_amdgcn_permlane32_swap(__float_as_uint(ps), __float_as_uint(ps), false, false);
;     ps = __uint_as_float(rr[0]) + __uint_as_float(rr[1]); }
;   l_reg += ps;
;     ...
;   PK4(p0, 0, pa0); PK4(p0, 8, pa1); PK4(p1, 0, pa2); PK4(p1, 8, pa3);
;     ...
; }
; __device__ __forceinline__ void qkt(f32x16& p0, f32x16& p1, const bf16* Ks, const bf16x8* qr, int r32, int hi, const f32x16& negm) {
; #pragma unroll
;   for (int d0 = 0; d0 < 8; ++d0) { int cb = (d0 * 16 + hi * 8) * 2;
;     bf16x8 b0 = *reinterpret_cast<const bf16x8*>((const char*)Ks + KSWZ(r32, cb));
;     bf16x8 b1 = *reinterpret_cast<const bf16x8*>((const char*)Ks + KSWZ(32 + r32, cb));
;     if (d0 == 0) { p0 = __builtin_amdgcn_mfma_f32_32x32x16_bf16(b0, qr[0], negm, 0, 0, 0); p1 = __builtin_amdgcn_mfma_f32_32x32x16_bf16(b1, qr[0], negm, 0, 0, 0); }
;     else { p0 = __builtin_amdgcn_mfma_f32_32x32x16_bf16(b0, qr[d0], p0, 0, 0, 0); p1 = __builtin_amdgcn_mfma_f32_32x32x16_bf16(b1, qr[d0], p1, 0, 0, 0); } }
; }
; __device__ __forceinline__ int v_st(int k, int c) { const int kk = (k & ~0xC) | ((k & 4) << 1) | ((k & 8) >> 1); return ((kk >> 3) * 4 + (c >> 5)) * 512 + ((kk & 7) * 32 + (c & 31)) * 2; }
; __device__ __forceinline__ int v_rd_base(int lane) { return ((lane & 3) << 3) | (((lane >> 2) & 3) << 6) | (((lane >> 4) & 1) << 5) | (((lane >> 5) & 1) << 8); }
; template <int OFF> __device__ __forceinline__ s16x4 tr_read(int vb) {
;   s16x4 r; asm volatile("ds_read_b64_tr_b16 %0, %1 offset:%2" : "=&v"(r) : "v"(vb), "i"(OFF) : "memory"); return r;
; }
; template <typename TQ> ...
;     ...
;   SBAR(); qkt(pB0, pB1, (bf16*)((char*)K_lds + SHM_K), qr, r32, hi, negm);
;   finishSM(pA0, pA1, l_reg, pa0, pa1, pa2, pa3); SBAR();
;   pv_d0(o, vb0, pa0, pa1, pa2, pa3); partialSM(pB0, pB1, mC);
;   __syncthreads();
;   finishSM(pB0, pB1, l_reg, pa0, pa1, pa2, pa3); SBAR();
;   pv_d0(o, vb0 + (int)SHM_V, pa0, pa1, pa2, pa3);
	s_waitcnt lgkmcnt(3)
	v_mfma_f32_16x16x32_bf16 v[114:117], v[178:181], v[146:149], v[2:5]
	v_add_f32_e32 v250, v82, v250
	s_add_u32 s98, s98, 0x8000
	s_addc_u32 s99, s99, 0
	s_add_u32 s100, s100, 0x8000
	s_addc_u32 s101, s101, 0
	s_add_u32 m0, s80, 49152
	s_nop 0
	global_load_lds_dwordx4 v248, s[100:101]
	v_mfma_f32_16x16x32_bf16 v[118:121], v[178:181], v[162:165], v[2:5]
	ds_read_b128 v[178:181], v235 offset:16384
	v_add_f32_e32 v250, v83, v250
	v_add_f32_e32 v250, v84, v250
	s_waitcnt lgkmcnt(3)
	v_mfma_f32_16x16x32_bf16 v[122:125], v[182:185], v[146:149], v[2:5]
	v_add_f32_e32 v250, v85, v250
	v_mfma_f32_16x16x32_bf16 v[126:129], v[182:185], v[162:165], v[2:5]
	ds_read_b128 v[182:185], v235 offset:20480
	v_add_f32_e32 v250, v90, v250
	v_add_f32_e32 v250, v91, v250
	s_waitcnt lgkmcnt(3)
	v_mfma_f32_16x16x32_bf16 v[130:133], v[186:189], v[146:149], v[2:5]
	v_add_f32_e32 v250, v92, v250
	v_mfma_f32_16x16x32_bf16 v[134:137], v[186:189], v[162:165], v[2:5]
	ds_read_b128 v[186:189], v235 offset:24576
	v_add_f32_e32 v250, v93, v250
	v_cvt_pk_bf16_f32 v82, v82, v83
	s_waitcnt lgkmcnt(3)
	v_mfma_f32_16x16x32_bf16 v[138:141], v[190:193], v[146:149], v[2:5]
	v_cvt_pk_bf16_f32 v83, v84, v85
	v_mfma_f32_16x16x32_bf16 v[142:145], v[190:193], v[162:165], v[2:5]
	ds_read_b128 v[190:193], v235 offset:28672
	v_cvt_pk_bf16_f32 v84, v90, v91
	v_cvt_pk_bf16_f32 v85, v92, v93
	s_waitcnt lgkmcnt(3)
	v_mfma_f32_16x16x32_bf16 v[114:117], v[178:181], v[150:153], v[114:117]
	v_add_f32_e32 v251, v86, v251
	s_add_u32 m0, s80, 50176
	s_nop 0
	global_load_lds_dwordx4 v249, s[100:101]
	v_mfma_f32_16x16x32_bf16 v[118:121], v[178:181], v[166:169], v[118:121]
	ds_read_b128 v[178:181], v236 offset:16384
	v_add_f32_e32 v251, v87, v251
	v_add_f32_e32 v251, v88, v251
	s_waitcnt lgkmcnt(3)
	v_mfma_f32_16x16x32_bf16 v[122:125], v[182:185], v[150:153], v[122:125]
	v_add_f32_e32 v251, v89, v251
	v_mfma_f32_16x16x32_bf16 v[126:129], v[182:185], v[166:169], v[126:129]
	ds_read_b128 v[182:185], v236 offset:20480
	v_add_f32_e32 v251, v94, v251
	v_add_f32_e32 v251, v95, v251
	s_waitcnt lgkmcnt(3)
	v_mfma_f32_16x16x32_bf16 v[130:133], v[186:189], v[150:153], v[130:133]
	v_add_f32_e32 v251, v96, v251
	v_mfma_f32_16x16x32_bf16 v[134:137], v[186:189], v[166:169], v[134:137]
	ds_read_b128 v[186:189], v236 offset:24576
	v_add_f32_e32 v251, v97, v251
	v_cvt_pk_bf16_f32 v86, v86, v87
	s_waitcnt lgkmcnt(3)
	v_mfma_f32_16x16x32_bf16 v[138:141], v[190:193], v[150:153], v[138:141]
	v_cvt_pk_bf16_f32 v87, v88, v89
	v_mfma_f32_16x16x32_bf16 v[142:145], v[190:193], v[166:169], v[142:145]
	ds_read_b128 v[190:193], v236 offset:28672
	v_cvt_pk_bf16_f32 v88, v94, v95
	v_cvt_pk_bf16_f32 v89, v96, v97
	s_waitcnt lgkmcnt(3)
	v_mfma_f32_16x16x32_bf16 v[114:117], v[178:181], v[154:157], v[114:117]
	v_add_f32_e32 v250, v98, v250
	v_mfma_f32_16x16x32_bf16 v[118:121], v[178:181], v[170:173], v[118:121]
	ds_read_b128 v[178:181], v237 offset:16384
	v_add_f32_e32 v250, v99, v250
	v_add_f32_e32 v250, v100, v250
	s_waitcnt lgkmcnt(3)
	v_mfma_f32_16x16x32_bf16 v[122:125], v[182:185], v[154:157], v[122:125]
	v_add_f32_e32 v250, v101, v250
	v_mfma_f32_16x16x32_bf16 v[126:129], v[182:185], v[170:173], v[126:129]
	ds_read_b128 v[182:185], v237 offset:20480
	v_add_f32_e32 v250, v106, v250
	v_add_f32_e32 v250, v107, v250
	s_waitcnt lgkmcnt(3)
	v_mfma_f32_16x16x32_bf16 v[130:133], v[186:189], v[154:157], v[130:133]
	v_add_f32_e32 v250, v108, v250
	ds_read_b64_tr_b16 v[202:203], v238 offset:0
	ds_read_b64_tr_b16 v[204:205], v238 offset:4096
	v_mfma_f32_16x16x32_bf16 v[134:137], v[186:189], v[170:173], v[134:137]
	ds_read_b128 v[186:189], v237 offset:24576
	v_add_f32_e32 v250, v109, v250
	v_cvt_pk_bf16_f32 v98, v98, v99
	s_waitcnt lgkmcnt(5)
	v_mfma_f32_16x16x32_bf16 v[138:141], v[190:193], v[154:157], v[138:141]
	v_cvt_pk_bf16_f32 v99, v100, v101
	ds_read_b64_tr_b16 v[206:207], v239 offset:0
	ds_read_b64_tr_b16 v[208:209], v239 offset:4096
	v_mfma_f32_16x16x32_bf16 v[142:145], v[190:193], v[170:173], v[142:145]
	ds_read_b128 v[190:193], v237 offset:28672
	v_cvt_pk_bf16_f32 v100, v106, v107
	v_cvt_pk_bf16_f32 v101, v108, v109
	s_waitcnt lgkmcnt(7)
	v_mfma_f32_16x16x32_bf16 v[114:117], v[178:181], v[158:161], v[114:117]
	v_add_f32_e32 v251, v102, v251
	ds_read_b64_tr_b16 v[210:211], v240 offset:0
	ds_read_b64_tr_b16 v[212:213], v240 offset:4096
	v_mfma_f32_16x16x32_bf16 v[118:121], v[178:181], v[174:177], v[118:121]
	v_add_f32_e32 v251, v103, v251
	v_add_f32_e32 v251, v104, v251
	s_waitcnt lgkmcnt(8)
	v_mfma_f32_16x16x32_bf16 v[122:125], v[182:185], v[158:161], v[122:125]
	v_add_f32_e32 v251, v105, v251
	ds_read_b64_tr_b16 v[214:215], v241 offset:0
	ds_read_b64_tr_b16 v[216:217], v241 offset:4096
	v_mfma_f32_16x16x32_bf16 v[126:129], v[182:185], v[174:177], v[126:129]
	v_add_f32_e32 v251, v110, v251
	v_add_f32_e32 v251, v111, v251
	s_waitcnt lgkmcnt(7)
	v_mfma_f32_16x16x32_bf16 v[130:133], v[186:189], v[158:161], v[130:133]
	v_add_f32_e32 v251, v112, v251
	ds_read_b64_tr_b16 v[218:219], v242 offset:0
	ds_read_b64_tr_b16 v[220:221], v242 offset:4096
	v_mfma_f32_16x16x32_bf16 v[134:137], v[186:189], v[174:177], v[134:137]
	v_add_f32_e32 v251, v113, v251
	v_cvt_pk_bf16_f32 v102, v102, v103
	s_waitcnt lgkmcnt(6)
; __device__ __forceinline__ void partialSM(f32x16& p0, f32x16& p1, float mC) {
;   (void)mC; (void)p1;
;   for (int r = 0; r < 16; ++r) p0[r] = __builtin_amdgcn_exp2f(p0[r]);
; }
; __device__ __forceinline__ void finishSM(f32x16& p0, f32x16& p1, float& l_reg, bf16x8& pa0, bf16x8& pa1, bf16x8& pa2, bf16x8& pa3) {
;   for (int r = 0; r < 16; ++r) p1[r] = __builtin_amdgcn_exp2f(p1[r]);
;   float ps = 0; for (int r = 0; r < 16; ++r) ps += p0[r]; for (int r = 0; r < 16; ++r) ps += p1[r];
;   { auto rr = __builtin_amdgcn_permlane32_swap(__float_as_uint(ps), __float_as_uint(ps), false, false);
;     ps = __uint_as_float(rr[0]) + __uint_as_float(rr[1]); }
;   l_reg += ps;
;     ...
;   PK4(p0, 0, pa0); PK4(p0, 8, pa1); PK4(p1, 0, pa2); PK4(p1, 8, pa3);
;     ...
; }
; __device__ __forceinline__ void qkt(f32x16& p0, f32x16& p1, const bf16* Ks, const bf16x8* qr, int r32, int hi, const f32x16& negm) {
; #pragma unroll
;   for (int d0 = 0; d0 < 8; ++d0) { int cb = (d0 * 16 + hi * 8) * 2;
;     bf16x8 b0 = *reinterpret_cast<const bf16x8*>((const char*)Ks + KSWZ(r32, cb));
;     bf16x8 b1 = *reinterpret_cast<const bf16x8*>((const char*)Ks + KSWZ(32 + r32, cb));
;     if (d0 == 0) { p0 = __builtin_amdgcn_mfma_f32_32x32x16_bf16(b0, qr[0], negm, 0, 0, 0); p1 = __builtin_amdgcn_mfma_f32_32x32x16_bf16(b1, qr[0], negm, 0, 0, 0); }
;     else { p0 = __builtin_amdgcn_mfma_f32_32x32x16_bf16(b0, qr[d0], p0, 0, 0, 0); p1 = __builtin_amdgcn_mfma_f32_32x32x16_bf16(b1, qr[d0], p1, 0, 0, 0); } }
; }
; __device__ __forceinline__ int v_st(int k, int c) { const int kk = (k & ~0xC) | ((k & 4) << 1) | ((k & 8) >> 1); return ((kk >> 3) * 4 + (c >> 5)) * 512 + ((kk & 7) * 32 + (c & 31)) * 2; }
; __device__ __forceinline__ int v_rd_base(int lane) { return ((lane & 3) << 3) | (((lane >> 2) & 3) << 6) | (((lane >> 4) & 1) << 5) | (((lane >> 5) & 1) << 8); }
; template <int OFF> __device__ __forceinline__ s16x4 tr_read(int vb) {
;   s16x4 r; asm volatile("ds_read_b64_tr_b16 %0, %1 offset:%2" : "=&v"(r) : "v"(vb), "i"(OFF) : "memory"); return r;
; }
; template <typename TQ> ...
;     ...
;   SBAR(); qkt(pB0, pB1, (bf16*)((char*)K_lds + SHM_K), qr, r32, hi, negm);
;   finishSM(pA0, pA1, l_reg, pa0, pa1, pa2, pa3); SBAR();
;   pv_d0(o, vb0, pa0, pa1, pa2, pa3); partialSM(pB0, pB1, mC);
;   __syncthreads();
;   finishSM(pB0, pB1, l_reg, pa0, pa1, pa2, pa3); SBAR();
;   pv_d0(o, vb0 + (int)SHM_V, pa0, pa1, pa2, pa3);
	v_mfma_f32_16x16x32_bf16 v[138:141], v[190:193], v[158:161], v[138:141]
	v_cvt_pk_bf16_f32 v103, v104, v105
	ds_read_b64_tr_b16 v[222:223], v243 offset:0
	ds_read_b64_tr_b16 v[224:225], v243 offset:4096
	v_mfma_f32_16x16x32_bf16 v[142:145], v[190:193], v[174:177], v[142:145]
	v_cvt_pk_bf16_f32 v104, v110, v111
	v_cvt_pk_bf16_f32 v105, v112, v113
	v_mfma_f32_16x16x32_bf16 v[18:21], v[202:205], v[82:85], v[18:21]
	v_exp_f32_e32 v114, v114
	v_mfma_f32_16x16x32_bf16 v[22:25], v[202:205], v[86:89], v[22:25]
	ds_read_b64_tr_b16 v[202:203], v244 offset:0
	ds_read_b64_tr_b16 v[204:205], v244 offset:4096
	v_exp_f32_e32 v115, v115
	v_mfma_f32_16x16x32_bf16 v[26:29], v[206:209], v[82:85], v[26:29]
	v_exp_f32_e32 v116, v116
	v_mfma_f32_16x16x32_bf16 v[30:33], v[206:209], v[86:89], v[30:33]
	ds_read_b64_tr_b16 v[206:207], v245 offset:0
	ds_read_b64_tr_b16 v[208:209], v245 offset:4096
	v_exp_f32_e32 v117, v117
	s_waitcnt lgkmcnt(10)
	v_mfma_f32_16x16x32_bf16 v[34:37], v[210:213], v[82:85], v[34:37]
	v_exp_f32_e32 v118, v118
	v_mfma_f32_16x16x32_bf16 v[38:41], v[210:213], v[86:89], v[38:41]
	ds_read_b64_tr_b16 v[210:211], v238 offset:8192
	ds_read_b64_tr_b16 v[212:213], v238 offset:12288
	v_exp_f32_e32 v119, v119
	s_waitcnt lgkmcnt(10)
	v_mfma_f32_16x16x32_bf16 v[42:45], v[214:217], v[82:85], v[42:45]
	v_exp_f32_e32 v120, v120
	v_mfma_f32_16x16x32_bf16 v[46:49], v[214:217], v[86:89], v[46:49]
	ds_read_b64_tr_b16 v[214:215], v239 offset:8192
	ds_read_b64_tr_b16 v[216:217], v239 offset:12288
	v_exp_f32_e32 v121, v121
	s_waitcnt lgkmcnt(10)
	v_mfma_f32_16x16x32_bf16 v[50:53], v[218:221], v[82:85], v[50:53]
	v_exp_f32_e32 v122, v122
	v_mfma_f32_16x16x32_bf16 v[54:57], v[218:221], v[86:89], v[54:57]
	ds_read_b64_tr_b16 v[218:219], v240 offset:8192
	ds_read_b64_tr_b16 v[220:221], v240 offset:12288
	v_exp_f32_e32 v123, v123
	s_waitcnt lgkmcnt(10)
	v_mfma_f32_16x16x32_bf16 v[58:61], v[222:225], v[82:85], v[58:61]
	v_exp_f32_e32 v124, v124
	v_mfma_f32_16x16x32_bf16 v[62:65], v[222:225], v[86:89], v[62:65]
	ds_read_b64_tr_b16 v[222:223], v241 offset:8192
	ds_read_b64_tr_b16 v[224:225], v241 offset:12288
	v_exp_f32_e32 v125, v125
	s_waitcnt lgkmcnt(10)
	v_mfma_f32_16x16x32_bf16 v[66:69], v[202:205], v[82:85], v[66:69]
	v_exp_f32_e32 v126, v126
	v_mfma_f32_16x16x32_bf16 v[70:73], v[202:205], v[86:89], v[70:73]
	ds_read_b64_tr_b16 v[202:203], v242 offset:8192
	ds_read_b64_tr_b16 v[204:205], v242 offset:12288
	v_exp_f32_e32 v127, v127
	s_waitcnt lgkmcnt(10)
	v_mfma_f32_16x16x32_bf16 v[74:77], v[206:209], v[82:85], v[74:77]
	v_exp_f32_e32 v128, v128
	v_mfma_f32_16x16x32_bf16 v[78:81], v[206:209], v[86:89], v[78:81]
	ds_read_b64_tr_b16 v[206:207], v243 offset:8192
	ds_read_b64_tr_b16 v[208:209], v243 offset:12288
	v_exp_f32_e32 v129, v129
	s_waitcnt lgkmcnt(10)
	v_mfma_f32_16x16x32_bf16 v[18:21], v[210:213], v[98:101], v[18:21]
	v_exp_f32_e32 v130, v130
	v_mfma_f32_16x16x32_bf16 v[22:25], v[210:213], v[102:105], v[22:25]
	ds_read_b64_tr_b16 v[210:211], v244 offset:8192
	ds_read_b64_tr_b16 v[212:213], v244 offset:12288
	v_exp_f32_e32 v131, v131
	s_waitcnt lgkmcnt(10)
	v_mfma_f32_16x16x32_bf16 v[26:29], v[214:217], v[98:101], v[26:29]
	v_exp_f32_e32 v132, v132
	v_mfma_f32_16x16x32_bf16 v[30:33], v[214:217], v[102:105], v[30:33]
	ds_read_b64_tr_b16 v[214:215], v245 offset:8192
	ds_read_b64_tr_b16 v[216:217], v245 offset:12288
	v_exp_f32_e32 v133, v133
	s_waitcnt lgkmcnt(10)
	v_mfma_f32_16x16x32_bf16 v[34:37], v[218:221], v[98:101], v[34:37]
	v_exp_f32_e32 v134, v134
	v_mfma_f32_16x16x32_bf16 v[38:41], v[218:221], v[102:105], v[38:41]
	v_exp_f32_e32 v135, v135
	s_waitcnt lgkmcnt(8)
	v_mfma_f32_16x16x32_bf16 v[42:45], v[222:225], v[98:101], v[42:45]
	v_exp_f32_e32 v136, v136
	v_mfma_f32_16x16x32_bf16 v[46:49], v[222:225], v[102:105], v[46:49]
	v_exp_f32_e32 v137, v137
	s_waitcnt lgkmcnt(6)
	v_mfma_f32_16x16x32_bf16 v[50:53], v[202:205], v[98:101], v[50:53]
	v_exp_f32_e32 v138, v138
	ds_read_b128 v[178:181], v234 offset:32768
	v_mfma_f32_16x16x32_bf16 v[54:57], v[202:205], v[102:105], v[54:57]
	v_exp_f32_e32 v139, v139
	s_waitcnt lgkmcnt(5)
	v_mfma_f32_16x16x32_bf16 v[58:61], v[206:209], v[98:101], v[58:61]
	v_exp_f32_e32 v140, v140
	ds_read_b128 v[182:185], v234 offset:36864
	v_mfma_f32_16x16x32_bf16 v[62:65], v[206:209], v[102:105], v[62:65]
	v_exp_f32_e32 v141, v141
	s_waitcnt lgkmcnt(4)
	v_mfma_f32_16x16x32_bf16 v[66:69], v[210:213], v[98:101], v[66:69]
	v_exp_f32_e32 v142, v142
	ds_read_b128 v[186:189], v234 offset:40960
	v_mfma_f32_16x16x32_bf16 v[70:73], v[210:213], v[102:105], v[70:73]
	v_exp_f32_e32 v143, v143
	s_waitcnt lgkmcnt(3)
	v_mfma_f32_16x16x32_bf16 v[74:77], v[214:217], v[98:101], v[74:77]
	v_exp_f32_e32 v144, v144
	ds_read_b128 v[190:193], v234 offset:45056
	v_mfma_f32_16x16x32_bf16 v[78:81], v[214:217], v[102:105], v[78:81]
	v_exp_f32_e32 v145, v145
	s_waitcnt vmcnt(2)
	s_barrier
; __device__ __forceinline__ void partialSM(f32x16& p0, f32x16& p1, float mC) {
;   (void)mC; (void)p1;
;   for (int r = 0; r < 16; ++r) p0[r] = __builtin_amdgcn_exp2f(p0[r]);
; }
; __device__ __forceinline__ void finishSM(f32x16& p0, f32x16& p1, float& l_reg, bf16x8& pa0, bf16x8& pa1, bf16x8& pa2, bf16x8& pa3) {
;   for (int r = 0; r < 16; ++r) p1[r] = __builtin_amdgcn_exp2f(p1[r]);
;   float ps = 0; for (int r = 0; r < 16; ++r) ps += p0[r]; for (int r = 0; r < 16; ++r) ps += p1[r];
;   { auto rr = __builtin_amdgcn_permlane32_swap(__float_as_uint(ps), __float_as_uint(ps), false, false);
;     ps = __uint_as_float(rr[0]) + __uint_as_float(rr[1]); }
;   l_reg += ps;
;     ...
;   PK4(p0, 0, pa0); PK4(p0, 8, pa1); PK4(p1, 0, pa2); PK4(p1, 8, pa3);
;     ...
; }
; __device__ __forceinline__ void qkt(f32x16& p0, f32x16& p1, const bf16* Ks, const bf16x8* qr, int r32, int hi, const f32x16& negm) {
; #pragma unroll
;   for (int d0 = 0; d0 < 8; ++d0) { int cb = (d0 * 16 + hi * 8) * 2;
;     bf16x8 b0 = *reinterpret_cast<const bf16x8*>((const char*)Ks + KSWZ(r32, cb));
;     bf16x8 b1 = *reinterpret_cast<const bf16x8*>((const char*)Ks + KSWZ(32 + r32, cb));
;     if (d0 == 0) { p0 = __builtin_amdgcn_mfma_f32_32x32x16_bf16(b0, qr[0], negm, 0, 0, 0); p1 = __builtin_amdgcn_mfma_f32_32x32x16_bf16(b1, qr[0], negm, 0, 0, 0); }
;     else { p0 = __builtin_amdgcn_mfma_f32_32x32x16_bf16(b0, qr[d0], p0, 0, 0, 0); p1 = __builtin_amdgcn_mfma_f32_32x32x16_bf16(b1, qr[d0], p1, 0, 0, 0); } }
; }
; __device__ __forceinline__ int v_st(int k, int c) { const int kk = (k & ~0xC) | ((k & 4) << 1) | ((k & 8) >> 1); return ((kk >> 3) * 4 + (c >> 5)) * 512 + ((kk & 7) * 32 + (c & 31)) * 2; }
; __device__ __forceinline__ int v_rd_base(int lane) { return ((lane & 3) << 3) | (((lane >> 2) & 3) << 6) | (((lane >> 4) & 1) << 5) | (((lane >> 5) & 1) << 8); }
; template <int OFF> __device__ __forceinline__ s16x4 tr_read(int vb) {
;   s16x4 r; asm volatile("ds_read_b64_tr_b16 %0, %1 offset:%2" : "=&v"(r) : "v"(vb), "i"(OFF) : "memory"); return r;
; }
; template <typename TQ> ...
;     ...
;   SBAR(); qkt(pB0, pB1, (bf16*)((char*)K_lds + SHM_K), qr, r32, hi, negm);
;   finishSM(pA0, pA1, l_reg, pa0, pa1, pa2, pa3); SBAR();
;   pv_d0(o, vb0, pa0, pa1, pa2, pa3); partialSM(pB0, pB1, mC);
;   __syncthreads();
;   finishSM(pB0, pB1, l_reg, pa0, pa1, pa2, pa3); SBAR();
;   pv_d0(o, vb0 + (int)SHM_V, pa0, pa1, pa2, pa3);
	s_waitcnt lgkmcnt(3)
	v_mfma_f32_16x16x32_bf16 v[82:85], v[178:181], v[146:149], v[2:5]
	v_add_f32_e32 v250, v114, v250
	v_mfma_f32_16x16x32_bf16 v[86:89], v[178:181], v[162:165], v[2:5]
	ds_read_b128 v[178:181], v235 offset:32768
	v_add_f32_e32 v250, v115, v250
	v_add_f32_e32 v250, v116, v250
	s_waitcnt lgkmcnt(3)
	v_mfma_f32_16x16x32_bf16 v[90:93], v[182:185], v[146:149], v[2:5]
	v_add_f32_e32 v250, v117, v250
	v_mfma_f32_16x16x32_bf16 v[94:97], v[182:185], v[162:165], v[2:5]
	ds_read_b128 v[182:185], v235 offset:36864
	v_add_f32_e32 v250, v122, v250
	v_add_f32_e32 v250, v123, v250
	s_waitcnt lgkmcnt(3)
	v_mfma_f32_16x16x32_bf16 v[98:101], v[186:189], v[146:149], v[2:5]
	v_add_f32_e32 v250, v124, v250
	v_mfma_f32_16x16x32_bf16 v[102:105], v[186:189], v[162:165], v[2:5]
	ds_read_b128 v[186:189], v235 offset:40960
	v_add_f32_e32 v250, v125, v250
	v_cvt_pk_bf16_f32 v114, v114, v115
	s_waitcnt lgkmcnt(3)
	v_mfma_f32_16x16x32_bf16 v[106:109], v[190:193], v[146:149], v[2:5]
	v_cvt_pk_bf16_f32 v115, v116, v117
	v_mfma_f32_16x16x32_bf16 v[110:113], v[190:193], v[162:165], v[2:5]
	ds_read_b128 v[190:193], v235 offset:45056
	v_cvt_pk_bf16_f32 v116, v122, v123
	v_cvt_pk_bf16_f32 v117, v124, v125
	s_waitcnt lgkmcnt(3)
	v_mfma_f32_16x16x32_bf16 v[82:85], v[178:181], v[150:153], v[82:85]
	v_add_f32_e32 v251, v118, v251
	v_mfma_f32_16x16x32_bf16 v[86:89], v[178:181], v[166:169], v[86:89]
	ds_read_b128 v[178:181], v236 offset:32768
	v_add_f32_e32 v251, v119, v251
	v_add_f32_e32 v251, v120, v251
	s_waitcnt lgkmcnt(3)
	v_mfma_f32_16x16x32_bf16 v[90:93], v[182:185], v[150:153], v[90:93]
	v_add_f32_e32 v251, v121, v251
	v_mfma_f32_16x16x32_bf16 v[94:97], v[182:185], v[166:169], v[94:97]
	ds_read_b128 v[182:185], v236 offset:36864
	v_add_f32_e32 v251, v126, v251
	v_add_f32_e32 v251, v127, v251
	s_waitcnt lgkmcnt(3)
	v_mfma_f32_16x16x32_bf16 v[98:101], v[186:189], v[150:153], v[98:101]
	v_add_f32_e32 v251, v128, v251
	v_mfma_f32_16x16x32_bf16 v[102:105], v[186:189], v[166:169], v[102:105]
	ds_read_b128 v[186:189], v236 offset:40960
	v_add_f32_e32 v251, v129, v251
	v_cvt_pk_bf16_f32 v118, v118, v119
	s_waitcnt lgkmcnt(3)
	v_mfma_f32_16x16x32_bf16 v[106:109], v[190:193], v[150:153], v[106:109]
	v_cvt_pk_bf16_f32 v119, v120, v121
	v_mfma_f32_16x16x32_bf16 v[110:113], v[190:193], v[166:169], v[110:113]
	ds_read_b128 v[190:193], v236 offset:45056
	v_cvt_pk_bf16_f32 v120, v126, v127
	v_cvt_pk_bf16_f32 v121, v128, v129
	s_waitcnt lgkmcnt(3)
	v_mfma_f32_16x16x32_bf16 v[82:85], v[178:181], v[154:157], v[82:85]
	v_add_f32_e32 v250, v130, v250
	v_mfma_f32_16x16x32_bf16 v[86:89], v[178:181], v[170:173], v[86:89]
	ds_read_b128 v[178:181], v237 offset:32768
	v_add_f32_e32 v250, v131, v250
	v_add_f32_e32 v250, v132, v250
	s_waitcnt lgkmcnt(3)
	v_mfma_f32_16x16x32_bf16 v[90:93], v[182:185], v[154:157], v[90:93]
	v_add_f32_e32 v250, v133, v250
	v_mfma_f32_16x16x32_bf16 v[94:97], v[182:185], v[170:173], v[94:97]
	ds_read_b128 v[182:185], v237 offset:36864
	v_add_f32_e32 v250, v138, v250
	v_add_f32_e32 v250, v139, v250
	s_waitcnt lgkmcnt(3)
	v_mfma_f32_16x16x32_bf16 v[98:101], v[186:189], v[154:157], v[98:101]
	v_add_f32_e32 v250, v140, v250
	ds_read_b64_tr_b16 v[202:203], v238 offset:16384
	ds_read_b64_tr_b16 v[204:205], v238 offset:20480
	v_mfma_f32_16x16x32_bf16 v[102:105], v[186:189], v[170:173], v[102:105]
	ds_read_b128 v[186:189], v237 offset:40960
	v_add_f32_e32 v250, v141, v250
	v_cvt_pk_bf16_f32 v130, v130, v131
	s_waitcnt lgkmcnt(5)
	v_mfma_f32_16x16x32_bf16 v[106:109], v[190:193], v[154:157], v[106:109]
	v_cvt_pk_bf16_f32 v131, v132, v133
	ds_read_b64_tr_b16 v[206:207], v239 offset:16384
	ds_read_b64_tr_b16 v[208:209], v239 offset:20480
	v_mfma_f32_16x16x32_bf16 v[110:113], v[190:193], v[170:173], v[110:113]
	ds_read_b128 v[190:193], v237 offset:45056
	v_cvt_pk_bf16_f32 v132, v138, v139
	v_cvt_pk_bf16_f32 v133, v140, v141
	s_waitcnt lgkmcnt(7)
	v_mfma_f32_16x16x32_bf16 v[82:85], v[178:181], v[158:161], v[82:85]
	v_add_f32_e32 v251, v134, v251
	ds_read_b64_tr_b16 v[210:211], v240 offset:16384
	ds_read_b64_tr_b16 v[212:213], v240 offset:20480
	v_mfma_f32_16x16x32_bf16 v[86:89], v[178:181], v[174:177], v[86:89]
	v_add_f32_e32 v251, v135, v251
	v_add_f32_e32 v251, v136, v251
	s_waitcnt lgkmcnt(8)
	v_mfma_f32_16x16x32_bf16 v[90:93], v[182:185], v[158:161], v[90:93]
	v_add_f32_e32 v251, v137, v251
	ds_read_b64_tr_b16 v[214:215], v241 offset:16384
	ds_read_b64_tr_b16 v[216:217], v241 offset:20480
	v_mfma_f32_16x16x32_bf16 v[94:97], v[182:185], v[174:177], v[94:97]
	v_add_f32_e32 v251, v142, v251
	v_add_f32_e32 v251, v143, v251
	s_waitcnt lgkmcnt(7)
	v_mfma_f32_16x16x32_bf16 v[98:101], v[186:189], v[158:161], v[98:101]
	v_add_f32_e32 v251, v144, v251
	ds_read_b64_tr_b16 v[218:219], v242 offset:16384
	ds_read_b64_tr_b16 v[220:221], v242 offset:20480
	v_mfma_f32_16x16x32_bf16 v[102:105], v[186:189], v[174:177], v[102:105]
	v_add_f32_e32 v251, v145, v251
	v_cvt_pk_bf16_f32 v134, v134, v135
	s_waitcnt lgkmcnt(6)
	v_mfma_f32_16x16x32_bf16 v[106:109], v[190:193], v[158:161], v[106:109]
	v_cvt_pk_bf16_f32 v135, v136, v137
	ds_read_b64_tr_b16 v[222:223], v243 offset:16384
	ds_read_b64_tr_b16 v[224:225], v243 offset:20480
	v_mfma_f32_16x16x32_bf16 v[110:113], v[190:193], v[174:177], v[110:113]
	v_cvt_pk_bf16_f32 v136, v142, v143
	v_cvt_pk_bf16_f32 v137, v144, v145
	v_mfma_f32_16x16x32_bf16 v[18:21], v[202:205], v[114:117], v[18:21]
	v_exp_f32_e32 v82, v82
	v_mfma_f32_16x16x32_bf16 v[22:25], v[202:205], v[118:121], v[22:25]
	ds_read_b64_tr_b16 v[202:203], v244 offset:16384
	ds_read_b64_tr_b16 v[204:205], v244 offset:20480
	v_exp_f32_e32 v83, v83
	v_mfma_f32_16x16x32_bf16 v[26:29], v[206:209], v[114:117], v[26:29]
	v_exp_f32_e32 v84, v84
	v_mfma_f32_16x16x32_bf16 v[30:33], v[206:209], v[118:121], v[30:33]
	ds_read_b64_tr_b16 v[206:207], v245 offset:16384
	ds_read_b64_tr_b16 v[208:209], v245 offset:20480
	v_exp_f32_e32 v85, v85
	s_waitcnt lgkmcnt(10)
; __device__ __forceinline__ void partialSM(f32x16& p0, f32x16& p1, float mC) {
;   (void)mC; (void)p1;
;   for (int r = 0; r < 16; ++r) p0[r] = __builtin_amdgcn_exp2f(p0[r]);
; }
; __device__ __forceinline__ void finishSM(f32x16& p0, f32x16& p1, float& l_reg, bf16x8& pa0, bf16x8& pa1, bf16x8& pa2, bf16x8& pa3) {
;   for (int r = 0; r < 16; ++r) p1[r] = __builtin_amdgcn_exp2f(p1[r]);
;   float ps = 0; for (int r = 0; r < 16; ++r) ps += p0[r]; for (int r = 0; r < 16; ++r) ps += p1[r];
;   { auto rr = __builtin_amdgcn_permlane32_swap(__float_as_uint(ps), __float_as_uint(ps), false, false);
;     ps = __uint_as_float(rr[0]) + __uint_as_float(rr[1]); }
;   l_reg += ps;
;     ...
;   PK4(p0, 0, pa0); PK4(p0, 8, pa1); PK4(p1, 0, pa2); PK4(p1, 8, pa3);
;     ...
; }
; __device__ __forceinline__ void qkt(f32x16& p0, f32x16& p1, const bf16* Ks, const bf16x8* qr, int r32, int hi, const f32x16& negm) {
; #pragma unroll
;   for (int d0 = 0; d0 < 8; ++d0) { int cb = (d0 * 16 + hi * 8) * 2;
;     bf16x8 b0 = *reinterpret_cast<const bf16x8*>((const char*)Ks + KSWZ(r32, cb));
;     bf16x8 b1 = *reinterpret_cast<const bf16x8*>((const char*)Ks + KSWZ(32 + r32, cb));
;     if (d0 == 0) { p0 = __builtin_amdgcn_mfma_f32_32x32x16_bf16(b0, qr[0], negm, 0, 0, 0); p1 = __builtin_amdgcn_mfma_f32_32x32x16_bf16(b1, qr[0], negm, 0, 0, 0); }
;     else { p0 = __builtin_amdgcn_mfma_f32_32x32x16_bf16(b0, qr[d0], p0, 0, 0, 0); p1 = __builtin_amdgcn_mfma_f32_32x32x16_bf16(b1, qr[d0], p1, 0, 0, 0); } }
; }
; __device__ __forceinline__ int v_st(int k, int c) { const int kk = (k & ~0xC) | ((k & 4) << 1) | ((k & 8) >> 1); return ((kk >> 3) * 4 + (c >> 5)) * 512 + ((kk & 7) * 32 + (c & 31)) * 2; }
; __device__ __forceinline__ int v_rd_base(int lane) { return ((lane & 3) << 3) | (((lane >> 2) & 3) << 6) | (((lane >> 4) & 1) << 5) | (((lane >> 5) & 1) << 8); }
; template <int OFF> __device__ __forceinline__ s16x4 tr_read(int vb) {
;   s16x4 r; asm volatile("ds_read_b64_tr_b16 %0, %1 offset:%2" : "=&v"(r) : "v"(vb), "i"(OFF) : "memory"); return r;
; }
; template <typename TQ> ...
;     ...
;   SBAR(); qkt(pB0, pB1, (bf16*)((char*)K_lds + SHM_K), qr, r32, hi, negm);
;   finishSM(pA0, pA1, l_reg, pa0, pa1, pa2, pa3); SBAR();
;   pv_d0(o, vb0, pa0, pa1, pa2, pa3); partialSM(pB0, pB1, mC);
;   __syncthreads();
;   finishSM(pB0, pB1, l_reg, pa0, pa1, pa2, pa3); SBAR();
;   pv_d0(o, vb0 + (int)SHM_V, pa0, pa1, pa2, pa3);
	v_mfma_f32_16x16x32_bf16 v[34:37], v[210:213], v[114:117], v[34:37]
	v_exp_f32_e32 v86, v86
	v_mfma_f32_16x16x32_bf16 v[38:41], v[210:213], v[118:121], v[38:41]
	ds_read_b64_tr_b16 v[210:211], v238 offset:24576
	ds_read_b64_tr_b16 v[212:213], v238 offset:28672
	v_exp_f32_e32 v87, v87
	s_waitcnt lgkmcnt(10)
	v_mfma_f32_16x16x32_bf16 v[42:45], v[214:217], v[114:117], v[42:45]
	v_exp_f32_e32 v88, v88
	v_mfma_f32_16x16x32_bf16 v[46:49], v[214:217], v[118:121], v[46:49]
	ds_read_b64_tr_b16 v[214:215], v239 offset:24576
	ds_read_b64_tr_b16 v[216:217], v239 offset:28672
	v_exp_f32_e32 v89, v89
	s_waitcnt lgkmcnt(10)
	v_mfma_f32_16x16x32_bf16 v[50:53], v[218:221], v[114:117], v[50:53]
	v_exp_f32_e32 v90, v90
	v_mfma_f32_16x16x32_bf16 v[54:57], v[218:221], v[118:121], v[54:57]
	ds_read_b64_tr_b16 v[218:219], v240 offset:24576
	ds_read_b64_tr_b16 v[220:221], v240 offset:28672
	v_exp_f32_e32 v91, v91
	s_waitcnt lgkmcnt(10)
	v_mfma_f32_16x16x32_bf16 v[58:61], v[222:225], v[114:117], v[58:61]
	v_exp_f32_e32 v92, v92
	v_mfma_f32_16x16x32_bf16 v[62:65], v[222:225], v[118:121], v[62:65]
	ds_read_b64_tr_b16 v[222:223], v241 offset:24576
	ds_read_b64_tr_b16 v[224:225], v241 offset:28672
	v_exp_f32_e32 v93, v93
	s_waitcnt lgkmcnt(10)
	v_mfma_f32_16x16x32_bf16 v[66:69], v[202:205], v[114:117], v[66:69]
	v_exp_f32_e32 v94, v94
	v_mfma_f32_16x16x32_bf16 v[70:73], v[202:205], v[118:121], v[70:73]
	ds_read_b64_tr_b16 v[202:203], v242 offset:24576
	ds_read_b64_tr_b16 v[204:205], v242 offset:28672
	v_exp_f32_e32 v95, v95
	s_waitcnt lgkmcnt(10)
	v_mfma_f32_16x16x32_bf16 v[74:77], v[206:209], v[114:117], v[74:77]
	v_exp_f32_e32 v96, v96
	v_mfma_f32_16x16x32_bf16 v[78:81], v[206:209], v[118:121], v[78:81]
	ds_read_b64_tr_b16 v[206:207], v243 offset:24576
	ds_read_b64_tr_b16 v[208:209], v243 offset:28672
	v_exp_f32_e32 v97, v97
	s_waitcnt lgkmcnt(10)
	v_mfma_f32_16x16x32_bf16 v[18:21], v[210:213], v[130:133], v[18:21]
	v_exp_f32_e32 v98, v98
	v_mfma_f32_16x16x32_bf16 v[22:25], v[210:213], v[134:137], v[22:25]
	ds_read_b64_tr_b16 v[210:211], v244 offset:24576
	ds_read_b64_tr_b16 v[212:213], v244 offset:28672
	v_exp_f32_e32 v99, v99
	s_waitcnt lgkmcnt(10)
	v_mfma_f32_16x16x32_bf16 v[26:29], v[214:217], v[130:133], v[26:29]
	v_exp_f32_e32 v100, v100
	v_mfma_f32_16x16x32_bf16 v[30:33], v[214:217], v[134:137], v[30:33]
	ds_read_b64_tr_b16 v[214:215], v245 offset:24576
	ds_read_b64_tr_b16 v[216:217], v245 offset:28672
	v_exp_f32_e32 v101, v101
	s_waitcnt lgkmcnt(10)
	v_mfma_f32_16x16x32_bf16 v[34:37], v[218:221], v[130:133], v[34:37]
	v_exp_f32_e32 v102, v102
	v_mfma_f32_16x16x32_bf16 v[38:41], v[218:221], v[134:137], v[38:41]
	v_exp_f32_e32 v103, v103
	s_waitcnt lgkmcnt(8)
	v_mfma_f32_16x16x32_bf16 v[42:45], v[222:225], v[130:133], v[42:45]
	v_exp_f32_e32 v104, v104
	v_mfma_f32_16x16x32_bf16 v[46:49], v[222:225], v[134:137], v[46:49]
	v_exp_f32_e32 v105, v105
	s_waitcnt lgkmcnt(6)
	v_mfma_f32_16x16x32_bf16 v[50:53], v[202:205], v[130:133], v[50:53]
	v_exp_f32_e32 v106, v106
	ds_read_b128 v[178:181], v234 offset:49152
	v_mfma_f32_16x16x32_bf16 v[54:57], v[202:205], v[134:137], v[54:57]
	v_exp_f32_e32 v107, v107
	s_waitcnt lgkmcnt(5)
	v_mfma_f32_16x16x32_bf16 v[58:61], v[206:209], v[130:133], v[58:61]
	v_exp_f32_e32 v108, v108
	ds_read_b128 v[182:185], v234 offset:53248
	v_mfma_f32_16x16x32_bf16 v[62:65], v[206:209], v[134:137], v[62:65]
	v_exp_f32_e32 v109, v109
	s_waitcnt lgkmcnt(4)
	v_mfma_f32_16x16x32_bf16 v[66:69], v[210:213], v[130:133], v[66:69]
	v_exp_f32_e32 v110, v110
	ds_read_b128 v[186:189], v234 offset:57344
	v_mfma_f32_16x16x32_bf16 v[70:73], v[210:213], v[134:137], v[70:73]
	v_exp_f32_e32 v111, v111
	s_waitcnt lgkmcnt(3)
	v_mfma_f32_16x16x32_bf16 v[74:77], v[214:217], v[130:133], v[74:77]
	v_exp_f32_e32 v112, v112
	ds_read_b128 v[190:193], v234 offset:61440
	v_mfma_f32_16x16x32_bf16 v[78:81], v[214:217], v[134:137], v[78:81]
	v_exp_f32_e32 v113, v113
	s_waitcnt vmcnt(0)
	s_barrier
	s_waitcnt lgkmcnt(3)
	v_mfma_f32_16x16x32_bf16 v[114:117], v[178:181], v[146:149], v[2:5]
	v_add_f32_e32 v250, v82, v250
	v_mfma_f32_16x16x32_bf16 v[118:121], v[178:181], v[162:165], v[2:5]
	ds_read_b128 v[178:181], v235 offset:49152
	v_add_f32_e32 v250, v83, v250
	v_add_f32_e32 v250, v84, v250
	s_waitcnt lgkmcnt(3)
	v_mfma_f32_16x16x32_bf16 v[122:125], v[182:185], v[146:149], v[2:5]
	v_add_f32_e32 v250, v85, v250
	v_mfma_f32_16x16x32_bf16 v[126:129], v[182:185], v[162:165], v[2:5]
	ds_read_b128 v[182:185], v235 offset:53248
	v_add_f32_e32 v250, v90, v250
	v_add_f32_e32 v250, v91, v250
	s_waitcnt lgkmcnt(3)
	v_mfma_f32_16x16x32_bf16 v[130:133], v[186:189], v[146:149], v[2:5]
	v_add_f32_e32 v250, v92, v250
	v_mfma_f32_16x16x32_bf16 v[134:137], v[186:189], v[162:165], v[2:5]
	ds_read_b128 v[186:189], v235 offset:57344
	v_add_f32_e32 v250, v93, v250
	v_cvt_pk_bf16_f32 v82, v82, v83
	s_waitcnt lgkmcnt(3)
	v_mfma_f32_16x16x32_bf16 v[138:141], v[190:193], v[146:149], v[2:5]
	v_cvt_pk_bf16_f32 v83, v84, v85
	v_mfma_f32_16x16x32_bf16 v[142:145], v[190:193], v[162:165], v[2:5]
	ds_read_b128 v[190:193], v235 offset:61440
	v_cvt_pk_bf16_f32 v84, v90, v91
	v_cvt_pk_bf16_f32 v85, v92, v93
	s_waitcnt lgkmcnt(3)
	v_mfma_f32_16x16x32_bf16 v[114:117], v[178:181], v[150:153], v[114:117]
	v_add_f32_e32 v251, v86, v251
	v_mfma_f32_16x16x32_bf16 v[118:121], v[178:181], v[166:169], v[118:121]
	ds_read_b128 v[178:181], v236 offset:49152
	v_add_f32_e32 v251, v87, v251
	v_add_f32_e32 v251, v88, v251
	s_waitcnt lgkmcnt(3)
	v_mfma_f32_16x16x32_bf16 v[122:125], v[182:185], v[150:153], v[122:125]
	v_add_f32_e32 v251, v89, v251
	v_mfma_f32_16x16x32_bf16 v[126:129], v[182:185], v[166:169], v[126:129]
	ds_read_b128 v[182:185], v236 offset:53248
	v_add_f32_e32 v251, v94, v251
	v_add_f32_e32 v251, v95, v251
	s_waitcnt lgkmcnt(3)
; __device__ __forceinline__ void partialSM(f32x16& p0, f32x16& p1, float mC) {
;   (void)mC; (void)p1;
;   for (int r = 0; r < 16; ++r) p0[r] = __builtin_amdgcn_exp2f(p0[r]);
; }
; __device__ __forceinline__ void finishSM(f32x16& p0, f32x16& p1, float& l_reg, bf16x8& pa0, bf16x8& pa1, bf16x8& pa2, bf16x8& pa3) {
;   for (int r = 0; r < 16; ++r) p1[r] = __builtin_amdgcn_exp2f(p1[r]);
;   float ps = 0; for (int r = 0; r < 16; ++r) ps += p0[r]; for (int r = 0; r < 16; ++r) ps += p1[r];
;   { auto rr = __builtin_amdgcn_permlane32_swap(__float_as_uint(ps), __float_as_uint(ps), false, false);
;     ps = __uint_as_float(rr[0]) + __uint_as_float(rr[1]); }
;   l_reg += ps;
;     ...
;   PK4(p0, 0, pa0); PK4(p0, 8, pa1); PK4(p1, 0, pa2); PK4(p1, 8, pa3);
;     ...
; }
; __device__ __forceinline__ void qkt(f32x16& p0, f32x16& p1, const bf16* Ks, const bf16x8* qr, int r32, int hi, const f32x16& negm) {
; #pragma unroll
;   for (int d0 = 0; d0 < 8; ++d0) { int cb = (d0 * 16 + hi * 8) * 2;
;     bf16x8 b0 = *reinterpret_cast<const bf16x8*>((const char*)Ks + KSWZ(r32, cb));
;     bf16x8 b1 = *reinterpret_cast<const bf16x8*>((const char*)Ks + KSWZ(32 + r32, cb));
;     if (d0 == 0) { p0 = __builtin_amdgcn_mfma_f32_32x32x16_bf16(b0, qr[0], negm, 0, 0, 0); p1 = __builtin_amdgcn_mfma_f32_32x32x16_bf16(b1, qr[0], negm, 0, 0, 0); }
;     else { p0 = __builtin_amdgcn_mfma_f32_32x32x16_bf16(b0, qr[d0], p0, 0, 0, 0); p1 = __builtin_amdgcn_mfma_f32_32x32x16_bf16(b1, qr[d0], p1, 0, 0, 0); } }
; }
; __device__ __forceinline__ int v_st(int k, int c) { const int kk = (k & ~0xC) | ((k & 4) << 1) | ((k & 8) >> 1); return ((kk >> 3) * 4 + (c >> 5)) * 512 + ((kk & 7) * 32 + (c & 31)) * 2; }
; __device__ __forceinline__ int v_rd_base(int lane) { return ((lane & 3) << 3) | (((lane >> 2) & 3) << 6) | (((lane >> 4) & 1) << 5) | (((lane >> 5) & 1) << 8); }
; template <int OFF> __device__ __forceinline__ s16x4 tr_read(int vb) {
;   s16x4 r; asm volatile("ds_read_b64_tr_b16 %0, %1 offset:%2" : "=&v"(r) : "v"(vb), "i"(OFF) : "memory"); return r;
; }
; template <typename TQ> ...
;     ...
;   SBAR(); qkt(pB0, pB1, (bf16*)((char*)K_lds + SHM_K), qr, r32, hi, negm);
;   finishSM(pA0, pA1, l_reg, pa0, pa1, pa2, pa3); SBAR();
;   pv_d0(o, vb0, pa0, pa1, pa2, pa3); partialSM(pB0, pB1, mC);
;   __syncthreads();
;   finishSM(pB0, pB1, l_reg, pa0, pa1, pa2, pa3); SBAR();
;   pv_d0(o, vb0 + (int)SHM_V, pa0, pa1, pa2, pa3);
	v_mfma_f32_16x16x32_bf16 v[130:133], v[186:189], v[150:153], v[130:133]
	v_add_f32_e32 v251, v96, v251
	v_mfma_f32_16x16x32_bf16 v[134:137], v[186:189], v[166:169], v[134:137]
	ds_read_b128 v[186:189], v236 offset:57344
	v_add_f32_e32 v251, v97, v251
	v_cvt_pk_bf16_f32 v86, v86, v87
	s_waitcnt lgkmcnt(3)
	v_mfma_f32_16x16x32_bf16 v[138:141], v[190:193], v[150:153], v[138:141]
	v_cvt_pk_bf16_f32 v87, v88, v89
	v_mfma_f32_16x16x32_bf16 v[142:145], v[190:193], v[166:169], v[142:145]
	ds_read_b128 v[190:193], v236 offset:61440
	v_cvt_pk_bf16_f32 v88, v94, v95
	v_cvt_pk_bf16_f32 v89, v96, v97
	s_waitcnt lgkmcnt(3)
	v_mfma_f32_16x16x32_bf16 v[114:117], v[178:181], v[154:157], v[114:117]
	v_add_f32_e32 v250, v98, v250
	v_mfma_f32_16x16x32_bf16 v[118:121], v[178:181], v[170:173], v[118:121]
	ds_read_b128 v[178:181], v237 offset:49152
	v_add_f32_e32 v250, v99, v250
	v_add_f32_e32 v250, v100, v250
	s_waitcnt lgkmcnt(3)
	v_mfma_f32_16x16x32_bf16 v[122:125], v[182:185], v[154:157], v[122:125]
	v_add_f32_e32 v250, v101, v250
	v_mfma_f32_16x16x32_bf16 v[126:129], v[182:185], v[170:173], v[126:129]
	ds_read_b128 v[182:185], v237 offset:53248
	v_add_f32_e32 v250, v106, v250
	v_add_f32_e32 v250, v107, v250
	s_waitcnt lgkmcnt(3)
	v_mfma_f32_16x16x32_bf16 v[130:133], v[186:189], v[154:157], v[130:133]
	v_add_f32_e32 v250, v108, v250
	ds_read_b64_tr_b16 v[202:203], v238 offset:32768
	ds_read_b64_tr_b16 v[204:205], v238 offset:36864
	v_mfma_f32_16x16x32_bf16 v[134:137], v[186:189], v[170:173], v[134:137]
	ds_read_b128 v[186:189], v237 offset:57344
	v_add_f32_e32 v250, v109, v250
	v_cvt_pk_bf16_f32 v98, v98, v99
	s_waitcnt lgkmcnt(5)
	v_mfma_f32_16x16x32_bf16 v[138:141], v[190:193], v[154:157], v[138:141]
	v_cvt_pk_bf16_f32 v99, v100, v101
	ds_read_b64_tr_b16 v[206:207], v239 offset:32768
	ds_read_b64_tr_b16 v[208:209], v239 offset:36864
	v_mfma_f32_16x16x32_bf16 v[142:145], v[190:193], v[170:173], v[142:145]
	ds_read_b128 v[190:193], v237 offset:61440
	v_cvt_pk_bf16_f32 v100, v106, v107
	v_cvt_pk_bf16_f32 v101, v108, v109
	s_waitcnt lgkmcnt(7)
	v_mfma_f32_16x16x32_bf16 v[114:117], v[178:181], v[158:161], v[114:117]
	v_add_f32_e32 v251, v102, v251
	ds_read_b64_tr_b16 v[210:211], v240 offset:32768
	ds_read_b64_tr_b16 v[212:213], v240 offset:36864
	v_mfma_f32_16x16x32_bf16 v[118:121], v[178:181], v[174:177], v[118:121]
	v_add_f32_e32 v251, v103, v251
	v_add_f32_e32 v251, v104, v251
	s_waitcnt lgkmcnt(8)
	v_mfma_f32_16x16x32_bf16 v[122:125], v[182:185], v[158:161], v[122:125]
	v_add_f32_e32 v251, v105, v251
	ds_read_b64_tr_b16 v[214:215], v241 offset:32768
	ds_read_b64_tr_b16 v[216:217], v241 offset:36864
	v_mfma_f32_16x16x32_bf16 v[126:129], v[182:185], v[174:177], v[126:129]
	v_add_f32_e32 v251, v110, v251
	v_add_f32_e32 v251, v111, v251
	s_waitcnt lgkmcnt(7)
	v_mfma_f32_16x16x32_bf16 v[130:133], v[186:189], v[158:161], v[130:133]
	v_add_f32_e32 v251, v112, v251
	ds_read_b64_tr_b16 v[218:219], v242 offset:32768
	ds_read_b64_tr_b16 v[220:221], v242 offset:36864
	v_mfma_f32_16x16x32_bf16 v[134:137], v[186:189], v[174:177], v[134:137]
	v_add_f32_e32 v251, v113, v251
	v_cvt_pk_bf16_f32 v102, v102, v103
	s_waitcnt lgkmcnt(6)
	v_mfma_f32_16x16x32_bf16 v[138:141], v[190:193], v[158:161], v[138:141]
	v_cvt_pk_bf16_f32 v103, v104, v105
	ds_read_b64_tr_b16 v[222:223], v243 offset:32768
	ds_read_b64_tr_b16 v[224:225], v243 offset:36864
	v_mfma_f32_16x16x32_bf16 v[142:145], v[190:193], v[174:177], v[142:145]
	v_cvt_pk_bf16_f32 v104, v110, v111
	v_cvt_pk_bf16_f32 v105, v112, v113
	v_mfma_f32_16x16x32_bf16 v[18:21], v[202:205], v[82:85], v[18:21]
	v_exp_f32_e32 v114, v114
	v_mfma_f32_16x16x32_bf16 v[22:25], v[202:205], v[86:89], v[22:25]
	ds_read_b64_tr_b16 v[202:203], v244 offset:32768
	ds_read_b64_tr_b16 v[204:205], v244 offset:36864
	v_exp_f32_e32 v115, v115
	v_mfma_f32_16x16x32_bf16 v[26:29], v[206:209], v[82:85], v[26:29]
	v_exp_f32_e32 v116, v116
	v_mfma_f32_16x16x32_bf16 v[30:33], v[206:209], v[86:89], v[30:33]
	ds_read_b64_tr_b16 v[206:207], v245 offset:32768
	ds_read_b64_tr_b16 v[208:209], v245 offset:36864
	v_exp_f32_e32 v117, v117
	s_waitcnt lgkmcnt(10)
	v_mfma_f32_16x16x32_bf16 v[34:37], v[210:213], v[82:85], v[34:37]
	v_exp_f32_e32 v118, v118
	v_mfma_f32_16x16x32_bf16 v[38:41], v[210:213], v[86:89], v[38:41]
	ds_read_b64_tr_b16 v[210:211], v238 offset:40960
	ds_read_b64_tr_b16 v[212:213], v238 offset:45056
	v_exp_f32_e32 v119, v119
	s_waitcnt lgkmcnt(10)
	v_mfma_f32_16x16x32_bf16 v[42:45], v[214:217], v[82:85], v[42:45]
	v_exp_f32_e32 v120, v120
	v_mfma_f32_16x16x32_bf16 v[46:49], v[214:217], v[86:89], v[46:49]
	ds_read_b64_tr_b16 v[214:215], v239 offset:40960
	ds_read_b64_tr_b16 v[216:217], v239 offset:45056
	v_exp_f32_e32 v121, v121
	s_waitcnt lgkmcnt(10)
	v_mfma_f32_16x16x32_bf16 v[50:53], v[218:221], v[82:85], v[50:53]
	v_exp_f32_e32 v122, v122
	v_mfma_f32_16x16x32_bf16 v[54:57], v[218:221], v[86:89], v[54:57]
	ds_read_b64_tr_b16 v[218:219], v240 offset:40960
	ds_read_b64_tr_b16 v[220:221], v240 offset:45056
	v_exp_f32_e32 v123, v123
	s_waitcnt lgkmcnt(10)
	v_mfma_f32_16x16x32_bf16 v[58:61], v[222:225], v[82:85], v[58:61]
	v_exp_f32_e32 v124, v124
	v_mfma_f32_16x16x32_bf16 v[62:65], v[222:225], v[86:89], v[62:65]
	ds_read_b64_tr_b16 v[222:223], v241 offset:40960
	ds_read_b64_tr_b16 v[224:225], v241 offset:45056
	v_exp_f32_e32 v125, v125
	s_waitcnt lgkmcnt(10)
	v_mfma_f32_16x16x32_bf16 v[66:69], v[202:205], v[82:85], v[66:69]
	v_exp_f32_e32 v126, v126
	v_mfma_f32_16x16x32_bf16 v[70:73], v[202:205], v[86:89], v[70:73]
	ds_read_b64_tr_b16 v[202:203], v242 offset:40960
	ds_read_b64_tr_b16 v[204:205], v242 offset:45056
	v_exp_f32_e32 v127, v127
	s_waitcnt lgkmcnt(10)
; __device__ __forceinline__ void partialSM(f32x16& p0, f32x16& p1, float mC) {
;   (void)mC; (void)p1;
;   for (int r = 0; r < 16; ++r) p0[r] = __builtin_amdgcn_exp2f(p0[r]);
; }
; __device__ __forceinline__ void finishSM(f32x16& p0, f32x16& p1, float& l_reg, bf16x8& pa0, bf16x8& pa1, bf16x8& pa2, bf16x8& pa3) {
;   for (int r = 0; r < 16; ++r) p1[r] = __builtin_amdgcn_exp2f(p1[r]);
;   float ps = 0; for (int r = 0; r < 16; ++r) ps += p0[r]; for (int r = 0; r < 16; ++r) ps += p1[r];
;   { auto rr = __builtin_amdgcn_permlane32_swap(__float_as_uint(ps), __float_as_uint(ps), false, false);
;     ps = __uint_as_float(rr[0]) + __uint_as_float(rr[1]); }
;   l_reg += ps;
;     ...
;   PK4(p0, 0, pa0); PK4(p0, 8, pa1); PK4(p1, 0, pa2); PK4(p1, 8, pa3);
;     ...
; }
; __device__ __forceinline__ void qkt(f32x16& p0, f32x16& p1, const bf16* Ks, const bf16x8* qr, int r32, int hi, const f32x16& negm) {
; #pragma unroll
;   for (int d0 = 0; d0 < 8; ++d0) { int cb = (d0 * 16 + hi * 8) * 2;
;     bf16x8 b0 = *reinterpret_cast<const bf16x8*>((const char*)Ks + KSWZ(r32, cb));
;     bf16x8 b1 = *reinterpret_cast<const bf16x8*>((const char*)Ks + KSWZ(32 + r32, cb));
;     if (d0 == 0) { p0 = __builtin_amdgcn_mfma_f32_32x32x16_bf16(b0, qr[0], negm, 0, 0, 0); p1 = __builtin_amdgcn_mfma_f32_32x32x16_bf16(b1, qr[0], negm, 0, 0, 0); }
;     else { p0 = __builtin_amdgcn_mfma_f32_32x32x16_bf16(b0, qr[d0], p0, 0, 0, 0); p1 = __builtin_amdgcn_mfma_f32_32x32x16_bf16(b1, qr[d0], p1, 0, 0, 0); } }
; }
; __device__ __forceinline__ int v_st(int k, int c) { const int kk = (k & ~0xC) | ((k & 4) << 1) | ((k & 8) >> 1); return ((kk >> 3) * 4 + (c >> 5)) * 512 + ((kk & 7) * 32 + (c & 31)) * 2; }
; __device__ __forceinline__ int v_rd_base(int lane) { return ((lane & 3) << 3) | (((lane >> 2) & 3) << 6) | (((lane >> 4) & 1) << 5) | (((lane >> 5) & 1) << 8); }
; template <int OFF> __device__ __forceinline__ s16x4 tr_read(int vb) {
;   s16x4 r; asm volatile("ds_read_b64_tr_b16 %0, %1 offset:%2" : "=&v"(r) : "v"(vb), "i"(OFF) : "memory"); return r;
; }
; template <int D0> __device__ __forceinline__ void pv_one(f32x16& od, int vb, bf16x8 pa0, bf16x8 pa1, bf16x8 pa2, bf16x8 pa3) {
;   const s16x4 l0 = tr_read<v_rd_off(D0, 0, 0)>(vb), h0 = tr_read<v_rd_off(D0, 0, 1)>(vb), l1 = tr_read<v_rd_off(D0, 1, 0)>(vb), h1 = tr_read<v_rd_off(D0, 1, 1)>(vb);
	v_mfma_f32_16x16x32_bf16 v[74:77], v[206:209], v[82:85], v[74:77]
	v_exp_f32_e32 v128, v128
	v_mfma_f32_16x16x32_bf16 v[78:81], v[206:209], v[86:89], v[78:81]
	ds_read_b64_tr_b16 v[206:207], v243 offset:40960
	ds_read_b64_tr_b16 v[208:209], v243 offset:45056
	v_exp_f32_e32 v129, v129
	s_waitcnt lgkmcnt(10)
	v_mfma_f32_16x16x32_bf16 v[18:21], v[210:213], v[98:101], v[18:21]
	v_exp_f32_e32 v130, v130
	v_mfma_f32_16x16x32_bf16 v[22:25], v[210:213], v[102:105], v[22:25]
	ds_read_b64_tr_b16 v[210:211], v244 offset:40960
	ds_read_b64_tr_b16 v[212:213], v244 offset:45056
	v_exp_f32_e32 v131, v131
	s_waitcnt lgkmcnt(10)
	v_mfma_f32_16x16x32_bf16 v[26:29], v[214:217], v[98:101], v[26:29]
	v_exp_f32_e32 v132, v132
	v_mfma_f32_16x16x32_bf16 v[30:33], v[214:217], v[102:105], v[30:33]
	ds_read_b64_tr_b16 v[214:215], v245 offset:40960
	ds_read_b64_tr_b16 v[216:217], v245 offset:45056
	v_exp_f32_e32 v133, v133
	s_waitcnt lgkmcnt(10)
	v_mfma_f32_16x16x32_bf16 v[34:37], v[218:221], v[98:101], v[34:37]
	v_exp_f32_e32 v134, v134
	v_mfma_f32_16x16x32_bf16 v[38:41], v[218:221], v[102:105], v[38:41]
	v_exp_f32_e32 v135, v135
	s_waitcnt lgkmcnt(8)
	v_mfma_f32_16x16x32_bf16 v[42:45], v[222:225], v[98:101], v[42:45]
	v_exp_f32_e32 v136, v136
	v_mfma_f32_16x16x32_bf16 v[46:49], v[222:225], v[102:105], v[46:49]
	v_exp_f32_e32 v137, v137
	s_waitcnt lgkmcnt(6)
	v_mfma_f32_16x16x32_bf16 v[50:53], v[202:205], v[98:101], v[50:53]
	v_exp_f32_e32 v138, v138
	v_mfma_f32_16x16x32_bf16 v[54:57], v[202:205], v[102:105], v[54:57]
	v_exp_f32_e32 v139, v139
	s_waitcnt lgkmcnt(4)
	v_mfma_f32_16x16x32_bf16 v[58:61], v[206:209], v[98:101], v[58:61]
	v_exp_f32_e32 v140, v140
	v_mfma_f32_16x16x32_bf16 v[62:65], v[206:209], v[102:105], v[62:65]
	v_exp_f32_e32 v141, v141
	s_waitcnt lgkmcnt(2)
	v_mfma_f32_16x16x32_bf16 v[66:69], v[210:213], v[98:101], v[66:69]
	v_exp_f32_e32 v142, v142
	v_mfma_f32_16x16x32_bf16 v[70:73], v[210:213], v[102:105], v[70:73]
	v_exp_f32_e32 v143, v143
	s_waitcnt lgkmcnt(0)
	v_mfma_f32_16x16x32_bf16 v[74:77], v[214:217], v[98:101], v[74:77]
	v_exp_f32_e32 v144, v144
	v_mfma_f32_16x16x32_bf16 v[78:81], v[214:217], v[102:105], v[78:81]
	v_exp_f32_e32 v145, v145
	s_waitcnt vmcnt(0)
	v_add_f32_e32 v250, v114, v250
	v_add_f32_e32 v250, v115, v250
	v_add_f32_e32 v250, v116, v250
	v_add_f32_e32 v250, v117, v250
	v_add_f32_e32 v250, v122, v250
	v_add_f32_e32 v250, v123, v250
	v_add_f32_e32 v250, v124, v250
	v_add_f32_e32 v250, v125, v250
	v_cvt_pk_bf16_f32 v114, v114, v115
	v_cvt_pk_bf16_f32 v115, v116, v117
	v_cvt_pk_bf16_f32 v116, v122, v123
	v_cvt_pk_bf16_f32 v117, v124, v125
	v_add_f32_e32 v251, v118, v251
	v_add_f32_e32 v251, v119, v251
	v_add_f32_e32 v251, v120, v251
	v_add_f32_e32 v251, v121, v251
	v_add_f32_e32 v251, v126, v251
	v_add_f32_e32 v251, v127, v251
	v_add_f32_e32 v251, v128, v251
	v_add_f32_e32 v251, v129, v251
	v_cvt_pk_bf16_f32 v118, v118, v119
	v_cvt_pk_bf16_f32 v119, v120, v121
	v_cvt_pk_bf16_f32 v120, v126, v127
	v_cvt_pk_bf16_f32 v121, v128, v129
	v_add_f32_e32 v250, v130, v250
	v_add_f32_e32 v250, v131, v250
	v_add_f32_e32 v250, v132, v250
	v_add_f32_e32 v250, v133, v250
	v_add_f32_e32 v250, v138, v250
	v_add_f32_e32 v250, v139, v250
	v_add_f32_e32 v250, v140, v250
	v_add_f32_e32 v250, v141, v250
	v_cvt_pk_bf16_f32 v130, v130, v131
	v_cvt_pk_bf16_f32 v131, v132, v133
	v_cvt_pk_bf16_f32 v132, v138, v139
	v_cvt_pk_bf16_f32 v133, v140, v141
	v_add_f32_e32 v251, v134, v251
	v_add_f32_e32 v251, v135, v251
	v_add_f32_e32 v251, v136, v251
	v_add_f32_e32 v251, v137, v251
	v_add_f32_e32 v251, v142, v251
	v_add_f32_e32 v251, v143, v251
	v_add_f32_e32 v251, v144, v251
	v_add_f32_e32 v251, v145, v251
	v_cvt_pk_bf16_f32 v134, v134, v135
	v_cvt_pk_bf16_f32 v135, v136, v137
	v_cvt_pk_bf16_f32 v136, v142, v143
	v_cvt_pk_bf16_f32 v137, v144, v145
	ds_read_b64_tr_b16 v[202:203], v238 offset:49152
	ds_read_b64_tr_b16 v[204:205], v238 offset:53248
	ds_read_b64_tr_b16 v[206:207], v239 offset:49152
	ds_read_b64_tr_b16 v[208:209], v239 offset:53248
	ds_read_b64_tr_b16 v[210:211], v240 offset:49152
	ds_read_b64_tr_b16 v[212:213], v240 offset:53248
	ds_read_b64_tr_b16 v[214:215], v241 offset:49152
	ds_read_b64_tr_b16 v[216:217], v241 offset:53248
	ds_read_b64_tr_b16 v[218:219], v242 offset:49152
	ds_read_b64_tr_b16 v[220:221], v242 offset:53248
	ds_read_b64_tr_b16 v[222:223], v243 offset:49152
	ds_read_b64_tr_b16 v[224:225], v243 offset:53248
	s_waitcnt lgkmcnt(10)
	v_mfma_f32_16x16x32_bf16 v[18:21], v[202:205], v[114:117], v[18:21]
	v_mfma_f32_16x16x32_bf16 v[22:25], v[202:205], v[118:121], v[22:25]
	ds_read_b64_tr_b16 v[202:203], v244 offset:49152
	ds_read_b64_tr_b16 v[204:205], v244 offset:53248
	s_waitcnt lgkmcnt(10)
	v_mfma_f32_16x16x32_bf16 v[26:29], v[206:209], v[114:117], v[26:29]
	v_mfma_f32_16x16x32_bf16 v[30:33], v[206:209], v[118:121], v[30:33]
	ds_read_b64_tr_b16 v[206:207], v245 offset:49152
	ds_read_b64_tr_b16 v[208:209], v245 offset:53248
	s_waitcnt lgkmcnt(10)
	v_mfma_f32_16x16x32_bf16 v[34:37], v[210:213], v[114:117], v[34:37]
	v_mfma_f32_16x16x32_bf16 v[38:41], v[210:213], v[118:121], v[38:41]
	ds_read_b64_tr_b16 v[210:211], v238 offset:57344
	ds_read_b64_tr_b16 v[212:213], v238 offset:61440
	s_waitcnt lgkmcnt(10)
	v_mfma_f32_16x16x32_bf16 v[42:45], v[214:217], v[114:117], v[42:45]
	v_mfma_f32_16x16x32_bf16 v[46:49], v[214:217], v[118:121], v[46:49]
	ds_read_b64_tr_b16 v[214:215], v239 offset:57344
	ds_read_b64_tr_b16 v[216:217], v239 offset:61440
	s_waitcnt lgkmcnt(10)
	v_mfma_f32_16x16x32_bf16 v[50:53], v[218:221], v[114:117], v[50:53]
	v_mfma_f32_16x16x32_bf16 v[54:57], v[218:221], v[118:121], v[54:57]
	ds_read_b64_tr_b16 v[218:219], v240 offset:57344
	ds_read_b64_tr_b16 v[220:221], v240 offset:61440
	s_waitcnt lgkmcnt(10)
; __device__ __forceinline__ int crow(int r, int hi) { return (r & 3) + 8 * (r >> 2) + 4 * hi; }
; template <typename TQ> ...
;     ...
;   if (hi == 0) li_l[r32] = l_reg; asm volatile("s_waitcnt lgkmcnt(0)" ::: "memory");
;   float rli[16];
; #pragma unroll
;   for (int r = 0; r < 16; ++r) rli[r] = __builtin_amdgcn_rcpf(li_l[crow(r, hi)]);
;   int le = (int)(threadIdx.x & 63u); asm volatile("" : "+v"(le));
;   const int r32e = le & 31, hie = le >> 5;
;   bf16* Ow = Ob + (long)(wid * QBLK) * LDO;
; #pragma unroll
;   for (int r = 0; r < 16; ++r) { int orow = crow(r, hie);
;     for (int d0 = 0; d0 < 4; ++d0) Ow[(long)orow * LDO + d0 * 32 + r32e] = __float2bfloat16(o[d0][r] * rli[r]); }
	v_mfma_f32_16x16x32_bf16 v[58:61], v[222:225], v[114:117], v[58:61]
	v_mfma_f32_16x16x32_bf16 v[62:65], v[222:225], v[118:121], v[62:65]
	ds_read_b64_tr_b16 v[222:223], v241 offset:57344
	ds_read_b64_tr_b16 v[224:225], v241 offset:61440
	s_waitcnt lgkmcnt(10)
	v_mfma_f32_16x16x32_bf16 v[66:69], v[202:205], v[114:117], v[66:69]
	v_mfma_f32_16x16x32_bf16 v[70:73], v[202:205], v[118:121], v[70:73]
	ds_read_b64_tr_b16 v[202:203], v242 offset:57344
	ds_read_b64_tr_b16 v[204:205], v242 offset:61440
	s_waitcnt lgkmcnt(10)
	v_mfma_f32_16x16x32_bf16 v[74:77], v[206:209], v[114:117], v[74:77]
	v_mfma_f32_16x16x32_bf16 v[78:81], v[206:209], v[118:121], v[78:81]
	ds_read_b64_tr_b16 v[206:207], v243 offset:57344
	ds_read_b64_tr_b16 v[208:209], v243 offset:61440
	s_waitcnt lgkmcnt(10)
	v_mfma_f32_16x16x32_bf16 v[18:21], v[210:213], v[130:133], v[18:21]
	v_mfma_f32_16x16x32_bf16 v[22:25], v[210:213], v[134:137], v[22:25]
	ds_read_b64_tr_b16 v[210:211], v244 offset:57344
	ds_read_b64_tr_b16 v[212:213], v244 offset:61440
	s_waitcnt lgkmcnt(10)
	v_mfma_f32_16x16x32_bf16 v[26:29], v[214:217], v[130:133], v[26:29]
	v_mfma_f32_16x16x32_bf16 v[30:33], v[214:217], v[134:137], v[30:33]
	ds_read_b64_tr_b16 v[214:215], v245 offset:57344
	ds_read_b64_tr_b16 v[216:217], v245 offset:61440
	s_waitcnt lgkmcnt(10)
	v_mfma_f32_16x16x32_bf16 v[34:37], v[218:221], v[130:133], v[34:37]
	v_mfma_f32_16x16x32_bf16 v[38:41], v[218:221], v[134:137], v[38:41]
	s_waitcnt lgkmcnt(8)
	v_mfma_f32_16x16x32_bf16 v[42:45], v[222:225], v[130:133], v[42:45]
	v_mfma_f32_16x16x32_bf16 v[46:49], v[222:225], v[134:137], v[46:49]
	s_waitcnt lgkmcnt(6)
	v_mfma_f32_16x16x32_bf16 v[50:53], v[202:205], v[130:133], v[50:53]
	v_mfma_f32_16x16x32_bf16 v[54:57], v[202:205], v[134:137], v[54:57]
	s_waitcnt lgkmcnt(4)
	v_mfma_f32_16x16x32_bf16 v[58:61], v[206:209], v[130:133], v[58:61]
	v_mfma_f32_16x16x32_bf16 v[62:65], v[206:209], v[134:137], v[62:65]
	s_waitcnt lgkmcnt(2)
	v_mfma_f32_16x16x32_bf16 v[66:69], v[210:213], v[130:133], v[66:69]
	v_mfma_f32_16x16x32_bf16 v[70:73], v[210:213], v[134:137], v[70:73]
	s_waitcnt lgkmcnt(0)
	v_mfma_f32_16x16x32_bf16 v[74:77], v[214:217], v[130:133], v[74:77]
	v_mfma_f32_16x16x32_bf16 v[78:81], v[214:217], v[134:137], v[78:81]
	s_setprio 0
	ds_swizzle_b32 v6, v250 offset:swizzle(SWAP,16)
	s_waitcnt lgkmcnt(0)
	v_add_f32_e32 v250, v250, v6
	v_mov_b32_e32 v6, v250
	s_nop 1
	v_permlane32_swap_b32_e32 v250, v6
	v_add_f32_e32 v250, v250, v6
	v_rcp_f32_e32 v250, v250
	ds_swizzle_b32 v6, v251 offset:swizzle(SWAP,16)
	s_waitcnt lgkmcnt(0)
	v_add_f32_e32 v251, v251, v6
	v_mov_b32_e32 v6, v251
	s_nop 1
	v_permlane32_swap_b32_e32 v251, v6
	v_add_f32_e32 v251, v251, v6
	v_rcp_f32_e32 v251, v251
	s_add_u32 s12, s71, s48
	s_addc_u32 s13, s72, s49
	v_add_u32_e32 v201, s52, v16
	v_lshlrev_b32_e32 v201, 11, v201
	v_lshl_or_b32 v7, v17, 3, v201
	v_add_u32_e32 v200, 0x8000, v7
	v_mul_f32_e32 v18, v18, v250
	v_mul_f32_e32 v19, v19, v250
	v_mul_f32_e32 v20, v20, v250
	v_mul_f32_e32 v21, v21, v250
	v_cvt_pk_bf16_f32 v18, v18, v19
	v_cvt_pk_bf16_f32 v19, v20, v21
	global_store_dwordx2 v7, v[18:19], s[12:13] offset:0
	v_mul_f32_e32 v22, v22, v251
	v_mul_f32_e32 v23, v23, v251
	v_mul_f32_e32 v24, v24, v251
	v_mul_f32_e32 v25, v25, v251
	v_cvt_pk_bf16_f32 v22, v22, v23
	v_cvt_pk_bf16_f32 v23, v24, v25
	global_store_dwordx2 v200, v[22:23], s[12:13] offset:0
	v_mul_f32_e32 v26, v26, v250
	v_mul_f32_e32 v27, v27, v250
	v_mul_f32_e32 v28, v28, v250
	v_mul_f32_e32 v29, v29, v250
	v_cvt_pk_bf16_f32 v26, v26, v27
	v_cvt_pk_bf16_f32 v27, v28, v29
	global_store_dwordx2 v7, v[26:27], s[12:13] offset:32
	v_mul_f32_e32 v30, v30, v251
	v_mul_f32_e32 v31, v31, v251
	v_mul_f32_e32 v32, v32, v251
	v_mul_f32_e32 v33, v33, v251
	v_cvt_pk_bf16_f32 v30, v30, v31
	v_cvt_pk_bf16_f32 v31, v32, v33
	global_store_dwordx2 v200, v[30:31], s[12:13] offset:32
	v_mul_f32_e32 v34, v34, v250
	v_mul_f32_e32 v35, v35, v250
	v_mul_f32_e32 v36, v36, v250
	v_mul_f32_e32 v37, v37, v250
	v_cvt_pk_bf16_f32 v34, v34, v35
	v_cvt_pk_bf16_f32 v35, v36, v37
	global_store_dwordx2 v7, v[34:35], s[12:13] offset:64
	v_mul_f32_e32 v38, v38, v251
	v_mul_f32_e32 v39, v39, v251
	v_mul_f32_e32 v40, v40, v251
	v_mul_f32_e32 v41, v41, v251
	v_cvt_pk_bf16_f32 v38, v38, v39
	v_cvt_pk_bf16_f32 v39, v40, v41
	global_store_dwordx2 v200, v[38:39], s[12:13] offset:64
	v_mul_f32_e32 v42, v42, v250
	v_mul_f32_e32 v43, v43, v250
	v_mul_f32_e32 v44, v44, v250
	v_mul_f32_e32 v45, v45, v250
	v_cvt_pk_bf16_f32 v42, v42, v43
	v_cvt_pk_bf16_f32 v43, v44, v45
	global_store_dwordx2 v7, v[42:43], s[12:13] offset:96
	v_mul_f32_e32 v46, v46, v251
	v_mul_f32_e32 v47, v47, v251
	v_mul_f32_e32 v48, v48, v251
	v_mul_f32_e32 v49, v49, v251
	v_cvt_pk_bf16_f32 v46, v46, v47
	v_cvt_pk_bf16_f32 v47, v48, v49
	global_store_dwordx2 v200, v[46:47], s[12:13] offset:96
	v_mul_f32_e32 v50, v50, v250
	v_mul_f32_e32 v51, v51, v250
	v_mul_f32_e32 v52, v52, v250
	v_mul_f32_e32 v53, v53, v250
	v_cvt_pk_bf16_f32 v50, v50, v51
	v_cvt_pk_bf16_f32 v51, v52, v53
	global_store_dwordx2 v7, v[50:51], s[12:13] offset:128
	v_mul_f32_e32 v54, v54, v251
	v_mul_f32_e32 v55, v55, v251
	v_mul_f32_e32 v56, v56, v251
	v_mul_f32_e32 v57, v57, v251
	v_cvt_pk_bf16_f32 v54, v54, v55
	v_cvt_pk_bf16_f32 v55, v56, v57
	global_store_dwordx2 v200, v[54:55], s[12:13] offset:128
	v_mul_f32_e32 v58, v58, v250
	v_mul_f32_e32 v59, v59, v250
	v_mul_f32_e32 v60, v60, v250
	v_mul_f32_e32 v61, v61, v250
	v_cvt_pk_bf16_f32 v58, v58, v59
	v_cvt_pk_bf16_f32 v59, v60, v61
	global_store_dwordx2 v7, v[58:59], s[12:13] offset:160
	v_mul_f32_e32 v62, v62, v251
	v_mul_f32_e32 v63, v63, v251
	v_mul_f32_e32 v64, v64, v251
	v_mul_f32_e32 v65, v65, v251
	v_cvt_pk_bf16_f32 v62, v62, v63
	v_cvt_pk_bf16_f32 v63, v64, v65
	global_store_dwordx2 v200, v[62:63], s[12:13] offset:160
	v_mul_f32_e32 v66, v66, v250
	v_mul_f32_e32 v67, v67, v250
	v_mul_f32_e32 v68, v68, v250
	v_mul_f32_e32 v69, v69, v250
	v_cvt_pk_bf16_f32 v66, v66, v67
	v_cvt_pk_bf16_f32 v67, v68, v69
	global_store_dwordx2 v7, v[66:67], s[12:13] offset:192
	v_mul_f32_e32 v70, v70, v251
	v_mul_f32_e32 v71, v71, v251
	v_mul_f32_e32 v72, v72, v251
	v_mul_f32_e32 v73, v73, v251
	v_cvt_pk_bf16_f32 v70, v70, v71
	v_cvt_pk_bf16_f32 v71, v72, v73
	global_store_dwordx2 v200, v[70:71], s[12:13] offset:192
	v_mul_f32_e32 v74, v74, v250
	v_mul_f32_e32 v75, v75, v250
	v_mul_f32_e32 v76, v76, v250
	v_mul_f32_e32 v77, v77, v250
	v_cvt_pk_bf16_f32 v74, v74, v75
	v_cvt_pk_bf16_f32 v75, v76, v77
	global_store_dwordx2 v7, v[74:75], s[12:13] offset:224
	v_mul_f32_e32 v78, v78, v251
	v_mul_f32_e32 v79, v79, v251
	v_mul_f32_e32 v80, v80, v251
	v_mul_f32_e32 v81, v81, v251
	v_cvt_pk_bf16_f32 v78, v78, v79
	v_cvt_pk_bf16_f32 v79, v80, v81
	global_store_dwordx2 v200, v[78:79], s[12:13] offset:224
	s_add_i32 s74, s74, 1
	s_add_i32 s94, s94, 1
	s_cmp_eq_u32 s74, s66
	s_cselect_b64 s[0:1], -1, 0
	s_barrier
	s_branch .LBB0_818
	s_branch .Lattn_done

; #define SEAM(k) do { if (IN(k) && IN((k) + 1)) xcd_barrier(bar); } while (0)
; __global__ void __launch_bounds__(NTHR, 2) fwd_megakernel(KArgs a) {
;     ...
;         for (int i = 0; i < upb; ++i) {
;             const int unit = vcu * upb + i; if (unit >= 512) break;
;             const int grp = unit >> 7, rem = unit & 127, gq = rem >> 5, qb = rem & 31, b = grp >> 1, kvh = grp & 1, h = kvh * 4 + gq;
;             const size_t qoff = ((size_t)(b * SEQ + qb * 256)) * DM + h * 128, koff = (size_t)b * SKV * 256 + kvh * 128;
;             att::attn_dense_body<att::bf16>(Q + qoff, Kb + koff, Vb + koff, O + qoff, SKV, (char*)lds_raw, mC, a.g_q, (const float*)(ws + WS_ROPE), (const float*)(ws + WS_ROPE) + 4096, qb * 256);
;             __syncthreads();
;         }
;     } SEAM(9);
.Lattn_done:
.LBB0_824:
	v_readlane_b32 s92, v254, 7
	v_readlane_b32 s93, v254, 8
	v_readlane_b32 s94, v254, 9
	v_readlane_b32 s95, v254, 10
